# provably redundant s_waitcnt lgkmcnt(0) right after the phase barriers removed (56 sites; the same wait precedes the barrier)
# baseline (speedup 1.0000x reference)
.LBB0_398:
	s_add_u32 s48, s10, 0xfffc0080
	s_addc_u32 s49, s11, -1
	s_add_i32 s83, 0, 0x10000
	s_cmp_eq_u32 s67, 12
	s_cselect_b32 s61, s9, s49
	s_cselect_b32 s60, s55, s48
	v_add_u32_e32 v128, s83, v173
	s_cselect_b32 s49, s53, s66
	s_cselect_b32 s48, s64, s65
	s_add_i32 s85, 0, 0x14000
	ds_read_b128 v[168:171], v128
	ds_read_b128 v[176:179], v128 offset:1024
	ds_read_b128 v[180:183], v128 offset:2048
	ds_read_b128 v[184:187], v128 offset:3072
	v_add_u32_e32 v128, s85, v173
	ds_read_b128 v[188:191], v128
	ds_read_b128 v[192:195], v128 offset:1024
	ds_read_b128 v[196:199], v128 offset:2048
	ds_read_b128 v[202:205], v128 offset:3072
	s_add_i32 m0, s63, 0xc000
	ds_read_b128 v[206:209], v200
	ds_read_b128 v[210:213], v200 offset:1024
	ds_read_b128 v[218:221], v200 offset:2048
	ds_read_b128 v[222:225], v200 offset:3072
	ds_read_b128 v[226:229], v200 offset:4096
	ds_read_b128 v[234:237], v200 offset:5120
	ds_read_b128 v[238:241], v200 offset:6144
	ds_read_b128 v[242:245], v200 offset:7168
	global_load_lds_dwordx4 v148, s[10:11]
	s_add_i32 m0, s63, 0xe000
	s_nop 0
	global_load_lds_dwordx4 v150, s[10:11]
	s_waitcnt vmcnt(8)
	s_waitcnt lgkmcnt(0)
	s_barrier
	v_mfma_f32_16x16x32_bf16 v[124:127], v[168:171], v[206:209], v[124:127]
	v_mfma_f32_16x16x32_bf16 v[120:123], v[180:183], v[206:209], v[120:123]
	v_mfma_f32_16x16x32_bf16 v[108:111], v[168:171], v[218:221], v[108:111]
	v_mfma_f32_16x16x32_bf16 v[104:107], v[180:183], v[218:221], v[104:107]
	v_mfma_f32_16x16x32_bf16 v[92:95], v[168:171], v[226:229], v[92:95]
	v_mfma_f32_16x16x32_bf16 v[88:91], v[180:183], v[226:229], v[88:91]
	v_mfma_f32_16x16x32_bf16 v[76:79], v[168:171], v[238:241], v[76:79]
	v_mfma_f32_16x16x32_bf16 v[72:75], v[180:183], v[238:241], v[72:75]
	v_mfma_f32_16x16x32_bf16 v[124:127], v[176:179], v[210:213], v[124:127]
	v_mfma_f32_16x16x32_bf16 v[120:123], v[184:187], v[210:213], v[120:123]
	v_mfma_f32_16x16x32_bf16 v[108:111], v[176:179], v[222:225], v[108:111]
	v_mfma_f32_16x16x32_bf16 v[104:107], v[184:187], v[222:225], v[104:107]
	v_mfma_f32_16x16x32_bf16 v[92:95], v[176:179], v[234:237], v[92:95]
	v_mfma_f32_16x16x32_bf16 v[88:91], v[184:187], v[234:237], v[88:91]
	v_mfma_f32_16x16x32_bf16 v[76:79], v[176:179], v[242:245], v[76:79]
	v_mfma_f32_16x16x32_bf16 v[72:75], v[184:187], v[242:245], v[72:75]
	v_mfma_f32_16x16x32_bf16 v[116:119], v[188:191], v[206:209], v[116:119]
	v_mfma_f32_16x16x32_bf16 v[112:115], v[196:199], v[206:209], v[112:115]
	v_mfma_f32_16x16x32_bf16 v[100:103], v[188:191], v[218:221], v[100:103]
	v_mfma_f32_16x16x32_bf16 v[96:99], v[196:199], v[218:221], v[96:99]
	v_mfma_f32_16x16x32_bf16 v[84:87], v[188:191], v[226:229], v[84:87]
	v_mfma_f32_16x16x32_bf16 v[80:83], v[196:199], v[226:229], v[80:83]
	v_mfma_f32_16x16x32_bf16 v[68:71], v[188:191], v[238:241], v[68:71]
	v_mfma_f32_16x16x32_bf16 v[64:67], v[196:199], v[238:241], v[64:67]
	v_mfma_f32_16x16x32_bf16 v[116:119], v[192:195], v[210:213], v[116:119]
	v_mfma_f32_16x16x32_bf16 v[112:115], v[202:205], v[210:213], v[112:115]
	v_mfma_f32_16x16x32_bf16 v[100:103], v[192:195], v[222:225], v[100:103]
	v_mfma_f32_16x16x32_bf16 v[96:99], v[202:205], v[222:225], v[96:99]
	v_mfma_f32_16x16x32_bf16 v[84:87], v[192:195], v[234:237], v[84:87]
	v_mfma_f32_16x16x32_bf16 v[80:83], v[202:205], v[234:237], v[80:83]
	v_mfma_f32_16x16x32_bf16 v[68:71], v[192:195], v[242:245], v[68:71]
	v_mfma_f32_16x16x32_bf16 v[64:67], v[202:205], v[242:245], v[64:67]
	s_barrier
	s_add_i32 s83, s83, s74
	s_mov_b64 s[98:99], s[48:49]
	s_mov_b32 m0, s83
	ds_read_b128 v[206:209], v200 offset:16384
	ds_read_b128 v[210:213], v200 offset:17408
	ds_read_b128 v[218:221], v200 offset:18432
	ds_read_b128 v[222:225], v200 offset:19456
	ds_read_b128 v[226:229], v200 offset:20480
	ds_read_b128 v[234:237], v200 offset:21504
	ds_read_b128 v[238:241], v200 offset:22528
	ds_read_b128 v[242:245], v200 offset:23552
	global_load_lds_dwordx4 v136, s[48:49]
	s_add_i32 m0, s83, 0x2000
	s_add_u32 s86, s48, 0x40000
	s_addc_u32 s87, s49, 0
	s_add_i32 s83, s85, s74
	global_load_lds_dwordx4 v140, s[48:49]
	s_mov_b32 m0, s83
	s_mov_b64 s[100:101], s[60:61]
	global_load_lds_dwordx4 v136, s[86:87]
	s_add_i32 m0, s83, 0x2000
	s_nop 0
	global_load_lds_dwordx4 v140, s[86:87]
	s_mov_b32 m0, s63
	s_nop 0
	global_load_lds_dwordx4 v134, s[60:61]
	s_mov_b32 m0, s75
	s_nop 0
	global_load_lds_dwordx4 v138, s[60:61]
	s_waitcnt vmcnt(8)
	s_waitcnt lgkmcnt(0)
	s_barrier
	v_mfma_f32_16x16x32_bf16 v[60:63], v[168:171], v[206:209], v[60:63]
	v_mfma_f32_16x16x32_bf16 v[56:59], v[180:183], v[206:209], v[56:59]
	v_mfma_f32_16x16x32_bf16 v[44:47], v[168:171], v[218:221], v[44:47]
	v_mfma_f32_16x16x32_bf16 v[40:43], v[180:183], v[218:221], v[40:43]
	v_mfma_f32_16x16x32_bf16 v[28:31], v[168:171], v[226:229], v[28:31]
	v_mfma_f32_16x16x32_bf16 v[24:27], v[180:183], v[226:229], v[24:27]
	v_mfma_f32_16x16x32_bf16 v[12:15], v[168:171], v[238:241], v[12:15]
	v_mfma_f32_16x16x32_bf16 v[8:11], v[180:183], v[238:241], v[8:11]
	v_mfma_f32_16x16x32_bf16 v[60:63], v[176:179], v[210:213], v[60:63]
	v_mfma_f32_16x16x32_bf16 v[56:59], v[184:187], v[210:213], v[56:59]
	v_mfma_f32_16x16x32_bf16 v[44:47], v[176:179], v[222:225], v[44:47]
	v_mfma_f32_16x16x32_bf16 v[40:43], v[184:187], v[222:225], v[40:43]
	v_mfma_f32_16x16x32_bf16 v[28:31], v[176:179], v[234:237], v[28:31]
	v_mfma_f32_16x16x32_bf16 v[24:27], v[184:187], v[234:237], v[24:27]
	v_mfma_f32_16x16x32_bf16 v[12:15], v[176:179], v[242:245], v[12:15]
	v_mfma_f32_16x16x32_bf16 v[8:11], v[184:187], v[242:245], v[8:11]
	v_mfma_f32_16x16x32_bf16 v[52:55], v[188:191], v[206:209], v[52:55]
	v_mfma_f32_16x16x32_bf16 v[48:51], v[196:199], v[206:209], v[48:51]
	v_mfma_f32_16x16x32_bf16 v[36:39], v[188:191], v[218:221], v[36:39]
	v_mfma_f32_16x16x32_bf16 v[32:35], v[196:199], v[218:221], v[32:35]
	v_mfma_f32_16x16x32_bf16 v[20:23], v[188:191], v[226:229], v[20:23]
	v_mfma_f32_16x16x32_bf16 v[16:19], v[196:199], v[226:229], v[16:19]
	v_mfma_f32_16x16x32_bf16 v[4:7], v[188:191], v[238:241], v[4:7]
	v_mfma_f32_16x16x32_bf16 v[0:3], v[196:199], v[238:241], v[0:3]
	v_mfma_f32_16x16x32_bf16 v[52:55], v[192:195], v[210:213], v[52:55]
	v_mfma_f32_16x16x32_bf16 v[48:51], v[202:205], v[210:213], v[48:51]
	v_mfma_f32_16x16x32_bf16 v[36:39], v[192:195], v[222:225], v[36:39]
	v_mfma_f32_16x16x32_bf16 v[32:35], v[202:205], v[222:225], v[32:35]
	v_mfma_f32_16x16x32_bf16 v[20:23], v[192:195], v[234:237], v[20:23]
	v_mfma_f32_16x16x32_bf16 v[16:19], v[202:205], v[234:237], v[16:19]
	v_mfma_f32_16x16x32_bf16 v[4:7], v[192:195], v[242:245], v[4:7]
	v_mfma_f32_16x16x32_bf16 v[0:3], v[202:205], v[242:245], v[0:3]
	s_barrier
	v_add_u32_e32 v128, s0, v173
	s_add_i32 s83, 0, 0x1c000
	ds_read_b128 v[168:171], v128
	ds_read_b128 v[176:179], v128 offset:1024
	ds_read_b128 v[180:183], v128 offset:2048
	ds_read_b128 v[184:187], v128 offset:3072
	v_add_u32_e32 v128, s83, v173
	ds_read_b128 v[188:191], v128
	ds_read_b128 v[192:195], v128 offset:1024
	ds_read_b128 v[196:199], v128 offset:2048
	ds_read_b128 v[202:205], v128 offset:3072
	s_add_u32 s60, s60, 0x40000
	s_addc_u32 s61, s61, 0
	s_mov_b32 m0, s76
	ds_read_b128 v[206:209], v200 offset:32768
	ds_read_b128 v[210:213], v200 offset:33792
	ds_read_b128 v[218:221], v200 offset:34816
	ds_read_b128 v[222:225], v200 offset:35840
	ds_read_b128 v[226:229], v200 offset:36864
	ds_read_b128 v[234:237], v200 offset:37888
	ds_read_b128 v[238:241], v200 offset:38912
	ds_read_b128 v[242:245], v200 offset:39936
	global_load_lds_dwordx4 v134, s[60:61]
	v_lshl_add_u64 v[250:251], s[60:61], 0, v[138:139]
	s_mov_b32 m0, s77
	s_nop 0
	global_load_lds_dwordx4 v[250:251], off
	s_waitcnt vmcnt(8)
	s_waitcnt lgkmcnt(0)
	s_barrier
	v_mfma_f32_16x16x32_bf16 v[124:127], v[168:171], v[206:209], v[124:127]
	v_mfma_f32_16x16x32_bf16 v[120:123], v[180:183], v[206:209], v[120:123]
	v_mfma_f32_16x16x32_bf16 v[108:111], v[168:171], v[218:221], v[108:111]
	v_mfma_f32_16x16x32_bf16 v[104:107], v[180:183], v[218:221], v[104:107]
	v_mfma_f32_16x16x32_bf16 v[92:95], v[168:171], v[226:229], v[92:95]
	v_mfma_f32_16x16x32_bf16 v[88:91], v[180:183], v[226:229], v[88:91]
	v_mfma_f32_16x16x32_bf16 v[76:79], v[168:171], v[238:241], v[76:79]
	v_mfma_f32_16x16x32_bf16 v[72:75], v[180:183], v[238:241], v[72:75]
	v_mfma_f32_16x16x32_bf16 v[124:127], v[176:179], v[210:213], v[124:127]
	v_mfma_f32_16x16x32_bf16 v[120:123], v[184:187], v[210:213], v[120:123]
	v_mfma_f32_16x16x32_bf16 v[108:111], v[176:179], v[222:225], v[108:111]
	v_mfma_f32_16x16x32_bf16 v[104:107], v[184:187], v[222:225], v[104:107]
	v_mfma_f32_16x16x32_bf16 v[92:95], v[176:179], v[234:237], v[92:95]
	v_mfma_f32_16x16x32_bf16 v[88:91], v[184:187], v[234:237], v[88:91]
	v_mfma_f32_16x16x32_bf16 v[76:79], v[176:179], v[242:245], v[76:79]
	v_mfma_f32_16x16x32_bf16 v[72:75], v[184:187], v[242:245], v[72:75]
	v_mfma_f32_16x16x32_bf16 v[116:119], v[188:191], v[206:209], v[116:119]
	v_mfma_f32_16x16x32_bf16 v[112:115], v[196:199], v[206:209], v[112:115]
	v_mfma_f32_16x16x32_bf16 v[100:103], v[188:191], v[218:221], v[100:103]
	v_mfma_f32_16x16x32_bf16 v[96:99], v[196:199], v[218:221], v[96:99]
	v_mfma_f32_16x16x32_bf16 v[84:87], v[188:191], v[226:229], v[84:87]
	v_mfma_f32_16x16x32_bf16 v[80:83], v[196:199], v[226:229], v[80:83]
	v_mfma_f32_16x16x32_bf16 v[68:71], v[188:191], v[238:241], v[68:71]
	v_mfma_f32_16x16x32_bf16 v[64:67], v[196:199], v[238:241], v[64:67]
	v_mfma_f32_16x16x32_bf16 v[116:119], v[192:195], v[210:213], v[116:119]
	v_mfma_f32_16x16x32_bf16 v[112:115], v[202:205], v[210:213], v[112:115]
	v_mfma_f32_16x16x32_bf16 v[100:103], v[192:195], v[222:225], v[100:103]
	v_mfma_f32_16x16x32_bf16 v[96:99], v[202:205], v[222:225], v[96:99]
	v_mfma_f32_16x16x32_bf16 v[84:87], v[192:195], v[234:237], v[84:87]
	v_mfma_f32_16x16x32_bf16 v[80:83], v[202:205], v[234:237], v[80:83]
	v_mfma_f32_16x16x32_bf16 v[68:71], v[192:195], v[242:245], v[68:71]
	v_mfma_f32_16x16x32_bf16 v[64:67], v[202:205], v[242:245], v[64:67]
	s_barrier
	s_add_i32 s60, s0, s74
	s_add_u32 s98, s98, s12
	s_addc_u32 s99, s99, s13
	s_mov_b32 m0, s60
	ds_read_b128 v[206:209], v200 offset:49152
	ds_read_b128 v[210:213], v200 offset:50176
	ds_read_b128 v[218:221], v200 offset:51200
	ds_read_b128 v[222:225], v200 offset:52224
	ds_read_b128 v[226:229], v200 offset:53248
	ds_read_b128 v[234:237], v200 offset:54272
	ds_read_b128 v[238:241], v200 offset:55296
	ds_read_b128 v[242:245], v200 offset:56320
	global_load_lds_dwordx4 v136, s[98:99]
	s_add_i32 m0, s60, 0x2000
	s_add_u32 s48, s48, 0x40080
	s_addc_u32 s49, s49, 0
	s_add_i32 s60, s83, s74
	global_load_lds_dwordx4 v140, s[98:99]
	s_mov_b32 m0, s60
	s_nop 0
	global_load_lds_dwordx4 v136, s[48:49]
	s_add_i32 m0, s60, 0x2000
	s_nop 0
	global_load_lds_dwordx4 v140, s[48:49]
	s_add_u32 s100, s100, s12
	s_addc_u32 s101, s101, s13
	s_mov_b32 m0, s78
	s_nop 0
	global_load_lds_dwordx4 v134, s[100:101]
	s_mov_b32 m0, s79
	s_nop 0
	global_load_lds_dwordx4 v138, s[100:101]
	s_waitcnt vmcnt(8)
	s_waitcnt lgkmcnt(0)
	s_barrier
	v_mfma_f32_16x16x32_bf16 v[60:63], v[168:171], v[206:209], v[60:63]
	v_mfma_f32_16x16x32_bf16 v[56:59], v[180:183], v[206:209], v[56:59]
	v_mfma_f32_16x16x32_bf16 v[44:47], v[168:171], v[218:221], v[44:47]
	v_mfma_f32_16x16x32_bf16 v[40:43], v[180:183], v[218:221], v[40:43]
	v_mfma_f32_16x16x32_bf16 v[28:31], v[168:171], v[226:229], v[28:31]
	v_mfma_f32_16x16x32_bf16 v[24:27], v[180:183], v[226:229], v[24:27]
	v_mfma_f32_16x16x32_bf16 v[12:15], v[168:171], v[238:241], v[12:15]
	v_mfma_f32_16x16x32_bf16 v[8:11], v[180:183], v[238:241], v[8:11]
	v_mfma_f32_16x16x32_bf16 v[60:63], v[176:179], v[210:213], v[60:63]
	v_mfma_f32_16x16x32_bf16 v[56:59], v[184:187], v[210:213], v[56:59]
	v_mfma_f32_16x16x32_bf16 v[44:47], v[176:179], v[222:225], v[44:47]
	v_mfma_f32_16x16x32_bf16 v[40:43], v[184:187], v[222:225], v[40:43]
	v_mfma_f32_16x16x32_bf16 v[28:31], v[176:179], v[234:237], v[28:31]
	v_mfma_f32_16x16x32_bf16 v[24:27], v[184:187], v[234:237], v[24:27]
	v_mfma_f32_16x16x32_bf16 v[12:15], v[176:179], v[242:245], v[12:15]
	v_mfma_f32_16x16x32_bf16 v[8:11], v[184:187], v[242:245], v[8:11]
	v_mfma_f32_16x16x32_bf16 v[52:55], v[188:191], v[206:209], v[52:55]
	v_mfma_f32_16x16x32_bf16 v[48:51], v[196:199], v[206:209], v[48:51]
	v_mfma_f32_16x16x32_bf16 v[36:39], v[188:191], v[218:221], v[36:39]
	v_mfma_f32_16x16x32_bf16 v[32:35], v[196:199], v[218:221], v[32:35]
	v_mfma_f32_16x16x32_bf16 v[20:23], v[188:191], v[226:229], v[20:23]
	v_mfma_f32_16x16x32_bf16 v[16:19], v[196:199], v[226:229], v[16:19]
	v_mfma_f32_16x16x32_bf16 v[4:7], v[188:191], v[238:241], v[4:7]
	v_mfma_f32_16x16x32_bf16 v[0:3], v[196:199], v[238:241], v[0:3]
	v_mfma_f32_16x16x32_bf16 v[52:55], v[192:195], v[210:213], v[52:55]
	v_mfma_f32_16x16x32_bf16 v[48:51], v[202:205], v[210:213], v[48:51]
	v_mfma_f32_16x16x32_bf16 v[36:39], v[192:195], v[222:225], v[36:39]
	v_mfma_f32_16x16x32_bf16 v[32:35], v[202:205], v[222:225], v[32:35]
	v_mfma_f32_16x16x32_bf16 v[20:23], v[192:195], v[234:237], v[20:23]
	v_mfma_f32_16x16x32_bf16 v[16:19], v[202:205], v[234:237], v[16:19]
	v_mfma_f32_16x16x32_bf16 v[4:7], v[192:195], v[242:245], v[4:7]
	v_mfma_f32_16x16x32_bf16 v[0:3], v[202:205], v[242:245], v[0:3]
	s_barrier
	s_add_i32 s67, s67, 2
	s_add_u32 s10, s10, 0x100
	s_addc_u32 s11, s11, 0
	s_add_u32 s65, s65, 0x100
	s_addc_u32 s66, s66, 0
	s_cmp_gt_u32 s67, 13
	s_cbranch_scc0 .LBB0_398
	s_and_b64 vcc, exec, s[50:51]
	s_cbranch_vccz .LBB0_401
	s_barrier

.LBB0_479:
	s_add_u32 s66, s48, 0xfffe0080
	s_addc_u32 s67, s49, -1
	s_add_i32 s90, 0, 0x10000
	s_cmp_eq_u32 vcc_lo, 4
	s_cselect_b32 s71, s9, s67
	s_cselect_b32 s70, s61, s66
	s_cselect_b32 s67, s59, s83
	s_cselect_b32 s66, s72, s73
	s_add_i32 vcc_hi, 0, 0x14000
	v_add_u32_e32 v140, s90, v225
	v_add_u32_e32 v144, vcc_hi, v225
	ds_read_b128 v[128:131], v140
	ds_read_b128 v[132:135], v140 offset:1024
	ds_read_b128 v[136:139], v140 offset:2048
	ds_read_b128 v[140:143], v140 offset:3072
	ds_read_b128 v[174:177], v144
	ds_read_b128 v[178:181], v144 offset:1024
	ds_read_b128 v[182:185], v144 offset:2048
	ds_read_b128 v[186:189], v144 offset:3072
	s_add_i32 m0, s4, 0xc000
	ds_read_b128 v[190:193], v228
	ds_read_b128 v[194:197], v228 offset:1024
	ds_read_b128 v[198:201], v228 offset:2048
	ds_read_b128 v[202:205], v228 offset:3072
	ds_read_b128 v[206:209], v228 offset:4096
	ds_read_b128 v[210:213], v228 offset:5120
	ds_read_b128 v[234:237], v228 offset:6144
	ds_read_b128 v[238:241], v228 offset:7168
	global_load_lds_dwordx4 v168, s[48:49]
	s_add_i32 m0, s4, 0xe000
	s_nop 0
	global_load_lds_dwordx4 v170, s[48:49]
	s_waitcnt vmcnt(8)
	s_waitcnt lgkmcnt(0)
	s_barrier
	v_mfma_i32_16x16x64_i8 v[124:127], v[128:131], v[190:193], v[124:127]
	v_mfma_i32_16x16x64_i8 v[120:123], v[136:139], v[190:193], v[120:123]
	v_mfma_i32_16x16x64_i8 v[116:119], v[128:131], v[198:201], v[116:119]
	v_mfma_i32_16x16x64_i8 v[112:115], v[136:139], v[198:201], v[112:115]
	v_mfma_i32_16x16x64_i8 v[108:111], v[128:131], v[206:209], v[108:111]
	v_mfma_i32_16x16x64_i8 v[104:107], v[136:139], v[206:209], v[104:107]
	v_mfma_i32_16x16x64_i8 v[100:103], v[128:131], v[234:237], v[100:103]
	v_mfma_i32_16x16x64_i8 v[96:99], v[136:139], v[234:237], v[96:99]
	v_mfma_i32_16x16x64_i8 v[124:127], v[132:135], v[194:197], v[124:127]
	v_mfma_i32_16x16x64_i8 v[120:123], v[140:143], v[194:197], v[120:123]
	v_mfma_i32_16x16x64_i8 v[116:119], v[132:135], v[202:205], v[116:119]
	v_mfma_i32_16x16x64_i8 v[112:115], v[140:143], v[202:205], v[112:115]
	v_mfma_i32_16x16x64_i8 v[108:111], v[132:135], v[210:213], v[108:111]
	v_mfma_i32_16x16x64_i8 v[104:107], v[140:143], v[210:213], v[104:107]
	v_mfma_i32_16x16x64_i8 v[100:103], v[132:135], v[238:241], v[100:103]
	v_mfma_i32_16x16x64_i8 v[96:99], v[140:143], v[238:241], v[96:99]
	v_mfma_i32_16x16x64_i8 v[92:95], v[174:177], v[190:193], v[92:95]
	v_mfma_i32_16x16x64_i8 v[88:91], v[182:185], v[190:193], v[88:91]
	v_mfma_i32_16x16x64_i8 v[84:87], v[174:177], v[198:201], v[84:87]
	v_mfma_i32_16x16x64_i8 v[80:83], v[182:185], v[198:201], v[80:83]
	v_mfma_i32_16x16x64_i8 v[76:79], v[174:177], v[206:209], v[76:79]
	v_mfma_i32_16x16x64_i8 v[72:75], v[182:185], v[206:209], v[72:75]
	v_mfma_i32_16x16x64_i8 v[68:71], v[174:177], v[234:237], v[68:71]
	v_mfma_i32_16x16x64_i8 v[64:67], v[182:185], v[234:237], v[64:67]
	v_mfma_i32_16x16x64_i8 v[92:95], v[178:181], v[194:197], v[92:95]
	v_mfma_i32_16x16x64_i8 v[88:91], v[186:189], v[194:197], v[88:91]
	v_mfma_i32_16x16x64_i8 v[84:87], v[178:181], v[202:205], v[84:87]
	v_mfma_i32_16x16x64_i8 v[80:83], v[186:189], v[202:205], v[80:83]
	v_mfma_i32_16x16x64_i8 v[76:79], v[178:181], v[210:213], v[76:79]
	v_mfma_i32_16x16x64_i8 v[72:75], v[186:189], v[210:213], v[72:75]
	v_mfma_i32_16x16x64_i8 v[68:71], v[178:181], v[238:241], v[68:71]
	v_mfma_i32_16x16x64_i8 v[64:67], v[186:189], v[238:241], v[64:67]
	s_barrier
	s_add_i32 s90, s90, s77
	s_mov_b64 s[98:99], s[66:67]
	s_mov_b32 m0, s90
	ds_read_b128 v[190:193], v228 offset:16384
	ds_read_b128 v[194:197], v228 offset:17408
	ds_read_b128 v[198:201], v228 offset:18432
	ds_read_b128 v[202:205], v228 offset:19456
	ds_read_b128 v[206:209], v228 offset:20480
	ds_read_b128 v[210:213], v228 offset:21504
	ds_read_b128 v[234:237], v228 offset:22528
	ds_read_b128 v[238:241], v228 offset:23552
	global_load_lds_dwordx4 v154, s[66:67]
	s_add_i32 m0, s90, 0x2000
	s_add_u32 s90, s66, 0x20000
	s_addc_u32 s91, s67, 0
	s_add_i32 vcc_hi, vcc_hi, s77
	global_load_lds_dwordx4 v158, s[66:67]
	s_mov_b32 m0, vcc_hi
	s_mov_b64 s[100:101], s[70:71]
	global_load_lds_dwordx4 v154, s[90:91]
	s_add_i32 m0, vcc_hi, 0x2000
	s_nop 0
	global_load_lds_dwordx4 v158, s[90:91]
	s_mov_b32 m0, s4
	s_nop 0
	global_load_lds_dwordx4 v152, s[70:71]
	s_mov_b32 m0, s5
	s_nop 0
	global_load_lds_dwordx4 v156, s[70:71]
	s_waitcnt vmcnt(8)
	s_waitcnt lgkmcnt(0)
	s_barrier
	v_mfma_i32_16x16x64_i8 v[60:63], v[128:131], v[190:193], v[60:63]
	v_mfma_i32_16x16x64_i8 v[56:59], v[136:139], v[190:193], v[56:59]
	v_mfma_i32_16x16x64_i8 v[52:55], v[128:131], v[198:201], v[52:55]
	v_mfma_i32_16x16x64_i8 v[48:51], v[136:139], v[198:201], v[48:51]
	v_mfma_i32_16x16x64_i8 v[44:47], v[128:131], v[206:209], v[44:47]
	v_mfma_i32_16x16x64_i8 v[40:43], v[136:139], v[206:209], v[40:43]
	v_mfma_i32_16x16x64_i8 v[36:39], v[128:131], v[234:237], v[36:39]
	v_mfma_i32_16x16x64_i8 v[32:35], v[136:139], v[234:237], v[32:35]
	v_mfma_i32_16x16x64_i8 v[60:63], v[132:135], v[194:197], v[60:63]
	v_mfma_i32_16x16x64_i8 v[56:59], v[140:143], v[194:197], v[56:59]
	v_mfma_i32_16x16x64_i8 v[52:55], v[132:135], v[202:205], v[52:55]
	v_mfma_i32_16x16x64_i8 v[48:51], v[140:143], v[202:205], v[48:51]
	v_mfma_i32_16x16x64_i8 v[44:47], v[132:135], v[210:213], v[44:47]
	v_mfma_i32_16x16x64_i8 v[40:43], v[140:143], v[210:213], v[40:43]
	v_mfma_i32_16x16x64_i8 v[36:39], v[132:135], v[238:241], v[36:39]
	v_mfma_i32_16x16x64_i8 v[32:35], v[140:143], v[238:241], v[32:35]
	v_mfma_i32_16x16x64_i8 v[28:31], v[174:177], v[190:193], v[28:31]
	v_mfma_i32_16x16x64_i8 v[24:27], v[182:185], v[190:193], v[24:27]
	v_mfma_i32_16x16x64_i8 v[20:23], v[174:177], v[198:201], v[20:23]
	v_mfma_i32_16x16x64_i8 v[16:19], v[182:185], v[198:201], v[16:19]
	v_mfma_i32_16x16x64_i8 v[12:15], v[174:177], v[206:209], v[12:15]
	v_mfma_i32_16x16x64_i8 v[8:11], v[182:185], v[206:209], v[8:11]
	v_mfma_i32_16x16x64_i8 v[4:7], v[174:177], v[234:237], v[4:7]
	v_mfma_i32_16x16x64_i8 v[0:3], v[182:185], v[234:237], v[0:3]
	v_mfma_i32_16x16x64_i8 v[28:31], v[178:181], v[194:197], v[28:31]
	v_mfma_i32_16x16x64_i8 v[24:27], v[186:189], v[194:197], v[24:27]
	v_mfma_i32_16x16x64_i8 v[20:23], v[178:181], v[202:205], v[20:23]
	v_mfma_i32_16x16x64_i8 v[16:19], v[186:189], v[202:205], v[16:19]
	v_mfma_i32_16x16x64_i8 v[12:15], v[178:181], v[210:213], v[12:15]
	v_mfma_i32_16x16x64_i8 v[8:11], v[186:189], v[210:213], v[8:11]
	v_mfma_i32_16x16x64_i8 v[4:7], v[178:181], v[238:241], v[4:7]
	v_mfma_i32_16x16x64_i8 v[0:3], v[186:189], v[238:241], v[0:3]
	s_barrier
	s_add_i32 s90, 0, 0x1c000
	v_add_u32_e32 v140, s0, v225
	v_add_u32_e32 v144, s90, v225
	ds_read_b128 v[128:131], v140
	ds_read_b128 v[132:135], v140 offset:1024
	ds_read_b128 v[136:139], v140 offset:2048
	ds_read_b128 v[140:143], v140 offset:3072
	ds_read_b128 v[174:177], v144
	ds_read_b128 v[178:181], v144 offset:1024
	ds_read_b128 v[182:185], v144 offset:2048
	ds_read_b128 v[186:189], v144 offset:3072
	s_add_u32 s70, s70, 0x20000
	s_addc_u32 s71, s71, 0
	s_mov_b32 m0, s80
	ds_read_b128 v[190:193], v228 offset:32768
	ds_read_b128 v[194:197], v228 offset:33792
	ds_read_b128 v[198:201], v228 offset:34816
	ds_read_b128 v[202:205], v228 offset:35840
	ds_read_b128 v[206:209], v228 offset:36864
	ds_read_b128 v[210:213], v228 offset:37888
	ds_read_b128 v[234:237], v228 offset:38912
	ds_read_b128 v[238:241], v228 offset:39936
	global_load_lds_dwordx4 v152, s[70:71]
	v_lshl_add_u64 v[248:249], s[70:71], 0, v[156:157]
	s_mov_b32 m0, s82
	s_nop 0
	global_load_lds_dwordx4 v[248:249], off
	s_waitcnt vmcnt(8)
	s_waitcnt lgkmcnt(0)
	s_barrier
	v_mfma_i32_16x16x64_i8 v[124:127], v[128:131], v[190:193], v[124:127]
	v_mfma_i32_16x16x64_i8 v[120:123], v[136:139], v[190:193], v[120:123]
	v_mfma_i32_16x16x64_i8 v[116:119], v[128:131], v[198:201], v[116:119]
	v_mfma_i32_16x16x64_i8 v[112:115], v[136:139], v[198:201], v[112:115]
	v_mfma_i32_16x16x64_i8 v[108:111], v[128:131], v[206:209], v[108:111]
	v_mfma_i32_16x16x64_i8 v[104:107], v[136:139], v[206:209], v[104:107]
	v_mfma_i32_16x16x64_i8 v[100:103], v[128:131], v[234:237], v[100:103]
	v_mfma_i32_16x16x64_i8 v[96:99], v[136:139], v[234:237], v[96:99]
	v_mfma_i32_16x16x64_i8 v[124:127], v[132:135], v[194:197], v[124:127]
	v_mfma_i32_16x16x64_i8 v[120:123], v[140:143], v[194:197], v[120:123]
	v_mfma_i32_16x16x64_i8 v[116:119], v[132:135], v[202:205], v[116:119]
	v_mfma_i32_16x16x64_i8 v[112:115], v[140:143], v[202:205], v[112:115]
	v_mfma_i32_16x16x64_i8 v[108:111], v[132:135], v[210:213], v[108:111]
	v_mfma_i32_16x16x64_i8 v[104:107], v[140:143], v[210:213], v[104:107]
	v_mfma_i32_16x16x64_i8 v[100:103], v[132:135], v[238:241], v[100:103]
	v_mfma_i32_16x16x64_i8 v[96:99], v[140:143], v[238:241], v[96:99]
	v_mfma_i32_16x16x64_i8 v[92:95], v[174:177], v[190:193], v[92:95]
	v_mfma_i32_16x16x64_i8 v[88:91], v[182:185], v[190:193], v[88:91]
	v_mfma_i32_16x16x64_i8 v[84:87], v[174:177], v[198:201], v[84:87]
	v_mfma_i32_16x16x64_i8 v[80:83], v[182:185], v[198:201], v[80:83]
	v_mfma_i32_16x16x64_i8 v[76:79], v[174:177], v[206:209], v[76:79]
	v_mfma_i32_16x16x64_i8 v[72:75], v[182:185], v[206:209], v[72:75]
	v_mfma_i32_16x16x64_i8 v[68:71], v[174:177], v[234:237], v[68:71]
	v_mfma_i32_16x16x64_i8 v[64:67], v[182:185], v[234:237], v[64:67]
	v_mfma_i32_16x16x64_i8 v[92:95], v[178:181], v[194:197], v[92:95]
	v_mfma_i32_16x16x64_i8 v[88:91], v[186:189], v[194:197], v[88:91]
	v_mfma_i32_16x16x64_i8 v[84:87], v[178:181], v[202:205], v[84:87]
	v_mfma_i32_16x16x64_i8 v[80:83], v[186:189], v[202:205], v[80:83]
	v_mfma_i32_16x16x64_i8 v[76:79], v[178:181], v[210:213], v[76:79]
	v_mfma_i32_16x16x64_i8 v[72:75], v[186:189], v[210:213], v[72:75]
	v_mfma_i32_16x16x64_i8 v[68:71], v[178:181], v[238:241], v[68:71]
	v_mfma_i32_16x16x64_i8 v[64:67], v[186:189], v[238:241], v[64:67]
	s_barrier
	s_add_i32 s70, s0, s77
	s_add_u32 s98, s98, s14
	s_addc_u32 s99, s99, s15
	s_mov_b32 m0, s70
	ds_read_b128 v[190:193], v228 offset:49152
	ds_read_b128 v[194:197], v228 offset:50176
	ds_read_b128 v[198:201], v228 offset:51200
	ds_read_b128 v[202:205], v228 offset:52224
	ds_read_b128 v[206:209], v228 offset:53248
	ds_read_b128 v[210:213], v228 offset:54272
	ds_read_b128 v[234:237], v228 offset:55296
	ds_read_b128 v[238:241], v228 offset:56320
	global_load_lds_dwordx4 v154, s[98:99]
	s_add_i32 m0, s70, 0x2000
	s_add_u32 s66, s66, 0x20080
	s_addc_u32 s67, s67, 0
	s_add_i32 s70, s90, s77
	global_load_lds_dwordx4 v158, s[98:99]
	s_mov_b32 m0, s70
	s_nop 0
	global_load_lds_dwordx4 v154, s[66:67]
	s_add_i32 m0, s70, 0x2000
	s_nop 0
	global_load_lds_dwordx4 v158, s[66:67]
	s_add_u32 s100, s100, s14
	s_addc_u32 s101, s101, s15
	s_mov_b32 m0, s84
	s_nop 0
	global_load_lds_dwordx4 v152, s[100:101]
	s_mov_b32 m0, s74
	s_nop 0
	global_load_lds_dwordx4 v156, s[100:101]
	s_waitcnt vmcnt(8)
	s_waitcnt lgkmcnt(0)
	s_barrier
	v_mfma_i32_16x16x64_i8 v[60:63], v[128:131], v[190:193], v[60:63]
	v_mfma_i32_16x16x64_i8 v[56:59], v[136:139], v[190:193], v[56:59]
	v_mfma_i32_16x16x64_i8 v[52:55], v[128:131], v[198:201], v[52:55]
	v_mfma_i32_16x16x64_i8 v[48:51], v[136:139], v[198:201], v[48:51]
	v_mfma_i32_16x16x64_i8 v[44:47], v[128:131], v[206:209], v[44:47]
	v_mfma_i32_16x16x64_i8 v[40:43], v[136:139], v[206:209], v[40:43]
	v_mfma_i32_16x16x64_i8 v[36:39], v[128:131], v[234:237], v[36:39]
	v_mfma_i32_16x16x64_i8 v[32:35], v[136:139], v[234:237], v[32:35]
	v_mfma_i32_16x16x64_i8 v[60:63], v[132:135], v[194:197], v[60:63]
	v_mfma_i32_16x16x64_i8 v[56:59], v[140:143], v[194:197], v[56:59]
	v_mfma_i32_16x16x64_i8 v[52:55], v[132:135], v[202:205], v[52:55]
	v_mfma_i32_16x16x64_i8 v[48:51], v[140:143], v[202:205], v[48:51]
	v_mfma_i32_16x16x64_i8 v[44:47], v[132:135], v[210:213], v[44:47]
	v_mfma_i32_16x16x64_i8 v[40:43], v[140:143], v[210:213], v[40:43]
	v_mfma_i32_16x16x64_i8 v[36:39], v[132:135], v[238:241], v[36:39]
	v_mfma_i32_16x16x64_i8 v[32:35], v[140:143], v[238:241], v[32:35]
	v_mfma_i32_16x16x64_i8 v[28:31], v[174:177], v[190:193], v[28:31]
	v_mfma_i32_16x16x64_i8 v[24:27], v[182:185], v[190:193], v[24:27]
	v_mfma_i32_16x16x64_i8 v[20:23], v[174:177], v[198:201], v[20:23]
	v_mfma_i32_16x16x64_i8 v[16:19], v[182:185], v[198:201], v[16:19]
	v_mfma_i32_16x16x64_i8 v[12:15], v[174:177], v[206:209], v[12:15]
	v_mfma_i32_16x16x64_i8 v[8:11], v[182:185], v[206:209], v[8:11]
	v_mfma_i32_16x16x64_i8 v[4:7], v[174:177], v[234:237], v[4:7]
	v_mfma_i32_16x16x64_i8 v[0:3], v[182:185], v[234:237], v[0:3]
	v_mfma_i32_16x16x64_i8 v[28:31], v[178:181], v[194:197], v[28:31]
	v_mfma_i32_16x16x64_i8 v[24:27], v[186:189], v[194:197], v[24:27]
	v_mfma_i32_16x16x64_i8 v[20:23], v[178:181], v[202:205], v[20:23]
	v_mfma_i32_16x16x64_i8 v[16:19], v[186:189], v[202:205], v[16:19]
	v_mfma_i32_16x16x64_i8 v[12:15], v[178:181], v[210:213], v[12:15]
	v_mfma_i32_16x16x64_i8 v[8:11], v[186:189], v[210:213], v[8:11]
	v_mfma_i32_16x16x64_i8 v[4:7], v[178:181], v[238:241], v[4:7]
	v_mfma_i32_16x16x64_i8 v[0:3], v[186:189], v[238:241], v[0:3]
	s_barrier
	s_add_i32 vcc_lo, vcc_lo, 2
	s_add_u32 s48, s48, 0x100
	s_addc_u32 s49, s49, 0
	s_add_u32 s73, s73, 0x100
	s_addc_u32 s83, s83, 0
	s_cmp_gt_u32 vcc_lo, 5
	s_cbranch_scc0 .LBB0_479
	s_and_b64 vcc, exec, s[56:57]
	s_cbranch_vccz .LBB0_482
	s_barrier

.LBB0_925:
	s_add_u32 s58, s56, 0xfffe0080
	s_addc_u32 s59, s57, -1
	s_add_i32 s83, 0, 0x10000
	s_cmp_eq_u32 s82, 4
	s_cselect_b32 s61, s51, s59
	s_cselect_b32 s60, s79, s58
	s_cselect_b32 s59, s43, s81
	s_cselect_b32 s58, s45, s80
	s_add_i32 s86, 0, 0x14000
	v_add_u32_e32 v150, s83, v182
	v_add_u32_e32 v154, s86, v182
	ds_read_b128 v[138:141], v150
	ds_read_b128 v[142:145], v150 offset:1024
	ds_read_b128 v[146:149], v150 offset:2048
	ds_read_b128 v[150:153], v150 offset:3072
	ds_read_b128 v[166:169], v154
	ds_read_b128 v[190:193], v154 offset:1024
	ds_read_b128 v[194:197], v154 offset:2048
	ds_read_b128 v[198:201], v154 offset:3072
	s_add_i32 m0, s12, 0xc000
	ds_read_b128 v[202:205], v185
	ds_read_b128 v[206:209], v185 offset:1024
	ds_read_b128 v[210:213], v185 offset:2048
	ds_read_b128 v[214:217], v185 offset:3072
	ds_read_b128 v[218:221], v185 offset:4096
	ds_read_b128 v[222:225], v185 offset:5120
	ds_read_b128 v[226:229], v185 offset:6144
	ds_read_b128 v[234:237], v185 offset:7168
	global_load_lds_dwordx4 v134, s[56:57]
	s_add_i32 m0, s12, 0xe000
	s_nop 0
	global_load_lds_dwordx4 v136, s[56:57]
	s_waitcnt vmcnt(8)
	s_waitcnt lgkmcnt(0)
	s_barrier
	v_mfma_i32_16x16x64_i8 v[126:129], v[138:141], v[202:205], v[126:129]
	v_mfma_i32_16x16x64_i8 v[122:125], v[146:149], v[202:205], v[122:125]
	v_mfma_i32_16x16x64_i8 v[110:113], v[138:141], v[210:213], v[110:113]
	v_mfma_i32_16x16x64_i8 v[106:109], v[146:149], v[210:213], v[106:109]
	v_mfma_i32_16x16x64_i8 v[94:97], v[138:141], v[218:221], v[94:97]
	v_mfma_i32_16x16x64_i8 v[90:93], v[146:149], v[218:221], v[90:93]
	v_mfma_i32_16x16x64_i8 v[78:81], v[138:141], v[226:229], v[78:81]
	v_mfma_i32_16x16x64_i8 v[74:77], v[146:149], v[226:229], v[74:77]
	v_mfma_i32_16x16x64_i8 v[126:129], v[142:145], v[206:209], v[126:129]
	v_mfma_i32_16x16x64_i8 v[122:125], v[150:153], v[206:209], v[122:125]
	v_mfma_i32_16x16x64_i8 v[110:113], v[142:145], v[214:217], v[110:113]
	v_mfma_i32_16x16x64_i8 v[106:109], v[150:153], v[214:217], v[106:109]
	v_mfma_i32_16x16x64_i8 v[94:97], v[142:145], v[222:225], v[94:97]
	v_mfma_i32_16x16x64_i8 v[90:93], v[150:153], v[222:225], v[90:93]
	v_mfma_i32_16x16x64_i8 v[78:81], v[142:145], v[234:237], v[78:81]
	v_mfma_i32_16x16x64_i8 v[74:77], v[150:153], v[234:237], v[74:77]
	v_mfma_i32_16x16x64_i8 v[118:121], v[166:169], v[202:205], v[118:121]
	v_mfma_i32_16x16x64_i8 v[114:117], v[194:197], v[202:205], v[114:117]
	v_mfma_i32_16x16x64_i8 v[102:105], v[166:169], v[210:213], v[102:105]
	v_mfma_i32_16x16x64_i8 v[98:101], v[194:197], v[210:213], v[98:101]
	v_mfma_i32_16x16x64_i8 v[86:89], v[166:169], v[218:221], v[86:89]
	v_mfma_i32_16x16x64_i8 v[82:85], v[194:197], v[218:221], v[82:85]
	v_mfma_i32_16x16x64_i8 v[70:73], v[166:169], v[226:229], v[70:73]
	v_mfma_i32_16x16x64_i8 v[66:69], v[194:197], v[226:229], v[66:69]
	v_mfma_i32_16x16x64_i8 v[118:121], v[190:193], v[206:209], v[118:121]
	v_mfma_i32_16x16x64_i8 v[114:117], v[198:201], v[206:209], v[114:117]
	v_mfma_i32_16x16x64_i8 v[102:105], v[190:193], v[214:217], v[102:105]
	v_mfma_i32_16x16x64_i8 v[98:101], v[198:201], v[214:217], v[98:101]
	v_mfma_i32_16x16x64_i8 v[86:89], v[190:193], v[222:225], v[86:89]
	v_mfma_i32_16x16x64_i8 v[82:85], v[198:201], v[222:225], v[82:85]
	v_mfma_i32_16x16x64_i8 v[70:73], v[190:193], v[234:237], v[70:73]
	v_mfma_i32_16x16x64_i8 v[66:69], v[198:201], v[234:237], v[66:69]
	s_barrier
	s_add_i32 s83, s83, s69
	s_mov_b64 s[98:99], s[58:59]
	s_mov_b32 m0, s83
	ds_read_b128 v[202:205], v185 offset:16384
	ds_read_b128 v[206:209], v185 offset:17408
	ds_read_b128 v[210:213], v185 offset:18432
	ds_read_b128 v[214:217], v185 offset:19456
	ds_read_b128 v[218:221], v185 offset:20480
	ds_read_b128 v[222:225], v185 offset:21504
	ds_read_b128 v[226:229], v185 offset:22528
	ds_read_b128 v[234:237], v185 offset:23552
	global_load_lds_dwordx4 v0, s[58:59]
	s_add_i32 m0, s83, 0x2000
	s_add_u32 s84, s58, 0x20000
	s_addc_u32 s85, s59, 0
	s_add_i32 s83, s86, s69
	global_load_lds_dwordx4 v164, s[58:59]
	s_mov_b32 m0, s83
	s_mov_b64 s[100:101], s[60:61]
	global_load_lds_dwordx4 v0, s[84:85]
	s_add_i32 m0, s83, 0x2000
	s_nop 0
	global_load_lds_dwordx4 v164, s[84:85]
	s_mov_b32 m0, s12
	s_nop 0
	global_load_lds_dwordx4 v160, s[60:61]
	s_mov_b32 m0, s49
	s_nop 0
	global_load_lds_dwordx4 v162, s[60:61]
	s_waitcnt vmcnt(8)
	s_waitcnt lgkmcnt(0)
	s_barrier
	v_mfma_i32_16x16x64_i8 v[62:65], v[138:141], v[202:205], v[62:65]
	v_mfma_i32_16x16x64_i8 v[58:61], v[146:149], v[202:205], v[58:61]
	v_mfma_i32_16x16x64_i8 v[46:49], v[138:141], v[210:213], v[46:49]
	v_mfma_i32_16x16x64_i8 v[42:45], v[146:149], v[210:213], v[42:45]
	v_mfma_i32_16x16x64_i8 v[30:33], v[138:141], v[218:221], v[30:33]
	v_mfma_i32_16x16x64_i8 v[26:29], v[146:149], v[218:221], v[26:29]
	v_mfma_i32_16x16x64_i8 v[10:13], v[138:141], v[226:229], v[10:13]
	v_mfma_i32_16x16x64_i8 v[2:5], v[146:149], v[226:229], v[2:5]
	v_mfma_i32_16x16x64_i8 v[62:65], v[142:145], v[206:209], v[62:65]
	v_mfma_i32_16x16x64_i8 v[58:61], v[150:153], v[206:209], v[58:61]
	v_mfma_i32_16x16x64_i8 v[46:49], v[142:145], v[214:217], v[46:49]
	v_mfma_i32_16x16x64_i8 v[42:45], v[150:153], v[214:217], v[42:45]
	v_mfma_i32_16x16x64_i8 v[30:33], v[142:145], v[222:225], v[30:33]
	v_mfma_i32_16x16x64_i8 v[26:29], v[150:153], v[222:225], v[26:29]
	v_mfma_i32_16x16x64_i8 v[10:13], v[142:145], v[234:237], v[10:13]
	v_mfma_i32_16x16x64_i8 v[2:5], v[150:153], v[234:237], v[2:5]
	v_mfma_i32_16x16x64_i8 v[54:57], v[166:169], v[202:205], v[54:57]
	v_mfma_i32_16x16x64_i8 v[50:53], v[194:197], v[202:205], v[50:53]
	v_mfma_i32_16x16x64_i8 v[38:41], v[166:169], v[210:213], v[38:41]
	v_mfma_i32_16x16x64_i8 v[34:37], v[194:197], v[210:213], v[34:37]
	v_mfma_i32_16x16x64_i8 v[22:25], v[166:169], v[218:221], v[22:25]
	v_mfma_i32_16x16x64_i8 v[18:21], v[194:197], v[218:221], v[18:21]
	v_mfma_i32_16x16x64_i8 v[14:17], v[166:169], v[226:229], v[14:17]
	v_mfma_i32_16x16x64_i8 v[6:9], v[194:197], v[226:229], v[6:9]
	v_mfma_i32_16x16x64_i8 v[54:57], v[190:193], v[206:209], v[54:57]
	v_mfma_i32_16x16x64_i8 v[50:53], v[198:201], v[206:209], v[50:53]
	v_mfma_i32_16x16x64_i8 v[38:41], v[190:193], v[214:217], v[38:41]
	v_mfma_i32_16x16x64_i8 v[34:37], v[198:201], v[214:217], v[34:37]
	v_mfma_i32_16x16x64_i8 v[22:25], v[190:193], v[222:225], v[22:25]
	v_mfma_i32_16x16x64_i8 v[18:21], v[198:201], v[222:225], v[18:21]
	v_mfma_i32_16x16x64_i8 v[14:17], v[190:193], v[234:237], v[14:17]
	v_mfma_i32_16x16x64_i8 v[6:9], v[198:201], v[234:237], v[6:9]
	s_barrier
	s_add_i32 s83, 0, 0x18000
	s_add_i32 s84, 0, 0x1c000
	v_add_u32_e32 v150, s83, v182
	v_add_u32_e32 v189, s84, v182
	ds_read_b128 v[138:141], v150
	ds_read_b128 v[142:145], v150 offset:1024
	ds_read_b128 v[146:149], v150 offset:2048
	ds_read_b128 v[150:153], v150 offset:3072
	ds_read_b128 v[166:169], v189
	ds_read_b128 v[190:193], v189 offset:1024
	ds_read_b128 v[194:197], v189 offset:2048
	ds_read_b128 v[198:201], v189 offset:3072
	s_add_u32 s60, s60, 0x20000
	s_addc_u32 s61, s61, 0
	s_mov_b32 m0, s70
	ds_read_b128 v[202:205], v185 offset:32768
	ds_read_b128 v[206:209], v185 offset:33792
	ds_read_b128 v[210:213], v185 offset:34816
	ds_read_b128 v[214:217], v185 offset:35840
	ds_read_b128 v[218:221], v185 offset:36864
	ds_read_b128 v[222:225], v185 offset:37888
	ds_read_b128 v[226:229], v185 offset:38912
	ds_read_b128 v[234:237], v185 offset:39936
	global_load_lds_dwordx4 v160, s[60:61]
	s_mov_b32 m0, s71
	s_nop 0
	global_load_lds_dwordx4 v162, s[60:61]
	s_waitcnt vmcnt(8)
	s_waitcnt lgkmcnt(0)
	s_barrier
	v_mfma_i32_16x16x64_i8 v[126:129], v[138:141], v[202:205], v[126:129]
	v_mfma_i32_16x16x64_i8 v[122:125], v[146:149], v[202:205], v[122:125]
	v_mfma_i32_16x16x64_i8 v[110:113], v[138:141], v[210:213], v[110:113]
	v_mfma_i32_16x16x64_i8 v[106:109], v[146:149], v[210:213], v[106:109]
	v_mfma_i32_16x16x64_i8 v[94:97], v[138:141], v[218:221], v[94:97]
	v_mfma_i32_16x16x64_i8 v[90:93], v[146:149], v[218:221], v[90:93]
	v_mfma_i32_16x16x64_i8 v[78:81], v[138:141], v[226:229], v[78:81]
	v_mfma_i32_16x16x64_i8 v[74:77], v[146:149], v[226:229], v[74:77]
	v_mfma_i32_16x16x64_i8 v[126:129], v[142:145], v[206:209], v[126:129]
	v_mfma_i32_16x16x64_i8 v[122:125], v[150:153], v[206:209], v[122:125]
	v_mfma_i32_16x16x64_i8 v[110:113], v[142:145], v[214:217], v[110:113]
	v_mfma_i32_16x16x64_i8 v[106:109], v[150:153], v[214:217], v[106:109]
	v_mfma_i32_16x16x64_i8 v[94:97], v[142:145], v[222:225], v[94:97]
	v_mfma_i32_16x16x64_i8 v[90:93], v[150:153], v[222:225], v[90:93]
	v_mfma_i32_16x16x64_i8 v[78:81], v[142:145], v[234:237], v[78:81]
	v_mfma_i32_16x16x64_i8 v[74:77], v[150:153], v[234:237], v[74:77]
	v_mfma_i32_16x16x64_i8 v[118:121], v[166:169], v[202:205], v[118:121]
	v_mfma_i32_16x16x64_i8 v[114:117], v[194:197], v[202:205], v[114:117]
	v_mfma_i32_16x16x64_i8 v[102:105], v[166:169], v[210:213], v[102:105]
	v_mfma_i32_16x16x64_i8 v[98:101], v[194:197], v[210:213], v[98:101]
	v_mfma_i32_16x16x64_i8 v[86:89], v[166:169], v[218:221], v[86:89]
	v_mfma_i32_16x16x64_i8 v[82:85], v[194:197], v[218:221], v[82:85]
	v_mfma_i32_16x16x64_i8 v[70:73], v[166:169], v[226:229], v[70:73]
	v_mfma_i32_16x16x64_i8 v[66:69], v[194:197], v[226:229], v[66:69]
	v_mfma_i32_16x16x64_i8 v[118:121], v[190:193], v[206:209], v[118:121]
	v_mfma_i32_16x16x64_i8 v[114:117], v[198:201], v[206:209], v[114:117]
	v_mfma_i32_16x16x64_i8 v[102:105], v[190:193], v[214:217], v[102:105]
	v_mfma_i32_16x16x64_i8 v[98:101], v[198:201], v[214:217], v[98:101]
	v_mfma_i32_16x16x64_i8 v[86:89], v[190:193], v[222:225], v[86:89]
	v_mfma_i32_16x16x64_i8 v[82:85], v[198:201], v[222:225], v[82:85]
	v_mfma_i32_16x16x64_i8 v[70:73], v[190:193], v[234:237], v[70:73]
	v_mfma_i32_16x16x64_i8 v[66:69], v[198:201], v[234:237], v[66:69]
	s_barrier
	s_add_i32 s60, s83, s69
	s_add_u32 s98, s98, s14
	s_addc_u32 s99, s99, s15
	s_mov_b32 m0, s60
	ds_read_b128 v[202:205], v185 offset:49152
	ds_read_b128 v[206:209], v185 offset:50176
	ds_read_b128 v[210:213], v185 offset:51200
	ds_read_b128 v[214:217], v185 offset:52224
	ds_read_b128 v[218:221], v185 offset:53248
	ds_read_b128 v[222:225], v185 offset:54272
	ds_read_b128 v[226:229], v185 offset:55296
	ds_read_b128 v[234:237], v185 offset:56320
	global_load_lds_dwordx4 v0, s[98:99]
	s_add_i32 m0, s60, 0x2000
	s_add_u32 s58, s58, 0x20080
	s_addc_u32 s59, s59, 0
	s_add_i32 s60, s84, s69
	global_load_lds_dwordx4 v164, s[98:99]
	s_mov_b32 m0, s60
	s_nop 0
	global_load_lds_dwordx4 v0, s[58:59]
	s_add_i32 m0, s60, 0x2000
	s_nop 0
	global_load_lds_dwordx4 v164, s[58:59]
	s_add_u32 s100, s100, s14
	s_addc_u32 s101, s101, s15
	s_mov_b32 m0, s72
	s_nop 0
	global_load_lds_dwordx4 v160, s[100:101]
	s_mov_b32 m0, s73
	s_nop 0
	global_load_lds_dwordx4 v162, s[100:101]
	s_waitcnt vmcnt(8)
	s_waitcnt lgkmcnt(0)
	s_barrier
	v_mfma_i32_16x16x64_i8 v[62:65], v[138:141], v[202:205], v[62:65]
	v_mfma_i32_16x16x64_i8 v[58:61], v[146:149], v[202:205], v[58:61]
	v_mfma_i32_16x16x64_i8 v[46:49], v[138:141], v[210:213], v[46:49]
	v_mfma_i32_16x16x64_i8 v[42:45], v[146:149], v[210:213], v[42:45]
	v_mfma_i32_16x16x64_i8 v[30:33], v[138:141], v[218:221], v[30:33]
	v_mfma_i32_16x16x64_i8 v[26:29], v[146:149], v[218:221], v[26:29]
	v_mfma_i32_16x16x64_i8 v[10:13], v[138:141], v[226:229], v[10:13]
	v_mfma_i32_16x16x64_i8 v[2:5], v[146:149], v[226:229], v[2:5]
	v_mfma_i32_16x16x64_i8 v[62:65], v[142:145], v[206:209], v[62:65]
	v_mfma_i32_16x16x64_i8 v[58:61], v[150:153], v[206:209], v[58:61]
	v_mfma_i32_16x16x64_i8 v[46:49], v[142:145], v[214:217], v[46:49]
	v_mfma_i32_16x16x64_i8 v[42:45], v[150:153], v[214:217], v[42:45]
	v_mfma_i32_16x16x64_i8 v[30:33], v[142:145], v[222:225], v[30:33]
	v_mfma_i32_16x16x64_i8 v[26:29], v[150:153], v[222:225], v[26:29]
	v_mfma_i32_16x16x64_i8 v[10:13], v[142:145], v[234:237], v[10:13]
	v_mfma_i32_16x16x64_i8 v[2:5], v[150:153], v[234:237], v[2:5]
	v_mfma_i32_16x16x64_i8 v[54:57], v[166:169], v[202:205], v[54:57]
	v_mfma_i32_16x16x64_i8 v[50:53], v[194:197], v[202:205], v[50:53]
	v_mfma_i32_16x16x64_i8 v[38:41], v[166:169], v[210:213], v[38:41]
	v_mfma_i32_16x16x64_i8 v[34:37], v[194:197], v[210:213], v[34:37]
	v_mfma_i32_16x16x64_i8 v[22:25], v[166:169], v[218:221], v[22:25]
	v_mfma_i32_16x16x64_i8 v[18:21], v[194:197], v[218:221], v[18:21]
	v_mfma_i32_16x16x64_i8 v[14:17], v[166:169], v[226:229], v[14:17]
	v_mfma_i32_16x16x64_i8 v[6:9], v[194:197], v[226:229], v[6:9]
	v_mfma_i32_16x16x64_i8 v[54:57], v[190:193], v[206:209], v[54:57]
	v_mfma_i32_16x16x64_i8 v[50:53], v[198:201], v[206:209], v[50:53]
	v_mfma_i32_16x16x64_i8 v[38:41], v[190:193], v[214:217], v[38:41]
	v_mfma_i32_16x16x64_i8 v[34:37], v[198:201], v[214:217], v[34:37]
	v_mfma_i32_16x16x64_i8 v[22:25], v[190:193], v[222:225], v[22:25]
	v_mfma_i32_16x16x64_i8 v[18:21], v[198:201], v[222:225], v[18:21]
	v_mfma_i32_16x16x64_i8 v[14:17], v[190:193], v[234:237], v[14:17]
	v_mfma_i32_16x16x64_i8 v[6:9], v[198:201], v[234:237], v[6:9]
	s_barrier
	s_add_i32 s82, s82, 2
	s_add_u32 s56, s56, 0x100
	s_addc_u32 s57, s57, 0
	s_add_u32 s80, s80, 0x100
	s_addc_u32 s81, s81, 0
	s_cmp_gt_u32 s82, 5
	s_cbranch_scc0 .LBB0_925
	s_and_b64 vcc, exec, s[40:41]
	s_cbranch_vccz .LBB0_928
	s_barrier

.LBB0_955:
	s_add_u32 s8, s6, 0xfffe0080
	s_addc_u32 s9, s7, -1
	s_add_i32 s70, 0, 0x10000
	s_cmp_eq_u32 s69, 4
	s_cselect_b32 s55, s43, s9
	s_cselect_b32 s54, s49, s8
	v_add_u32_e32 v0, s70, v188
	s_cselect_b32 s9, s39, s68
	s_cselect_b32 s8, s41, s67
	s_add_i32 s72, 0, 0x14000
	ds_read_b128 v[132:135], v0
	ds_read_b128 v[136:139], v0 offset:1024
	ds_read_b128 v[140:143], v0 offset:2048
	ds_read_b128 v[144:147], v0 offset:3072
	v_add_u32_e32 v0, s72, v188
	ds_read_b128 v[148:151], v0
	ds_read_b128 v[152:155], v0 offset:1024
	ds_read_b128 v[176:179], v0 offset:2048
	ds_read_b128 v[180:183], v0 offset:3072
	s_add_i32 m0, s45, 0xc000
	ds_read_b128 v[198:201], v196
	ds_read_b128 v[202:205], v196 offset:1024
	ds_read_b128 v[206:209], v196 offset:2048
	ds_read_b128 v[210:213], v196 offset:3072
	ds_read_b128 v[214:217], v196 offset:4096
	ds_read_b128 v[218:221], v196 offset:5120
	ds_read_b128 v[222:225], v196 offset:6144
	ds_read_b128 v[226:229], v196 offset:7168
	global_load_lds_dwordx4 v172, s[6:7]
	s_add_i32 m0, s45, 0xe000
	s_nop 0
	global_load_lds_dwordx4 v174, s[6:7]
	s_waitcnt vmcnt(8)
	s_waitcnt lgkmcnt(0)
	s_barrier
	v_mfma_f32_16x16x32_bf16 v[128:131], v[132:135], v[198:201], v[128:131]
	v_mfma_f32_16x16x32_bf16 v[124:127], v[140:143], v[198:201], v[124:127]
	v_mfma_f32_16x16x32_bf16 v[120:123], v[132:135], v[206:209], v[120:123]
	v_mfma_f32_16x16x32_bf16 v[116:119], v[140:143], v[206:209], v[116:119]
	v_mfma_f32_16x16x32_bf16 v[112:115], v[132:135], v[214:217], v[112:115]
	v_mfma_f32_16x16x32_bf16 v[108:111], v[140:143], v[214:217], v[108:111]
	v_mfma_f32_16x16x32_bf16 v[104:107], v[132:135], v[222:225], v[104:107]
	v_mfma_f32_16x16x32_bf16 v[100:103], v[140:143], v[222:225], v[100:103]
	v_mfma_f32_16x16x32_bf16 v[128:131], v[136:139], v[202:205], v[128:131]
	v_mfma_f32_16x16x32_bf16 v[124:127], v[144:147], v[202:205], v[124:127]
	v_mfma_f32_16x16x32_bf16 v[120:123], v[136:139], v[210:213], v[120:123]
	v_mfma_f32_16x16x32_bf16 v[116:119], v[144:147], v[210:213], v[116:119]
	v_mfma_f32_16x16x32_bf16 v[112:115], v[136:139], v[218:221], v[112:115]
	v_mfma_f32_16x16x32_bf16 v[108:111], v[144:147], v[218:221], v[108:111]
	v_mfma_f32_16x16x32_bf16 v[104:107], v[136:139], v[226:229], v[104:107]
	v_mfma_f32_16x16x32_bf16 v[100:103], v[144:147], v[226:229], v[100:103]
	v_mfma_f32_16x16x32_bf16 v[96:99], v[148:151], v[198:201], v[96:99]
	v_mfma_f32_16x16x32_bf16 v[92:95], v[176:179], v[198:201], v[92:95]
	v_mfma_f32_16x16x32_bf16 v[88:91], v[148:151], v[206:209], v[88:91]
	v_mfma_f32_16x16x32_bf16 v[84:87], v[176:179], v[206:209], v[84:87]
	v_mfma_f32_16x16x32_bf16 v[80:83], v[148:151], v[214:217], v[80:83]
	v_mfma_f32_16x16x32_bf16 v[76:79], v[176:179], v[214:217], v[76:79]
	v_mfma_f32_16x16x32_bf16 v[72:75], v[148:151], v[222:225], v[72:75]
	v_mfma_f32_16x16x32_bf16 v[68:71], v[176:179], v[222:225], v[68:71]
	v_mfma_f32_16x16x32_bf16 v[96:99], v[152:155], v[202:205], v[96:99]
	v_mfma_f32_16x16x32_bf16 v[92:95], v[180:183], v[202:205], v[92:95]
	v_mfma_f32_16x16x32_bf16 v[88:91], v[152:155], v[210:213], v[88:91]
	v_mfma_f32_16x16x32_bf16 v[84:87], v[180:183], v[210:213], v[84:87]
	v_mfma_f32_16x16x32_bf16 v[80:83], v[152:155], v[218:221], v[80:83]
	v_mfma_f32_16x16x32_bf16 v[76:79], v[180:183], v[218:221], v[76:79]
	v_mfma_f32_16x16x32_bf16 v[72:75], v[152:155], v[226:229], v[72:75]
	v_mfma_f32_16x16x32_bf16 v[68:71], v[180:183], v[226:229], v[68:71]
	s_barrier
	s_add_i32 s70, s70, s58
	s_mov_b64 s[98:99], s[8:9]
	s_mov_b32 m0, s70
	ds_read_b128 v[198:201], v196 offset:16384
	ds_read_b128 v[202:205], v196 offset:17408
	ds_read_b128 v[206:209], v196 offset:18432
	ds_read_b128 v[210:213], v196 offset:19456
	ds_read_b128 v[214:217], v196 offset:20480
	ds_read_b128 v[218:221], v196 offset:21504
	ds_read_b128 v[222:225], v196 offset:22528
	ds_read_b128 v[226:229], v196 offset:23552
	global_load_lds_dwordx4 v166, s[8:9]
	s_add_i32 m0, s70, 0x2000
	s_add_u32 s70, s8, 0x20000
	s_addc_u32 s71, s9, 0
	s_add_i32 s72, s72, s58
	global_load_lds_dwordx4 v164, s[8:9]
	s_mov_b32 m0, s72
	s_mov_b64 s[100:101], s[54:55]
	global_load_lds_dwordx4 v166, s[70:71]
	s_add_i32 m0, s72, 0x2000
	s_nop 0
	global_load_lds_dwordx4 v164, s[70:71]
	s_mov_b32 m0, s45
	s_nop 0
	global_load_lds_dwordx4 v160, s[54:55]
	s_mov_b32 m0, s59
	s_nop 0
	global_load_lds_dwordx4 v162, s[54:55]
	s_waitcnt vmcnt(8)
	s_waitcnt lgkmcnt(0)
	s_barrier
	v_mfma_f32_16x16x32_bf16 v[64:67], v[132:135], v[198:201], v[64:67]
	v_mfma_f32_16x16x32_bf16 v[60:63], v[140:143], v[198:201], v[60:63]
	v_mfma_f32_16x16x32_bf16 v[56:59], v[132:135], v[206:209], v[56:59]
	v_mfma_f32_16x16x32_bf16 v[52:55], v[140:143], v[206:209], v[52:55]
	v_mfma_f32_16x16x32_bf16 v[48:51], v[132:135], v[214:217], v[48:51]
	v_mfma_f32_16x16x32_bf16 v[44:47], v[140:143], v[214:217], v[44:47]
	v_mfma_f32_16x16x32_bf16 v[40:43], v[132:135], v[222:225], v[40:43]
	v_mfma_f32_16x16x32_bf16 v[36:39], v[140:143], v[222:225], v[36:39]
	v_mfma_f32_16x16x32_bf16 v[64:67], v[136:139], v[202:205], v[64:67]
	v_mfma_f32_16x16x32_bf16 v[60:63], v[144:147], v[202:205], v[60:63]
	v_mfma_f32_16x16x32_bf16 v[56:59], v[136:139], v[210:213], v[56:59]
	v_mfma_f32_16x16x32_bf16 v[52:55], v[144:147], v[210:213], v[52:55]
	v_mfma_f32_16x16x32_bf16 v[48:51], v[136:139], v[218:221], v[48:51]
	v_mfma_f32_16x16x32_bf16 v[44:47], v[144:147], v[218:221], v[44:47]
	v_mfma_f32_16x16x32_bf16 v[40:43], v[136:139], v[226:229], v[40:43]
	v_mfma_f32_16x16x32_bf16 v[36:39], v[144:147], v[226:229], v[36:39]
	v_mfma_f32_16x16x32_bf16 v[32:35], v[148:151], v[198:201], v[32:35]
	v_mfma_f32_16x16x32_bf16 v[28:31], v[176:179], v[198:201], v[28:31]
	v_mfma_f32_16x16x32_bf16 v[24:27], v[148:151], v[206:209], v[24:27]
	v_mfma_f32_16x16x32_bf16 v[20:23], v[176:179], v[206:209], v[20:23]
	v_mfma_f32_16x16x32_bf16 v[16:19], v[148:151], v[214:217], v[16:19]
	v_mfma_f32_16x16x32_bf16 v[12:15], v[176:179], v[214:217], v[12:15]
	v_mfma_f32_16x16x32_bf16 v[8:11], v[148:151], v[222:225], v[8:11]
	v_mfma_f32_16x16x32_bf16 v[2:5], v[176:179], v[222:225], v[4:7]
	v_mfma_f32_16x16x32_bf16 v[32:35], v[152:155], v[202:205], v[32:35]
	v_mfma_f32_16x16x32_bf16 v[28:31], v[180:183], v[202:205], v[28:31]
	v_mfma_f32_16x16x32_bf16 v[24:27], v[152:155], v[210:213], v[24:27]
	v_mfma_f32_16x16x32_bf16 v[20:23], v[180:183], v[210:213], v[20:23]
	v_mfma_f32_16x16x32_bf16 v[16:19], v[152:155], v[218:221], v[16:19]
	v_mfma_f32_16x16x32_bf16 v[12:15], v[180:183], v[218:221], v[12:15]
	v_mfma_f32_16x16x32_bf16 v[8:11], v[152:155], v[226:229], v[8:11]
	v_mfma_f32_16x16x32_bf16 v[2:5], v[180:183], v[226:229], v[2:5]
	s_barrier
	s_add_i32 s70, 0, 0x18000
	v_add_u32_e32 v0, s70, v188
	s_add_i32 s71, 0, 0x1c000
	ds_read_b128 v[132:135], v0
	ds_read_b128 v[136:139], v0 offset:1024
	ds_read_b128 v[140:143], v0 offset:2048
	ds_read_b128 v[144:147], v0 offset:3072
	v_add_u32_e32 v0, s71, v188
	ds_read_b128 v[148:151], v0
	ds_read_b128 v[152:155], v0 offset:1024
	ds_read_b128 v[176:179], v0 offset:2048
	ds_read_b128 v[180:183], v0 offset:3072
	s_add_u32 s54, s54, 0x20000
	s_addc_u32 s55, s55, 0
	s_mov_b32 m0, s60
	ds_read_b128 v[198:201], v196 offset:32768
	ds_read_b128 v[202:205], v196 offset:33792
	ds_read_b128 v[206:209], v196 offset:34816
	ds_read_b128 v[210:213], v196 offset:35840
	ds_read_b128 v[214:217], v196 offset:36864
	ds_read_b128 v[218:221], v196 offset:37888
	ds_read_b128 v[222:225], v196 offset:38912
	ds_read_b128 v[226:229], v196 offset:39936
	global_load_lds_dwordx4 v160, s[54:55]
	s_mov_b32 m0, s61
	s_nop 0
	global_load_lds_dwordx4 v162, s[54:55]
	s_waitcnt vmcnt(8)
	s_waitcnt lgkmcnt(0)
	s_barrier
	v_mfma_f32_16x16x32_bf16 v[128:131], v[132:135], v[198:201], v[128:131]
	v_mfma_f32_16x16x32_bf16 v[124:127], v[140:143], v[198:201], v[124:127]
	v_mfma_f32_16x16x32_bf16 v[120:123], v[132:135], v[206:209], v[120:123]
	v_mfma_f32_16x16x32_bf16 v[116:119], v[140:143], v[206:209], v[116:119]
	v_mfma_f32_16x16x32_bf16 v[112:115], v[132:135], v[214:217], v[112:115]
	v_mfma_f32_16x16x32_bf16 v[108:111], v[140:143], v[214:217], v[108:111]
	v_mfma_f32_16x16x32_bf16 v[104:107], v[132:135], v[222:225], v[104:107]
	v_mfma_f32_16x16x32_bf16 v[100:103], v[140:143], v[222:225], v[100:103]
	v_mfma_f32_16x16x32_bf16 v[128:131], v[136:139], v[202:205], v[128:131]
	v_mfma_f32_16x16x32_bf16 v[124:127], v[144:147], v[202:205], v[124:127]
	v_mfma_f32_16x16x32_bf16 v[120:123], v[136:139], v[210:213], v[120:123]
	v_mfma_f32_16x16x32_bf16 v[116:119], v[144:147], v[210:213], v[116:119]
	v_mfma_f32_16x16x32_bf16 v[112:115], v[136:139], v[218:221], v[112:115]
	v_mfma_f32_16x16x32_bf16 v[108:111], v[144:147], v[218:221], v[108:111]
	v_mfma_f32_16x16x32_bf16 v[104:107], v[136:139], v[226:229], v[104:107]
	v_mfma_f32_16x16x32_bf16 v[100:103], v[144:147], v[226:229], v[100:103]
	v_mfma_f32_16x16x32_bf16 v[96:99], v[148:151], v[198:201], v[96:99]
	v_mfma_f32_16x16x32_bf16 v[92:95], v[176:179], v[198:201], v[92:95]
	v_mfma_f32_16x16x32_bf16 v[88:91], v[148:151], v[206:209], v[88:91]
	v_mfma_f32_16x16x32_bf16 v[84:87], v[176:179], v[206:209], v[84:87]
	v_mfma_f32_16x16x32_bf16 v[80:83], v[148:151], v[214:217], v[80:83]
	v_mfma_f32_16x16x32_bf16 v[76:79], v[176:179], v[214:217], v[76:79]
	v_mfma_f32_16x16x32_bf16 v[72:75], v[148:151], v[222:225], v[72:75]
	v_mfma_f32_16x16x32_bf16 v[68:71], v[176:179], v[222:225], v[68:71]
	v_mfma_f32_16x16x32_bf16 v[96:99], v[152:155], v[202:205], v[96:99]
	v_mfma_f32_16x16x32_bf16 v[92:95], v[180:183], v[202:205], v[92:95]
	v_mfma_f32_16x16x32_bf16 v[88:91], v[152:155], v[210:213], v[88:91]
	v_mfma_f32_16x16x32_bf16 v[84:87], v[180:183], v[210:213], v[84:87]
	v_mfma_f32_16x16x32_bf16 v[80:83], v[152:155], v[218:221], v[80:83]
	v_mfma_f32_16x16x32_bf16 v[76:79], v[180:183], v[218:221], v[76:79]
	v_mfma_f32_16x16x32_bf16 v[72:75], v[152:155], v[226:229], v[72:75]
	v_mfma_f32_16x16x32_bf16 v[68:71], v[180:183], v[226:229], v[68:71]
	s_barrier
	s_add_i32 s54, s70, s58
	s_add_u32 s98, s98, s14
	s_addc_u32 s99, s99, s15
	s_mov_b32 m0, s54
	ds_read_b128 v[198:201], v196 offset:49152
	ds_read_b128 v[202:205], v196 offset:50176
	ds_read_b128 v[206:209], v196 offset:51200
	ds_read_b128 v[210:213], v196 offset:52224
	ds_read_b128 v[214:217], v196 offset:53248
	ds_read_b128 v[218:221], v196 offset:54272
	ds_read_b128 v[222:225], v196 offset:55296
	ds_read_b128 v[226:229], v196 offset:56320
	global_load_lds_dwordx4 v166, s[98:99]
	s_add_i32 m0, s54, 0x2000
	s_add_u32 s8, s8, 0x20080
	s_addc_u32 s9, s9, 0
	s_add_i32 s54, s71, s58
	global_load_lds_dwordx4 v164, s[98:99]
	s_mov_b32 m0, s54
	s_nop 0
	global_load_lds_dwordx4 v166, s[8:9]
	s_add_i32 m0, s54, 0x2000
	s_nop 0
	global_load_lds_dwordx4 v164, s[8:9]
	s_add_u32 s100, s100, s14
	s_addc_u32 s101, s101, s15
	s_mov_b32 m0, s63
	s_nop 0
	global_load_lds_dwordx4 v160, s[100:101]
	s_mov_b32 m0, s64
	s_nop 0
	global_load_lds_dwordx4 v162, s[100:101]
	s_waitcnt vmcnt(8)
	s_waitcnt lgkmcnt(0)
	s_barrier
	v_mfma_f32_16x16x32_bf16 v[64:67], v[132:135], v[198:201], v[64:67]
	v_mfma_f32_16x16x32_bf16 v[60:63], v[140:143], v[198:201], v[60:63]
	v_mfma_f32_16x16x32_bf16 v[56:59], v[132:135], v[206:209], v[56:59]
	v_mfma_f32_16x16x32_bf16 v[52:55], v[140:143], v[206:209], v[52:55]
	v_mfma_f32_16x16x32_bf16 v[48:51], v[132:135], v[214:217], v[48:51]
	v_mfma_f32_16x16x32_bf16 v[44:47], v[140:143], v[214:217], v[44:47]
	v_mfma_f32_16x16x32_bf16 v[40:43], v[132:135], v[222:225], v[40:43]
	v_mfma_f32_16x16x32_bf16 v[36:39], v[140:143], v[222:225], v[36:39]
	v_mfma_f32_16x16x32_bf16 v[64:67], v[136:139], v[202:205], v[64:67]
	v_mfma_f32_16x16x32_bf16 v[60:63], v[144:147], v[202:205], v[60:63]
	v_mfma_f32_16x16x32_bf16 v[56:59], v[136:139], v[210:213], v[56:59]
	v_mfma_f32_16x16x32_bf16 v[52:55], v[144:147], v[210:213], v[52:55]
	v_mfma_f32_16x16x32_bf16 v[48:51], v[136:139], v[218:221], v[48:51]
	v_mfma_f32_16x16x32_bf16 v[44:47], v[144:147], v[218:221], v[44:47]
	v_mfma_f32_16x16x32_bf16 v[40:43], v[136:139], v[226:229], v[40:43]
	v_mfma_f32_16x16x32_bf16 v[36:39], v[144:147], v[226:229], v[36:39]
	v_mfma_f32_16x16x32_bf16 v[32:35], v[148:151], v[198:201], v[32:35]
	v_mfma_f32_16x16x32_bf16 v[28:31], v[176:179], v[198:201], v[28:31]
	v_mfma_f32_16x16x32_bf16 v[24:27], v[148:151], v[206:209], v[24:27]
	v_mfma_f32_16x16x32_bf16 v[20:23], v[176:179], v[206:209], v[20:23]
	v_mfma_f32_16x16x32_bf16 v[16:19], v[148:151], v[214:217], v[16:19]
	v_mfma_f32_16x16x32_bf16 v[12:15], v[176:179], v[214:217], v[12:15]
	v_mfma_f32_16x16x32_bf16 v[6:9], v[148:151], v[222:225], v[8:11]
	v_mfma_f32_16x16x32_bf16 v[2:5], v[176:179], v[222:225], v[2:5]
	v_mfma_f32_16x16x32_bf16 v[32:35], v[152:155], v[202:205], v[32:35]
	v_mfma_f32_16x16x32_bf16 v[28:31], v[180:183], v[202:205], v[28:31]
	v_mfma_f32_16x16x32_bf16 v[24:27], v[152:155], v[210:213], v[24:27]
	v_mfma_f32_16x16x32_bf16 v[20:23], v[180:183], v[210:213], v[20:23]
	v_mfma_f32_16x16x32_bf16 v[16:19], v[152:155], v[218:221], v[16:19]
	v_mfma_f32_16x16x32_bf16 v[12:15], v[180:183], v[218:221], v[12:15]
	v_mfma_f32_16x16x32_bf16 v[8:11], v[152:155], v[226:229], v[6:9]
	v_mfma_f32_16x16x32_bf16 v[4:7], v[180:183], v[226:229], v[2:5]
	s_barrier
	s_add_i32 s69, s69, 2
	s_add_u32 s6, s6, 0x100
	s_addc_u32 s7, s7, 0
	s_add_u32 s67, s67, 0x100
	s_addc_u32 s68, s68, 0
	s_cmp_gt_u32 s69, 5
	s_cbranch_scc0 .LBB0_955
	s_and_b64 vcc, exec, s[34:35]
	s_cbranch_vccz .LBB0_958
	s_barrier

.LBB0_1167:
	s_add_u32 s60, s48, 0xfffc0080
	s_addc_u32 s61, s49, -1
	s_add_i32 s66, 0, 0x10000
	s_cmp_eq_u32 s65, 12
	s_cselect_b32 s63, s14, s61
	s_cselect_b32 s62, s51, s60
	v_add_u32_e32 v0, s66, v169
	s_cselect_b32 s61, s45, s64
	s_cselect_b32 s60, s57, s59
	s_add_i32 s68, 0, 0x14000
	ds_read_b128 v[148:151], v0
	ds_read_b128 v[152:155], v0 offset:1024
	ds_read_b128 v[156:159], v0 offset:2048
	ds_read_b128 v[190:193], v0 offset:3072
	v_add_u32_e32 v0, s68, v169
	ds_read_b128 v[194:197], v0
	ds_read_b128 v[198:201], v0 offset:1024
	ds_read_b128 v[202:205], v0 offset:2048
	ds_read_b128 v[206:209], v0 offset:3072
	s_add_i32 m0, s79, 0xc000
	ds_read_b128 v[210:213], v188
	ds_read_b128 v[214:217], v188 offset:1024
	ds_read_b128 v[218:221], v188 offset:2048
	ds_read_b128 v[222:225], v188 offset:3072
	ds_read_b128 v[226:229], v188 offset:4096
	ds_read_b128 v[234:237], v188 offset:5120
	ds_read_b128 v[238:241], v188 offset:6144
	ds_read_b128 v[242:245], v188 offset:7168
	global_load_lds_dwordx4 v144, s[48:49]
	s_add_i32 m0, s79, 0xe000
	s_nop 0
	global_load_lds_dwordx4 v146, s[48:49]
	s_waitcnt vmcnt(8)
	s_waitcnt lgkmcnt(0)
	s_barrier
	v_mfma_f32_16x16x32_bf16 v[126:129], v[148:151], v[210:213], v[126:129]
	v_mfma_f32_16x16x32_bf16 v[122:125], v[156:159], v[210:213], v[122:125]
	v_mfma_f32_16x16x32_bf16 v[110:113], v[148:151], v[218:221], v[110:113]
	v_mfma_f32_16x16x32_bf16 v[106:109], v[156:159], v[218:221], v[106:109]
	v_mfma_f32_16x16x32_bf16 v[94:97], v[148:151], v[226:229], v[94:97]
	v_mfma_f32_16x16x32_bf16 v[90:93], v[156:159], v[226:229], v[90:93]
	v_mfma_f32_16x16x32_bf16 v[78:81], v[148:151], v[238:241], v[78:81]
	v_mfma_f32_16x16x32_bf16 v[74:77], v[156:159], v[238:241], v[74:77]
	v_mfma_f32_16x16x32_bf16 v[126:129], v[152:155], v[214:217], v[126:129]
	v_mfma_f32_16x16x32_bf16 v[122:125], v[190:193], v[214:217], v[122:125]
	v_mfma_f32_16x16x32_bf16 v[110:113], v[152:155], v[222:225], v[110:113]
	v_mfma_f32_16x16x32_bf16 v[106:109], v[190:193], v[222:225], v[106:109]
	v_mfma_f32_16x16x32_bf16 v[94:97], v[152:155], v[234:237], v[94:97]
	v_mfma_f32_16x16x32_bf16 v[90:93], v[190:193], v[234:237], v[90:93]
	v_mfma_f32_16x16x32_bf16 v[78:81], v[152:155], v[242:245], v[78:81]
	v_mfma_f32_16x16x32_bf16 v[74:77], v[190:193], v[242:245], v[74:77]
	v_mfma_f32_16x16x32_bf16 v[118:121], v[194:197], v[210:213], v[118:121]
	v_mfma_f32_16x16x32_bf16 v[114:117], v[202:205], v[210:213], v[114:117]
	v_mfma_f32_16x16x32_bf16 v[102:105], v[194:197], v[218:221], v[102:105]
	v_mfma_f32_16x16x32_bf16 v[98:101], v[202:205], v[218:221], v[98:101]
	v_mfma_f32_16x16x32_bf16 v[86:89], v[194:197], v[226:229], v[86:89]
	v_mfma_f32_16x16x32_bf16 v[82:85], v[202:205], v[226:229], v[82:85]
	v_mfma_f32_16x16x32_bf16 v[70:73], v[194:197], v[238:241], v[70:73]
	v_mfma_f32_16x16x32_bf16 v[66:69], v[202:205], v[238:241], v[66:69]
	v_mfma_f32_16x16x32_bf16 v[118:121], v[198:201], v[214:217], v[118:121]
	v_mfma_f32_16x16x32_bf16 v[114:117], v[206:209], v[214:217], v[114:117]
	v_mfma_f32_16x16x32_bf16 v[102:105], v[198:201], v[222:225], v[102:105]
	v_mfma_f32_16x16x32_bf16 v[98:101], v[206:209], v[222:225], v[98:101]
	v_mfma_f32_16x16x32_bf16 v[86:89], v[198:201], v[234:237], v[86:89]
	v_mfma_f32_16x16x32_bf16 v[82:85], v[206:209], v[234:237], v[82:85]
	v_mfma_f32_16x16x32_bf16 v[70:73], v[198:201], v[242:245], v[70:73]
	v_mfma_f32_16x16x32_bf16 v[66:69], v[206:209], v[242:245], v[66:69]
	s_barrier
	s_add_i32 s66, s66, s78
	s_mov_b64 s[98:99], s[60:61]
	s_mov_b32 m0, s66
	ds_read_b128 v[210:213], v188 offset:16384
	ds_read_b128 v[214:217], v188 offset:17408
	ds_read_b128 v[218:221], v188 offset:18432
	ds_read_b128 v[222:225], v188 offset:19456
	ds_read_b128 v[226:229], v188 offset:20480
	ds_read_b128 v[234:237], v188 offset:21504
	ds_read_b128 v[238:241], v188 offset:22528
	ds_read_b128 v[242:245], v188 offset:23552
	global_load_lds_dwordx4 v136, s[60:61]
	s_add_i32 m0, s66, 0x2000
	s_add_u32 s66, s60, 0x40000
	s_addc_u32 s67, s61, 0
	s_add_i32 s68, s68, s78
	global_load_lds_dwordx4 v140, s[60:61]
	s_mov_b32 m0, s68
	s_mov_b64 s[100:101], s[62:63]
	global_load_lds_dwordx4 v136, s[66:67]
	s_add_i32 m0, s68, 0x2000
	s_nop 0
	global_load_lds_dwordx4 v140, s[66:67]
	s_mov_b32 m0, s79
	s_nop 0
	global_load_lds_dwordx4 v134, s[62:63]
	s_mov_b32 m0, s80
	s_nop 0
	global_load_lds_dwordx4 v138, s[62:63]
	s_waitcnt vmcnt(8)
	s_waitcnt lgkmcnt(0)
	s_barrier
	v_mfma_f32_16x16x32_bf16 v[62:65], v[148:151], v[210:213], v[62:65]
	v_mfma_f32_16x16x32_bf16 v[58:61], v[156:159], v[210:213], v[58:61]
	v_mfma_f32_16x16x32_bf16 v[46:49], v[148:151], v[218:221], v[46:49]
	v_mfma_f32_16x16x32_bf16 v[42:45], v[156:159], v[218:221], v[42:45]
	v_mfma_f32_16x16x32_bf16 v[30:33], v[148:151], v[226:229], v[30:33]
	v_mfma_f32_16x16x32_bf16 v[26:29], v[156:159], v[226:229], v[26:29]
	v_mfma_f32_16x16x32_bf16 v[14:17], v[148:151], v[238:241], v[14:17]
	v_mfma_f32_16x16x32_bf16 v[10:13], v[156:159], v[238:241], v[10:13]
	v_mfma_f32_16x16x32_bf16 v[62:65], v[152:155], v[214:217], v[62:65]
	v_mfma_f32_16x16x32_bf16 v[58:61], v[190:193], v[214:217], v[58:61]
	v_mfma_f32_16x16x32_bf16 v[46:49], v[152:155], v[222:225], v[46:49]
	v_mfma_f32_16x16x32_bf16 v[42:45], v[190:193], v[222:225], v[42:45]
	v_mfma_f32_16x16x32_bf16 v[30:33], v[152:155], v[234:237], v[30:33]
	v_mfma_f32_16x16x32_bf16 v[26:29], v[190:193], v[234:237], v[26:29]
	v_mfma_f32_16x16x32_bf16 v[14:17], v[152:155], v[242:245], v[14:17]
	v_mfma_f32_16x16x32_bf16 v[10:13], v[190:193], v[242:245], v[10:13]
	v_mfma_f32_16x16x32_bf16 v[54:57], v[194:197], v[210:213], v[54:57]
	v_mfma_f32_16x16x32_bf16 v[50:53], v[202:205], v[210:213], v[50:53]
	v_mfma_f32_16x16x32_bf16 v[38:41], v[194:197], v[218:221], v[38:41]
	v_mfma_f32_16x16x32_bf16 v[34:37], v[202:205], v[218:221], v[34:37]
	v_mfma_f32_16x16x32_bf16 v[22:25], v[194:197], v[226:229], v[22:25]
	v_mfma_f32_16x16x32_bf16 v[18:21], v[202:205], v[226:229], v[18:21]
	v_mfma_f32_16x16x32_bf16 v[6:9], v[194:197], v[238:241], v[6:9]
	v_mfma_f32_16x16x32_bf16 v[2:5], v[202:205], v[238:241], v[2:5]
	v_mfma_f32_16x16x32_bf16 v[54:57], v[198:201], v[214:217], v[54:57]
	v_mfma_f32_16x16x32_bf16 v[50:53], v[206:209], v[214:217], v[50:53]
	v_mfma_f32_16x16x32_bf16 v[38:41], v[198:201], v[222:225], v[38:41]
	v_mfma_f32_16x16x32_bf16 v[34:37], v[206:209], v[222:225], v[34:37]
	v_mfma_f32_16x16x32_bf16 v[22:25], v[198:201], v[234:237], v[22:25]
	v_mfma_f32_16x16x32_bf16 v[18:21], v[206:209], v[234:237], v[18:21]
	v_mfma_f32_16x16x32_bf16 v[6:9], v[198:201], v[242:245], v[6:9]
	v_mfma_f32_16x16x32_bf16 v[2:5], v[206:209], v[242:245], v[2:5]
	s_barrier
	s_add_i32 s66, 0, 0x18000
	v_add_u32_e32 v0, s66, v169
	s_add_i32 s67, 0, 0x1c000
	ds_read_b128 v[148:151], v0
	ds_read_b128 v[152:155], v0 offset:1024
	ds_read_b128 v[156:159], v0 offset:2048
	ds_read_b128 v[190:193], v0 offset:3072
	v_add_u32_e32 v0, s67, v169
	ds_read_b128 v[194:197], v0
	ds_read_b128 v[198:201], v0 offset:1024
	ds_read_b128 v[202:205], v0 offset:2048
	ds_read_b128 v[206:209], v0 offset:3072
	s_add_u32 s62, s62, 0x40000
	s_addc_u32 s63, s63, 0
	s_mov_b32 m0, s81
	ds_read_b128 v[210:213], v188 offset:32768
	ds_read_b128 v[214:217], v188 offset:33792
	ds_read_b128 v[218:221], v188 offset:34816
	ds_read_b128 v[222:225], v188 offset:35840
	ds_read_b128 v[226:229], v188 offset:36864
	ds_read_b128 v[234:237], v188 offset:37888
	ds_read_b128 v[238:241], v188 offset:38912
	ds_read_b128 v[242:245], v188 offset:39936
	global_load_lds_dwordx4 v134, s[62:63]
	s_mov_b32 m0, s82
	s_nop 0
	global_load_lds_dwordx4 v138, s[62:63]
	s_waitcnt vmcnt(8)
	s_waitcnt lgkmcnt(0)
	s_barrier
	v_mfma_f32_16x16x32_bf16 v[126:129], v[148:151], v[210:213], v[126:129]
	v_mfma_f32_16x16x32_bf16 v[122:125], v[156:159], v[210:213], v[122:125]
	v_mfma_f32_16x16x32_bf16 v[110:113], v[148:151], v[218:221], v[110:113]
	v_mfma_f32_16x16x32_bf16 v[106:109], v[156:159], v[218:221], v[106:109]
	v_mfma_f32_16x16x32_bf16 v[94:97], v[148:151], v[226:229], v[94:97]
	v_mfma_f32_16x16x32_bf16 v[90:93], v[156:159], v[226:229], v[90:93]
	v_mfma_f32_16x16x32_bf16 v[78:81], v[148:151], v[238:241], v[78:81]
	v_mfma_f32_16x16x32_bf16 v[74:77], v[156:159], v[238:241], v[74:77]
	v_mfma_f32_16x16x32_bf16 v[126:129], v[152:155], v[214:217], v[126:129]
	v_mfma_f32_16x16x32_bf16 v[122:125], v[190:193], v[214:217], v[122:125]
	v_mfma_f32_16x16x32_bf16 v[110:113], v[152:155], v[222:225], v[110:113]
	v_mfma_f32_16x16x32_bf16 v[106:109], v[190:193], v[222:225], v[106:109]
	v_mfma_f32_16x16x32_bf16 v[94:97], v[152:155], v[234:237], v[94:97]
	v_mfma_f32_16x16x32_bf16 v[90:93], v[190:193], v[234:237], v[90:93]
	v_mfma_f32_16x16x32_bf16 v[78:81], v[152:155], v[242:245], v[78:81]
	v_mfma_f32_16x16x32_bf16 v[74:77], v[190:193], v[242:245], v[74:77]
	v_mfma_f32_16x16x32_bf16 v[118:121], v[194:197], v[210:213], v[118:121]
	v_mfma_f32_16x16x32_bf16 v[114:117], v[202:205], v[210:213], v[114:117]
	v_mfma_f32_16x16x32_bf16 v[102:105], v[194:197], v[218:221], v[102:105]
	v_mfma_f32_16x16x32_bf16 v[98:101], v[202:205], v[218:221], v[98:101]
	v_mfma_f32_16x16x32_bf16 v[86:89], v[194:197], v[226:229], v[86:89]
	v_mfma_f32_16x16x32_bf16 v[82:85], v[202:205], v[226:229], v[82:85]
	v_mfma_f32_16x16x32_bf16 v[70:73], v[194:197], v[238:241], v[70:73]
	v_mfma_f32_16x16x32_bf16 v[66:69], v[202:205], v[238:241], v[66:69]
	v_mfma_f32_16x16x32_bf16 v[118:121], v[198:201], v[214:217], v[118:121]
	v_mfma_f32_16x16x32_bf16 v[114:117], v[206:209], v[214:217], v[114:117]
	v_mfma_f32_16x16x32_bf16 v[102:105], v[198:201], v[222:225], v[102:105]
	v_mfma_f32_16x16x32_bf16 v[98:101], v[206:209], v[222:225], v[98:101]
	v_mfma_f32_16x16x32_bf16 v[86:89], v[198:201], v[234:237], v[86:89]
	v_mfma_f32_16x16x32_bf16 v[82:85], v[206:209], v[234:237], v[82:85]
	v_mfma_f32_16x16x32_bf16 v[70:73], v[198:201], v[242:245], v[70:73]
	v_mfma_f32_16x16x32_bf16 v[66:69], v[206:209], v[242:245], v[66:69]
	s_barrier
	s_add_i32 s62, s66, s78
	s_add_u32 s98, s98, s16
	s_addc_u32 s99, s99, s17
	s_mov_b32 m0, s62
	ds_read_b128 v[210:213], v188 offset:49152
	ds_read_b128 v[214:217], v188 offset:50176
	ds_read_b128 v[218:221], v188 offset:51200
	ds_read_b128 v[222:225], v188 offset:52224
	ds_read_b128 v[226:229], v188 offset:53248
	ds_read_b128 v[234:237], v188 offset:54272
	ds_read_b128 v[238:241], v188 offset:55296
	ds_read_b128 v[242:245], v188 offset:56320
	global_load_lds_dwordx4 v136, s[98:99]
	s_add_i32 m0, s62, 0x2000
	s_add_u32 s60, s60, 0x40080
	s_addc_u32 s61, s61, 0
	s_add_i32 s62, s67, s78
	global_load_lds_dwordx4 v140, s[98:99]
	s_mov_b32 m0, s62
	s_nop 0
	global_load_lds_dwordx4 v136, s[60:61]
	s_add_i32 m0, s62, 0x2000
	s_nop 0
	global_load_lds_dwordx4 v140, s[60:61]
	s_add_u32 s100, s100, s16
	s_addc_u32 s101, s101, s17
	s_mov_b32 m0, s85
	s_nop 0
	global_load_lds_dwordx4 v134, s[100:101]
	s_mov_b32 m0, s86
	s_nop 0
	global_load_lds_dwordx4 v138, s[100:101]
	s_waitcnt vmcnt(8)
	s_waitcnt lgkmcnt(0)
	s_barrier
	v_mfma_f32_16x16x32_bf16 v[62:65], v[148:151], v[210:213], v[62:65]
	v_mfma_f32_16x16x32_bf16 v[58:61], v[156:159], v[210:213], v[58:61]
	v_mfma_f32_16x16x32_bf16 v[46:49], v[148:151], v[218:221], v[46:49]
	v_mfma_f32_16x16x32_bf16 v[42:45], v[156:159], v[218:221], v[42:45]
	v_mfma_f32_16x16x32_bf16 v[30:33], v[148:151], v[226:229], v[30:33]
	v_mfma_f32_16x16x32_bf16 v[26:29], v[156:159], v[226:229], v[26:29]
	v_mfma_f32_16x16x32_bf16 v[14:17], v[148:151], v[238:241], v[14:17]
	v_mfma_f32_16x16x32_bf16 v[10:13], v[156:159], v[238:241], v[10:13]
	v_mfma_f32_16x16x32_bf16 v[62:65], v[152:155], v[214:217], v[62:65]
	v_mfma_f32_16x16x32_bf16 v[58:61], v[190:193], v[214:217], v[58:61]
	v_mfma_f32_16x16x32_bf16 v[46:49], v[152:155], v[222:225], v[46:49]
	v_mfma_f32_16x16x32_bf16 v[42:45], v[190:193], v[222:225], v[42:45]
	v_mfma_f32_16x16x32_bf16 v[30:33], v[152:155], v[234:237], v[30:33]
	v_mfma_f32_16x16x32_bf16 v[26:29], v[190:193], v[234:237], v[26:29]
	v_mfma_f32_16x16x32_bf16 v[14:17], v[152:155], v[242:245], v[14:17]
	v_mfma_f32_16x16x32_bf16 v[10:13], v[190:193], v[242:245], v[10:13]
	v_mfma_f32_16x16x32_bf16 v[54:57], v[194:197], v[210:213], v[54:57]
	v_mfma_f32_16x16x32_bf16 v[50:53], v[202:205], v[210:213], v[50:53]
	v_mfma_f32_16x16x32_bf16 v[38:41], v[194:197], v[218:221], v[38:41]
	v_mfma_f32_16x16x32_bf16 v[34:37], v[202:205], v[218:221], v[34:37]
	v_mfma_f32_16x16x32_bf16 v[22:25], v[194:197], v[226:229], v[22:25]
	v_mfma_f32_16x16x32_bf16 v[18:21], v[202:205], v[226:229], v[18:21]
	v_mfma_f32_16x16x32_bf16 v[6:9], v[194:197], v[238:241], v[6:9]
	v_mfma_f32_16x16x32_bf16 v[2:5], v[202:205], v[238:241], v[2:5]
	v_mfma_f32_16x16x32_bf16 v[54:57], v[198:201], v[214:217], v[54:57]
	v_mfma_f32_16x16x32_bf16 v[50:53], v[206:209], v[214:217], v[50:53]
	v_mfma_f32_16x16x32_bf16 v[38:41], v[198:201], v[222:225], v[38:41]
	v_mfma_f32_16x16x32_bf16 v[34:37], v[206:209], v[222:225], v[34:37]
	v_mfma_f32_16x16x32_bf16 v[22:25], v[198:201], v[234:237], v[22:25]
	v_mfma_f32_16x16x32_bf16 v[18:21], v[206:209], v[234:237], v[18:21]
	v_mfma_f32_16x16x32_bf16 v[6:9], v[198:201], v[242:245], v[6:9]
	v_mfma_f32_16x16x32_bf16 v[2:5], v[206:209], v[242:245], v[2:5]
	s_barrier
	s_add_i32 s65, s65, 2
	s_add_u32 s48, s48, 0x100
	s_addc_u32 s49, s49, 0
	s_add_u32 s59, s59, 0x100
	s_addc_u32 s64, s64, 0
	s_cmp_gt_u32 s65, 13
	s_cbranch_scc0 .LBB0_1167
	s_and_b64 vcc, exec, s[38:39]
	s_cbranch_vccz .LBB0_1171
	s_barrier
	s_andn2_b64 vcc, exec, s[20:21]
	s_cbranch_vccz .LBB0_1172

.LBB0_1636:
	s_add_u32 s56, s48, 0x100
	s_addc_u32 s57, s49, 0
	s_add_i32 s64, 0, 0x10000
	s_cmp_eq_u32 s63, 40
	s_cselect_b32 s61, s13, s57
	s_cselect_b32 s60, s12, s56
	v_add_u32_e32 v0, s64, v169
	s_cselect_b32 s59, s53, s55
	s_cselect_b32 s58, s52, s16
	s_add_i32 s65, 0, 0x14000
	ds_read_b128 v[148:151], v0
	ds_read_b128 v[152:155], v0 offset:1024
	ds_read_b128 v[156:159], v0 offset:2048
	ds_read_b128 v[190:193], v0 offset:3072
	v_add_u32_e32 v0, s65, v169
	ds_read_b128 v[194:197], v0
	ds_read_b128 v[198:201], v0 offset:1024
	ds_read_b128 v[202:205], v0 offset:2048
	ds_read_b128 v[206:209], v0 offset:3072
	v_lshl_add_u64 v[230:231], s[48:49], 0, v[144:145]
	s_add_i32 m0, s79, 0xc000
	ds_read_b128 v[210:213], v188
	ds_read_b128 v[214:217], v188 offset:1024
	ds_read_b128 v[218:221], v188 offset:2048
	ds_read_b128 v[222:225], v188 offset:3072
	ds_read_b128 v[226:229], v188 offset:4096
	ds_read_b128 v[234:237], v188 offset:5120
	ds_read_b128 v[238:241], v188 offset:6144
	ds_read_b128 v[242:245], v188 offset:7168
	global_load_lds_dwordx4 v[230:231], off
	v_lshl_add_u64 v[230:231], s[48:49], 0, v[146:147]
	s_add_i32 m0, s79, 0xe000
	s_nop 0
	global_load_lds_dwordx4 v[230:231], off
	s_waitcnt vmcnt(8)
	s_waitcnt lgkmcnt(0)
	s_barrier
	v_mfma_f32_16x16x32_bf16 v[126:129], v[148:151], v[210:213], v[126:129]
	v_mfma_f32_16x16x32_bf16 v[122:125], v[156:159], v[210:213], v[122:125]
	v_mfma_f32_16x16x32_bf16 v[110:113], v[148:151], v[218:221], v[110:113]
	v_mfma_f32_16x16x32_bf16 v[106:109], v[156:159], v[218:221], v[106:109]
	v_mfma_f32_16x16x32_bf16 v[94:97], v[148:151], v[226:229], v[94:97]
	v_mfma_f32_16x16x32_bf16 v[90:93], v[156:159], v[226:229], v[90:93]
	v_mfma_f32_16x16x32_bf16 v[78:81], v[148:151], v[238:241], v[78:81]
	v_mfma_f32_16x16x32_bf16 v[74:77], v[156:159], v[238:241], v[74:77]
	v_mfma_f32_16x16x32_bf16 v[126:129], v[152:155], v[214:217], v[126:129]
	v_mfma_f32_16x16x32_bf16 v[122:125], v[190:193], v[214:217], v[122:125]
	v_mfma_f32_16x16x32_bf16 v[110:113], v[152:155], v[222:225], v[110:113]
	v_mfma_f32_16x16x32_bf16 v[106:109], v[190:193], v[222:225], v[106:109]
	v_mfma_f32_16x16x32_bf16 v[94:97], v[152:155], v[234:237], v[94:97]
	v_mfma_f32_16x16x32_bf16 v[90:93], v[190:193], v[234:237], v[90:93]
	v_mfma_f32_16x16x32_bf16 v[78:81], v[152:155], v[242:245], v[78:81]
	v_mfma_f32_16x16x32_bf16 v[74:77], v[190:193], v[242:245], v[74:77]
	v_mfma_f32_16x16x32_bf16 v[118:121], v[194:197], v[210:213], v[118:121]
	v_mfma_f32_16x16x32_bf16 v[114:117], v[202:205], v[210:213], v[114:117]
	v_mfma_f32_16x16x32_bf16 v[102:105], v[194:197], v[218:221], v[102:105]
	v_mfma_f32_16x16x32_bf16 v[98:101], v[202:205], v[218:221], v[98:101]
	v_mfma_f32_16x16x32_bf16 v[86:89], v[194:197], v[226:229], v[86:89]
	v_mfma_f32_16x16x32_bf16 v[82:85], v[202:205], v[226:229], v[82:85]
	v_mfma_f32_16x16x32_bf16 v[70:73], v[194:197], v[238:241], v[70:73]
	v_mfma_f32_16x16x32_bf16 v[66:69], v[202:205], v[238:241], v[66:69]
	v_mfma_f32_16x16x32_bf16 v[118:121], v[198:201], v[214:217], v[118:121]
	v_mfma_f32_16x16x32_bf16 v[114:117], v[206:209], v[214:217], v[114:117]
	v_mfma_f32_16x16x32_bf16 v[102:105], v[198:201], v[222:225], v[102:105]
	v_mfma_f32_16x16x32_bf16 v[98:101], v[206:209], v[222:225], v[98:101]
	v_mfma_f32_16x16x32_bf16 v[86:89], v[198:201], v[234:237], v[86:89]
	v_mfma_f32_16x16x32_bf16 v[82:85], v[206:209], v[234:237], v[82:85]
	v_mfma_f32_16x16x32_bf16 v[70:73], v[198:201], v[242:245], v[70:73]
	v_mfma_f32_16x16x32_bf16 v[66:69], v[206:209], v[242:245], v[66:69]
	s_barrier
	s_add_i32 s48, s64, s78
	s_mov_b64 s[98:99], s[58:59]
	s_mov_b32 m0, s48
	ds_read_b128 v[210:213], v188 offset:16384
	ds_read_b128 v[214:217], v188 offset:17408
	ds_read_b128 v[218:221], v188 offset:18432
	ds_read_b128 v[222:225], v188 offset:19456
	ds_read_b128 v[226:229], v188 offset:20480
	ds_read_b128 v[234:237], v188 offset:21504
	ds_read_b128 v[238:241], v188 offset:22528
	ds_read_b128 v[242:245], v188 offset:23552
	global_load_lds_dwordx4 v136, s[58:59]
	s_add_i32 m0, s48, 0x2000
	s_add_u32 s48, s58, 0xb0000
	s_addc_u32 s49, s59, 0
	s_add_i32 s64, s65, s78
	global_load_lds_dwordx4 v140, s[58:59]
	s_mov_b32 m0, s64
	s_mov_b64 s[100:101], s[60:61]
	global_load_lds_dwordx4 v136, s[48:49]
	s_add_i32 m0, s64, 0x2000
	s_nop 0
	global_load_lds_dwordx4 v140, s[48:49]
	s_mov_b32 m0, s79
	s_nop 0
	global_load_lds_dwordx4 v134, s[60:61]
	s_mov_b32 m0, s80
	s_nop 0
	global_load_lds_dwordx4 v138, s[60:61]
	s_waitcnt vmcnt(8)
	s_waitcnt lgkmcnt(0)
	s_barrier
	v_mfma_f32_16x16x32_bf16 v[62:65], v[148:151], v[210:213], v[62:65]
	v_mfma_f32_16x16x32_bf16 v[58:61], v[156:159], v[210:213], v[58:61]
	v_mfma_f32_16x16x32_bf16 v[46:49], v[148:151], v[218:221], v[46:49]
	v_mfma_f32_16x16x32_bf16 v[42:45], v[156:159], v[218:221], v[42:45]
	v_mfma_f32_16x16x32_bf16 v[30:33], v[148:151], v[226:229], v[30:33]
	v_mfma_f32_16x16x32_bf16 v[26:29], v[156:159], v[226:229], v[26:29]
	v_mfma_f32_16x16x32_bf16 v[14:17], v[148:151], v[238:241], v[14:17]
	v_mfma_f32_16x16x32_bf16 v[10:13], v[156:159], v[238:241], v[10:13]
	v_mfma_f32_16x16x32_bf16 v[62:65], v[152:155], v[214:217], v[62:65]
	v_mfma_f32_16x16x32_bf16 v[58:61], v[190:193], v[214:217], v[58:61]
	v_mfma_f32_16x16x32_bf16 v[46:49], v[152:155], v[222:225], v[46:49]
	v_mfma_f32_16x16x32_bf16 v[42:45], v[190:193], v[222:225], v[42:45]
	v_mfma_f32_16x16x32_bf16 v[30:33], v[152:155], v[234:237], v[30:33]
	v_mfma_f32_16x16x32_bf16 v[26:29], v[190:193], v[234:237], v[26:29]
	v_mfma_f32_16x16x32_bf16 v[14:17], v[152:155], v[242:245], v[14:17]
	v_mfma_f32_16x16x32_bf16 v[10:13], v[190:193], v[242:245], v[10:13]
	v_mfma_f32_16x16x32_bf16 v[54:57], v[194:197], v[210:213], v[54:57]
	v_mfma_f32_16x16x32_bf16 v[50:53], v[202:205], v[210:213], v[50:53]
	v_mfma_f32_16x16x32_bf16 v[38:41], v[194:197], v[218:221], v[38:41]
	v_mfma_f32_16x16x32_bf16 v[34:37], v[202:205], v[218:221], v[34:37]
	v_mfma_f32_16x16x32_bf16 v[22:25], v[194:197], v[226:229], v[22:25]
	v_mfma_f32_16x16x32_bf16 v[18:21], v[202:205], v[226:229], v[18:21]
	v_mfma_f32_16x16x32_bf16 v[6:9], v[194:197], v[238:241], v[6:9]
	v_mfma_f32_16x16x32_bf16 v[2:5], v[202:205], v[238:241], v[2:5]
	v_mfma_f32_16x16x32_bf16 v[54:57], v[198:201], v[214:217], v[54:57]
	v_mfma_f32_16x16x32_bf16 v[50:53], v[206:209], v[214:217], v[50:53]
	v_mfma_f32_16x16x32_bf16 v[38:41], v[198:201], v[222:225], v[38:41]
	v_mfma_f32_16x16x32_bf16 v[34:37], v[206:209], v[222:225], v[34:37]
	v_mfma_f32_16x16x32_bf16 v[22:25], v[198:201], v[234:237], v[22:25]
	v_mfma_f32_16x16x32_bf16 v[18:21], v[206:209], v[234:237], v[18:21]
	v_mfma_f32_16x16x32_bf16 v[6:9], v[198:201], v[242:245], v[6:9]
	v_mfma_f32_16x16x32_bf16 v[2:5], v[206:209], v[242:245], v[2:5]
	s_barrier
	s_add_i32 s64, 0, 0x18000
	v_add_u32_e32 v0, s64, v169
	s_add_i32 s65, 0, 0x1c000
	ds_read_b128 v[148:151], v0
	ds_read_b128 v[152:155], v0 offset:1024
	ds_read_b128 v[156:159], v0 offset:2048
	ds_read_b128 v[190:193], v0 offset:3072
	v_add_u32_e32 v0, s65, v169
	ds_read_b128 v[194:197], v0
	ds_read_b128 v[198:201], v0 offset:1024
	ds_read_b128 v[202:205], v0 offset:2048
	ds_read_b128 v[206:209], v0 offset:3072
	s_add_u32 s48, s60, 0xb0000
	s_addc_u32 s49, s61, 0
	s_mov_b32 m0, s81
	ds_read_b128 v[210:213], v188 offset:32768
	ds_read_b128 v[214:217], v188 offset:33792
	ds_read_b128 v[218:221], v188 offset:34816
	ds_read_b128 v[222:225], v188 offset:35840
	ds_read_b128 v[226:229], v188 offset:36864
	ds_read_b128 v[234:237], v188 offset:37888
	ds_read_b128 v[238:241], v188 offset:38912
	ds_read_b128 v[242:245], v188 offset:39936
	global_load_lds_dwordx4 v134, s[48:49]
	s_mov_b32 m0, s82
	s_nop 0
	global_load_lds_dwordx4 v138, s[48:49]
	s_waitcnt vmcnt(8)
	s_waitcnt lgkmcnt(0)
	s_barrier
	v_mfma_f32_16x16x32_bf16 v[126:129], v[148:151], v[210:213], v[126:129]
	v_mfma_f32_16x16x32_bf16 v[122:125], v[156:159], v[210:213], v[122:125]
	v_mfma_f32_16x16x32_bf16 v[110:113], v[148:151], v[218:221], v[110:113]
	v_mfma_f32_16x16x32_bf16 v[106:109], v[156:159], v[218:221], v[106:109]
	v_mfma_f32_16x16x32_bf16 v[94:97], v[148:151], v[226:229], v[94:97]
	v_mfma_f32_16x16x32_bf16 v[90:93], v[156:159], v[226:229], v[90:93]
	v_mfma_f32_16x16x32_bf16 v[78:81], v[148:151], v[238:241], v[78:81]
	v_mfma_f32_16x16x32_bf16 v[74:77], v[156:159], v[238:241], v[74:77]
	v_mfma_f32_16x16x32_bf16 v[126:129], v[152:155], v[214:217], v[126:129]
	v_mfma_f32_16x16x32_bf16 v[122:125], v[190:193], v[214:217], v[122:125]
	v_mfma_f32_16x16x32_bf16 v[110:113], v[152:155], v[222:225], v[110:113]
	v_mfma_f32_16x16x32_bf16 v[106:109], v[190:193], v[222:225], v[106:109]
	v_mfma_f32_16x16x32_bf16 v[94:97], v[152:155], v[234:237], v[94:97]
	v_mfma_f32_16x16x32_bf16 v[90:93], v[190:193], v[234:237], v[90:93]
	v_mfma_f32_16x16x32_bf16 v[78:81], v[152:155], v[242:245], v[78:81]
	v_mfma_f32_16x16x32_bf16 v[74:77], v[190:193], v[242:245], v[74:77]
	v_mfma_f32_16x16x32_bf16 v[118:121], v[194:197], v[210:213], v[118:121]
	v_mfma_f32_16x16x32_bf16 v[114:117], v[202:205], v[210:213], v[114:117]
	v_mfma_f32_16x16x32_bf16 v[102:105], v[194:197], v[218:221], v[102:105]
	v_mfma_f32_16x16x32_bf16 v[98:101], v[202:205], v[218:221], v[98:101]
	v_mfma_f32_16x16x32_bf16 v[86:89], v[194:197], v[226:229], v[86:89]
	v_mfma_f32_16x16x32_bf16 v[82:85], v[202:205], v[226:229], v[82:85]
	v_mfma_f32_16x16x32_bf16 v[70:73], v[194:197], v[238:241], v[70:73]
	v_mfma_f32_16x16x32_bf16 v[66:69], v[202:205], v[238:241], v[66:69]
	v_mfma_f32_16x16x32_bf16 v[118:121], v[198:201], v[214:217], v[118:121]
	v_mfma_f32_16x16x32_bf16 v[114:117], v[206:209], v[214:217], v[114:117]
	v_mfma_f32_16x16x32_bf16 v[102:105], v[198:201], v[222:225], v[102:105]
	v_mfma_f32_16x16x32_bf16 v[98:101], v[206:209], v[222:225], v[98:101]
	v_mfma_f32_16x16x32_bf16 v[86:89], v[198:201], v[234:237], v[86:89]
	v_mfma_f32_16x16x32_bf16 v[82:85], v[206:209], v[234:237], v[82:85]
	v_mfma_f32_16x16x32_bf16 v[70:73], v[198:201], v[242:245], v[70:73]
	v_mfma_f32_16x16x32_bf16 v[66:69], v[206:209], v[242:245], v[66:69]
	s_barrier
	s_add_i32 s48, s64, s78
	s_add_u32 s98, s98, s18
	s_addc_u32 s99, s99, s19
	s_mov_b32 m0, s48
	ds_read_b128 v[210:213], v188 offset:49152
	ds_read_b128 v[214:217], v188 offset:50176
	ds_read_b128 v[218:221], v188 offset:51200
	ds_read_b128 v[222:225], v188 offset:52224
	ds_read_b128 v[226:229], v188 offset:53248
	ds_read_b128 v[234:237], v188 offset:54272
	ds_read_b128 v[238:241], v188 offset:55296
	ds_read_b128 v[242:245], v188 offset:56320
	global_load_lds_dwordx4 v136, s[98:99]
	s_add_i32 m0, s48, 0x2000
	s_add_u32 s48, s58, 0xb0080
	s_addc_u32 s49, s59, 0
	s_add_i32 s58, s65, s78
	global_load_lds_dwordx4 v140, s[98:99]
	s_mov_b32 m0, s58
	s_nop 0
	global_load_lds_dwordx4 v136, s[48:49]
	s_add_i32 m0, s58, 0x2000
	s_nop 0
	global_load_lds_dwordx4 v140, s[48:49]
	s_add_u32 s100, s100, s18
	s_addc_u32 s101, s101, s19
	s_mov_b32 m0, s85
	s_nop 0
	global_load_lds_dwordx4 v134, s[100:101]
	s_mov_b32 m0, s86
	s_nop 0
	global_load_lds_dwordx4 v138, s[100:101]
	s_waitcnt vmcnt(8)
	s_waitcnt lgkmcnt(0)
	s_barrier
	v_mfma_f32_16x16x32_bf16 v[62:65], v[148:151], v[210:213], v[62:65]
	v_mfma_f32_16x16x32_bf16 v[58:61], v[156:159], v[210:213], v[58:61]
	v_mfma_f32_16x16x32_bf16 v[46:49], v[148:151], v[218:221], v[46:49]
	v_mfma_f32_16x16x32_bf16 v[42:45], v[156:159], v[218:221], v[42:45]
	v_mfma_f32_16x16x32_bf16 v[30:33], v[148:151], v[226:229], v[30:33]
	v_mfma_f32_16x16x32_bf16 v[26:29], v[156:159], v[226:229], v[26:29]
	v_mfma_f32_16x16x32_bf16 v[14:17], v[148:151], v[238:241], v[14:17]
	v_mfma_f32_16x16x32_bf16 v[10:13], v[156:159], v[238:241], v[10:13]
	v_mfma_f32_16x16x32_bf16 v[62:65], v[152:155], v[214:217], v[62:65]
	v_mfma_f32_16x16x32_bf16 v[58:61], v[190:193], v[214:217], v[58:61]
	v_mfma_f32_16x16x32_bf16 v[46:49], v[152:155], v[222:225], v[46:49]
	v_mfma_f32_16x16x32_bf16 v[42:45], v[190:193], v[222:225], v[42:45]
	v_mfma_f32_16x16x32_bf16 v[30:33], v[152:155], v[234:237], v[30:33]
	v_mfma_f32_16x16x32_bf16 v[26:29], v[190:193], v[234:237], v[26:29]
	v_mfma_f32_16x16x32_bf16 v[14:17], v[152:155], v[242:245], v[14:17]
	v_mfma_f32_16x16x32_bf16 v[10:13], v[190:193], v[242:245], v[10:13]
	v_mfma_f32_16x16x32_bf16 v[54:57], v[194:197], v[210:213], v[54:57]
	v_mfma_f32_16x16x32_bf16 v[50:53], v[202:205], v[210:213], v[50:53]
	v_mfma_f32_16x16x32_bf16 v[38:41], v[194:197], v[218:221], v[38:41]
	v_mfma_f32_16x16x32_bf16 v[34:37], v[202:205], v[218:221], v[34:37]
	v_mfma_f32_16x16x32_bf16 v[22:25], v[194:197], v[226:229], v[22:25]
	v_mfma_f32_16x16x32_bf16 v[18:21], v[202:205], v[226:229], v[18:21]
	v_mfma_f32_16x16x32_bf16 v[6:9], v[194:197], v[238:241], v[6:9]
	v_mfma_f32_16x16x32_bf16 v[2:5], v[202:205], v[238:241], v[2:5]
	v_mfma_f32_16x16x32_bf16 v[54:57], v[198:201], v[214:217], v[54:57]
	v_mfma_f32_16x16x32_bf16 v[50:53], v[206:209], v[214:217], v[50:53]
	v_mfma_f32_16x16x32_bf16 v[38:41], v[198:201], v[222:225], v[38:41]
	v_mfma_f32_16x16x32_bf16 v[34:37], v[206:209], v[222:225], v[34:37]
	v_mfma_f32_16x16x32_bf16 v[22:25], v[198:201], v[234:237], v[22:25]
	v_mfma_f32_16x16x32_bf16 v[18:21], v[206:209], v[234:237], v[18:21]
	v_mfma_f32_16x16x32_bf16 v[6:9], v[198:201], v[242:245], v[6:9]
	v_mfma_f32_16x16x32_bf16 v[2:5], v[206:209], v[242:245], v[2:5]
	s_barrier
	s_add_i32 s63, s63, 2
	s_add_u32 s16, s16, 0x100
	s_addc_u32 s55, s55, 0
	s_cmp_gt_u32 s63, 41
	s_mov_b64 s[48:49], s[56:57]
	s_cbranch_scc0 .LBB0_1636
	s_and_b64 vcc, exec, s[42:43]
	s_cbranch_vccz .LBB0_1640
	s_barrier
	s_andn2_b64 vcc, exec, s[24:25]
	s_cbranch_vccz .LBB0_1641

.LBB0_2108:
	s_add_u32 s48, s8, 0xfffc0080
	s_addc_u32 s49, s9, -1
	s_add_i32 s85, 0, 0x10000
	s_cmp_eq_u32 s71, 12
	s_cselect_b32 s65, s7, s49
	s_cselect_b32 s64, s57, s48
	v_add_u32_e32 v128, s85, v173
	s_cselect_b32 s49, s59, s70
	s_cselect_b32 s48, s68, s69
	s_add_i32 s87, 0, 0x14000
	ds_read_b128 v[174:177], v128
	ds_read_b128 v[180:183], v128 offset:1024
	ds_read_b128 v[184:187], v128 offset:2048
	ds_read_b128 v[188:191], v128 offset:3072
	v_add_u32_e32 v128, s87, v173
	ds_read_b128 v[192:195], v128
	ds_read_b128 v[196:199], v128 offset:1024
	ds_read_b128 v[202:205], v128 offset:2048
	ds_read_b128 v[206:209], v128 offset:3072
	s_add_i32 m0, s67, 0xc000
	ds_read_b128 v[216:219], v200
	ds_read_b128 v[220:223], v200 offset:1024
	ds_read_b128 v[224:227], v200 offset:2048
	ds_read_b128 v[228:231], v200 offset:3072
	ds_read_b128 v[234:237], v200 offset:4096
	ds_read_b128 v[238:241], v200 offset:5120
	ds_read_b128 v[242:245], v200 offset:6144
	ds_read_b128 v[246:249], v200 offset:7168
	global_load_lds_dwordx4 v148, s[8:9]
	s_add_i32 m0, s67, 0xe000
	s_nop 0
	global_load_lds_dwordx4 v150, s[8:9]
	s_waitcnt vmcnt(8)
	s_waitcnt lgkmcnt(0)
	s_barrier
	v_mfma_f32_16x16x32_bf16 v[124:127], v[174:177], v[216:219], v[124:127]
	v_mfma_f32_16x16x32_bf16 v[120:123], v[184:187], v[216:219], v[120:123]
	v_mfma_f32_16x16x32_bf16 v[108:111], v[174:177], v[224:227], v[108:111]
	v_mfma_f32_16x16x32_bf16 v[104:107], v[184:187], v[224:227], v[104:107]
	v_mfma_f32_16x16x32_bf16 v[92:95], v[174:177], v[234:237], v[92:95]
	v_mfma_f32_16x16x32_bf16 v[88:91], v[184:187], v[234:237], v[88:91]
	v_mfma_f32_16x16x32_bf16 v[76:79], v[174:177], v[242:245], v[76:79]
	v_mfma_f32_16x16x32_bf16 v[72:75], v[184:187], v[242:245], v[72:75]
	v_mfma_f32_16x16x32_bf16 v[124:127], v[180:183], v[220:223], v[124:127]
	v_mfma_f32_16x16x32_bf16 v[120:123], v[188:191], v[220:223], v[120:123]
	v_mfma_f32_16x16x32_bf16 v[108:111], v[180:183], v[228:231], v[108:111]
	v_mfma_f32_16x16x32_bf16 v[104:107], v[188:191], v[228:231], v[104:107]
	v_mfma_f32_16x16x32_bf16 v[92:95], v[180:183], v[238:241], v[92:95]
	v_mfma_f32_16x16x32_bf16 v[88:91], v[188:191], v[238:241], v[88:91]
	v_mfma_f32_16x16x32_bf16 v[76:79], v[180:183], v[246:249], v[76:79]
	v_mfma_f32_16x16x32_bf16 v[72:75], v[188:191], v[246:249], v[72:75]
	v_mfma_f32_16x16x32_bf16 v[116:119], v[192:195], v[216:219], v[116:119]
	v_mfma_f32_16x16x32_bf16 v[112:115], v[202:205], v[216:219], v[112:115]
	v_mfma_f32_16x16x32_bf16 v[100:103], v[192:195], v[224:227], v[100:103]
	v_mfma_f32_16x16x32_bf16 v[96:99], v[202:205], v[224:227], v[96:99]
	v_mfma_f32_16x16x32_bf16 v[84:87], v[192:195], v[234:237], v[84:87]
	v_mfma_f32_16x16x32_bf16 v[80:83], v[202:205], v[234:237], v[80:83]
	v_mfma_f32_16x16x32_bf16 v[68:71], v[192:195], v[242:245], v[68:71]
	v_mfma_f32_16x16x32_bf16 v[64:67], v[202:205], v[242:245], v[64:67]
	v_mfma_f32_16x16x32_bf16 v[116:119], v[196:199], v[220:223], v[116:119]
	v_mfma_f32_16x16x32_bf16 v[112:115], v[206:209], v[220:223], v[112:115]
	v_mfma_f32_16x16x32_bf16 v[100:103], v[196:199], v[228:231], v[100:103]
	v_mfma_f32_16x16x32_bf16 v[96:99], v[206:209], v[228:231], v[96:99]
	v_mfma_f32_16x16x32_bf16 v[84:87], v[196:199], v[238:241], v[84:87]
	v_mfma_f32_16x16x32_bf16 v[80:83], v[206:209], v[238:241], v[80:83]
	v_mfma_f32_16x16x32_bf16 v[68:71], v[196:199], v[246:249], v[68:71]
	v_mfma_f32_16x16x32_bf16 v[64:67], v[206:209], v[246:249], v[64:67]
	s_barrier
	s_add_i32 s85, s85, s77
	s_mov_b64 s[98:99], s[48:49]
	s_mov_b32 m0, s85
	ds_read_b128 v[216:219], v200 offset:16384
	ds_read_b128 v[220:223], v200 offset:17408
	ds_read_b128 v[224:227], v200 offset:18432
	ds_read_b128 v[228:231], v200 offset:19456
	ds_read_b128 v[234:237], v200 offset:20480
	ds_read_b128 v[238:241], v200 offset:21504
	ds_read_b128 v[242:245], v200 offset:22528
	ds_read_b128 v[246:249], v200 offset:23552
	global_load_lds_dwordx4 v136, s[48:49]
	s_add_i32 m0, s85, 0x2000
	s_add_u32 s88, s48, 0x40000
	s_addc_u32 s89, s49, 0
	s_add_i32 s85, s87, s77
	global_load_lds_dwordx4 v140, s[48:49]
	s_mov_b32 m0, s85
	s_mov_b64 s[100:101], s[64:65]
	global_load_lds_dwordx4 v136, s[88:89]
	s_add_i32 m0, s85, 0x2000
	s_nop 0
	global_load_lds_dwordx4 v140, s[88:89]
	s_mov_b32 m0, s67
	s_nop 0
	global_load_lds_dwordx4 v134, s[64:65]
	s_mov_b32 m0, s78
	s_nop 0
	global_load_lds_dwordx4 v138, s[64:65]
	s_waitcnt vmcnt(8)
	s_waitcnt lgkmcnt(0)
	s_barrier
	v_mfma_f32_16x16x32_bf16 v[60:63], v[174:177], v[216:219], v[60:63]
	v_mfma_f32_16x16x32_bf16 v[56:59], v[184:187], v[216:219], v[56:59]
	v_mfma_f32_16x16x32_bf16 v[44:47], v[174:177], v[224:227], v[44:47]
	v_mfma_f32_16x16x32_bf16 v[40:43], v[184:187], v[224:227], v[40:43]
	v_mfma_f32_16x16x32_bf16 v[28:31], v[174:177], v[234:237], v[28:31]
	v_mfma_f32_16x16x32_bf16 v[24:27], v[184:187], v[234:237], v[24:27]
	v_mfma_f32_16x16x32_bf16 v[12:15], v[174:177], v[242:245], v[12:15]
	v_mfma_f32_16x16x32_bf16 v[8:11], v[184:187], v[242:245], v[8:11]
	v_mfma_f32_16x16x32_bf16 v[60:63], v[180:183], v[220:223], v[60:63]
	v_mfma_f32_16x16x32_bf16 v[56:59], v[188:191], v[220:223], v[56:59]
	v_mfma_f32_16x16x32_bf16 v[44:47], v[180:183], v[228:231], v[44:47]
	v_mfma_f32_16x16x32_bf16 v[40:43], v[188:191], v[228:231], v[40:43]
	v_mfma_f32_16x16x32_bf16 v[28:31], v[180:183], v[238:241], v[28:31]
	v_mfma_f32_16x16x32_bf16 v[24:27], v[188:191], v[238:241], v[24:27]
	v_mfma_f32_16x16x32_bf16 v[12:15], v[180:183], v[246:249], v[12:15]
	v_mfma_f32_16x16x32_bf16 v[8:11], v[188:191], v[246:249], v[8:11]
	v_mfma_f32_16x16x32_bf16 v[52:55], v[192:195], v[216:219], v[52:55]
	v_mfma_f32_16x16x32_bf16 v[48:51], v[202:205], v[216:219], v[48:51]
	v_mfma_f32_16x16x32_bf16 v[36:39], v[192:195], v[224:227], v[36:39]
	v_mfma_f32_16x16x32_bf16 v[32:35], v[202:205], v[224:227], v[32:35]
	v_mfma_f32_16x16x32_bf16 v[20:23], v[192:195], v[234:237], v[20:23]
	v_mfma_f32_16x16x32_bf16 v[16:19], v[202:205], v[234:237], v[16:19]
	v_mfma_f32_16x16x32_bf16 v[4:7], v[192:195], v[242:245], v[4:7]
	v_mfma_f32_16x16x32_bf16 v[0:3], v[202:205], v[242:245], v[0:3]
	v_mfma_f32_16x16x32_bf16 v[52:55], v[196:199], v[220:223], v[52:55]
	v_mfma_f32_16x16x32_bf16 v[48:51], v[206:209], v[220:223], v[48:51]
	v_mfma_f32_16x16x32_bf16 v[36:39], v[196:199], v[228:231], v[36:39]
	v_mfma_f32_16x16x32_bf16 v[32:35], v[206:209], v[228:231], v[32:35]
	v_mfma_f32_16x16x32_bf16 v[20:23], v[196:199], v[238:241], v[20:23]
	v_mfma_f32_16x16x32_bf16 v[16:19], v[206:209], v[238:241], v[16:19]
	v_mfma_f32_16x16x32_bf16 v[4:7], v[196:199], v[246:249], v[4:7]
	v_mfma_f32_16x16x32_bf16 v[0:3], v[206:209], v[246:249], v[0:3]
	s_barrier
	v_add_u32_e32 v128, s0, v173
	s_add_i32 s85, 0, 0x1c000
	ds_read_b128 v[174:177], v128
	ds_read_b128 v[180:183], v128 offset:1024
	ds_read_b128 v[184:187], v128 offset:2048
	ds_read_b128 v[188:191], v128 offset:3072
	v_add_u32_e32 v128, s85, v173
	ds_read_b128 v[192:195], v128
	ds_read_b128 v[196:199], v128 offset:1024
	ds_read_b128 v[202:205], v128 offset:2048
	ds_read_b128 v[206:209], v128 offset:3072
	s_add_u32 s64, s64, 0x40000
	s_addc_u32 s65, s65, 0
	s_mov_b32 m0, s79
	ds_read_b128 v[216:219], v200 offset:32768
	ds_read_b128 v[220:223], v200 offset:33792
	ds_read_b128 v[224:227], v200 offset:34816
	ds_read_b128 v[228:231], v200 offset:35840
	ds_read_b128 v[234:237], v200 offset:36864
	ds_read_b128 v[238:241], v200 offset:37888
	ds_read_b128 v[242:245], v200 offset:38912
	ds_read_b128 v[246:249], v200 offset:39936
	global_load_lds_dwordx4 v134, s[64:65]
	s_mov_b32 m0, s80
	s_nop 0
	global_load_lds_dwordx4 v138, s[64:65]
	s_waitcnt vmcnt(8)
	s_waitcnt lgkmcnt(0)
	s_barrier
	v_mfma_f32_16x16x32_bf16 v[124:127], v[174:177], v[216:219], v[124:127]
	v_mfma_f32_16x16x32_bf16 v[120:123], v[184:187], v[216:219], v[120:123]
	v_mfma_f32_16x16x32_bf16 v[108:111], v[174:177], v[224:227], v[108:111]
	v_mfma_f32_16x16x32_bf16 v[104:107], v[184:187], v[224:227], v[104:107]
	v_mfma_f32_16x16x32_bf16 v[92:95], v[174:177], v[234:237], v[92:95]
	v_mfma_f32_16x16x32_bf16 v[88:91], v[184:187], v[234:237], v[88:91]
	v_mfma_f32_16x16x32_bf16 v[76:79], v[174:177], v[242:245], v[76:79]
	v_mfma_f32_16x16x32_bf16 v[72:75], v[184:187], v[242:245], v[72:75]
	v_mfma_f32_16x16x32_bf16 v[124:127], v[180:183], v[220:223], v[124:127]
	v_mfma_f32_16x16x32_bf16 v[120:123], v[188:191], v[220:223], v[120:123]
	v_mfma_f32_16x16x32_bf16 v[108:111], v[180:183], v[228:231], v[108:111]
	v_mfma_f32_16x16x32_bf16 v[104:107], v[188:191], v[228:231], v[104:107]
	v_mfma_f32_16x16x32_bf16 v[92:95], v[180:183], v[238:241], v[92:95]
	v_mfma_f32_16x16x32_bf16 v[88:91], v[188:191], v[238:241], v[88:91]
	v_mfma_f32_16x16x32_bf16 v[76:79], v[180:183], v[246:249], v[76:79]
	v_mfma_f32_16x16x32_bf16 v[72:75], v[188:191], v[246:249], v[72:75]
	v_mfma_f32_16x16x32_bf16 v[116:119], v[192:195], v[216:219], v[116:119]
	v_mfma_f32_16x16x32_bf16 v[112:115], v[202:205], v[216:219], v[112:115]
	v_mfma_f32_16x16x32_bf16 v[100:103], v[192:195], v[224:227], v[100:103]
	v_mfma_f32_16x16x32_bf16 v[96:99], v[202:205], v[224:227], v[96:99]
	v_mfma_f32_16x16x32_bf16 v[84:87], v[192:195], v[234:237], v[84:87]
	v_mfma_f32_16x16x32_bf16 v[80:83], v[202:205], v[234:237], v[80:83]
	v_mfma_f32_16x16x32_bf16 v[68:71], v[192:195], v[242:245], v[68:71]
	v_mfma_f32_16x16x32_bf16 v[64:67], v[202:205], v[242:245], v[64:67]
	v_mfma_f32_16x16x32_bf16 v[116:119], v[196:199], v[220:223], v[116:119]
	v_mfma_f32_16x16x32_bf16 v[112:115], v[206:209], v[220:223], v[112:115]
	v_mfma_f32_16x16x32_bf16 v[100:103], v[196:199], v[228:231], v[100:103]
	v_mfma_f32_16x16x32_bf16 v[96:99], v[206:209], v[228:231], v[96:99]
	v_mfma_f32_16x16x32_bf16 v[84:87], v[196:199], v[238:241], v[84:87]
	v_mfma_f32_16x16x32_bf16 v[80:83], v[206:209], v[238:241], v[80:83]
	v_mfma_f32_16x16x32_bf16 v[68:71], v[196:199], v[246:249], v[68:71]
	v_mfma_f32_16x16x32_bf16 v[64:67], v[206:209], v[246:249], v[64:67]
	s_barrier
	s_add_i32 s64, s0, s77
	s_add_u32 s98, s98, s14
	s_addc_u32 s99, s99, s15
	s_mov_b32 m0, s64
	ds_read_b128 v[216:219], v200 offset:49152
	ds_read_b128 v[220:223], v200 offset:50176
	ds_read_b128 v[224:227], v200 offset:51200
	ds_read_b128 v[228:231], v200 offset:52224
	ds_read_b128 v[234:237], v200 offset:53248
	ds_read_b128 v[238:241], v200 offset:54272
	ds_read_b128 v[242:245], v200 offset:55296
	ds_read_b128 v[246:249], v200 offset:56320
	global_load_lds_dwordx4 v136, s[98:99]
	s_add_i32 m0, s64, 0x2000
	s_add_u32 s48, s48, 0x40080
	s_addc_u32 s49, s49, 0
	s_add_i32 s64, s85, s77
	global_load_lds_dwordx4 v140, s[98:99]
	s_mov_b32 m0, s64
	s_nop 0
	global_load_lds_dwordx4 v136, s[48:49]
	s_add_i32 m0, s64, 0x2000
	s_nop 0
	global_load_lds_dwordx4 v140, s[48:49]
	s_add_u32 s100, s100, s14
	s_addc_u32 s101, s101, s15
	s_mov_b32 m0, s81
	s_nop 0
	global_load_lds_dwordx4 v134, s[100:101]
	s_mov_b32 m0, s82
	s_nop 0
	global_load_lds_dwordx4 v138, s[100:101]
	s_waitcnt vmcnt(8)
	s_waitcnt lgkmcnt(0)
	s_barrier
	v_mfma_f32_16x16x32_bf16 v[60:63], v[174:177], v[216:219], v[60:63]
	v_mfma_f32_16x16x32_bf16 v[56:59], v[184:187], v[216:219], v[56:59]
	v_mfma_f32_16x16x32_bf16 v[44:47], v[174:177], v[224:227], v[44:47]
	v_mfma_f32_16x16x32_bf16 v[40:43], v[184:187], v[224:227], v[40:43]
	v_mfma_f32_16x16x32_bf16 v[28:31], v[174:177], v[234:237], v[28:31]
	v_mfma_f32_16x16x32_bf16 v[24:27], v[184:187], v[234:237], v[24:27]
	v_mfma_f32_16x16x32_bf16 v[12:15], v[174:177], v[242:245], v[12:15]
	v_mfma_f32_16x16x32_bf16 v[8:11], v[184:187], v[242:245], v[8:11]
	v_mfma_f32_16x16x32_bf16 v[60:63], v[180:183], v[220:223], v[60:63]
	v_mfma_f32_16x16x32_bf16 v[56:59], v[188:191], v[220:223], v[56:59]
	v_mfma_f32_16x16x32_bf16 v[44:47], v[180:183], v[228:231], v[44:47]
	v_mfma_f32_16x16x32_bf16 v[40:43], v[188:191], v[228:231], v[40:43]
	v_mfma_f32_16x16x32_bf16 v[28:31], v[180:183], v[238:241], v[28:31]
	v_mfma_f32_16x16x32_bf16 v[24:27], v[188:191], v[238:241], v[24:27]
	v_mfma_f32_16x16x32_bf16 v[12:15], v[180:183], v[246:249], v[12:15]
	v_mfma_f32_16x16x32_bf16 v[8:11], v[188:191], v[246:249], v[8:11]
	v_mfma_f32_16x16x32_bf16 v[52:55], v[192:195], v[216:219], v[52:55]
	v_mfma_f32_16x16x32_bf16 v[48:51], v[202:205], v[216:219], v[48:51]
	v_mfma_f32_16x16x32_bf16 v[36:39], v[192:195], v[224:227], v[36:39]
	v_mfma_f32_16x16x32_bf16 v[32:35], v[202:205], v[224:227], v[32:35]
	v_mfma_f32_16x16x32_bf16 v[20:23], v[192:195], v[234:237], v[20:23]
	v_mfma_f32_16x16x32_bf16 v[16:19], v[202:205], v[234:237], v[16:19]
	v_mfma_f32_16x16x32_bf16 v[4:7], v[192:195], v[242:245], v[4:7]
	v_mfma_f32_16x16x32_bf16 v[0:3], v[202:205], v[242:245], v[0:3]
	v_mfma_f32_16x16x32_bf16 v[52:55], v[196:199], v[220:223], v[52:55]
	v_mfma_f32_16x16x32_bf16 v[48:51], v[206:209], v[220:223], v[48:51]
	v_mfma_f32_16x16x32_bf16 v[36:39], v[196:199], v[228:231], v[36:39]
	v_mfma_f32_16x16x32_bf16 v[32:35], v[206:209], v[228:231], v[32:35]
	v_mfma_f32_16x16x32_bf16 v[20:23], v[196:199], v[238:241], v[20:23]
	v_mfma_f32_16x16x32_bf16 v[16:19], v[206:209], v[238:241], v[16:19]
	v_mfma_f32_16x16x32_bf16 v[4:7], v[196:199], v[246:249], v[4:7]
	v_mfma_f32_16x16x32_bf16 v[0:3], v[206:209], v[246:249], v[0:3]
	s_barrier
	s_add_i32 s71, s71, 2
	s_add_u32 s8, s8, 0x100
	s_addc_u32 s9, s9, 0
	s_add_u32 s69, s69, 0x100
	s_addc_u32 s70, s70, 0
	s_cmp_gt_u32 s71, 13
	s_cbranch_scc0 .LBB0_2108
	s_and_b64 vcc, exec, s[54:55]
	s_cbranch_vccz .LBB0_2111
	s_barrier

.LBB0_2189:
	s_add_u32 s68, s48, 0xfffe0080
	s_addc_u32 s69, s49, -1
	s_add_i32 s78, 0, 0x10000
	s_cmp_eq_u32 vcc_lo, 4
	s_cselect_b32 s73, s1, s69
	s_cselect_b32 s72, s7, s68
	s_cselect_b32 s69, s61, s75
	s_cselect_b32 s68, s63, s74
	s_add_i32 vcc_hi, 0, 0x14000
	v_add_u32_e32 v140, s78, v225
	v_add_u32_e32 v144, vcc_hi, v225
	ds_read_b128 v[128:131], v140
	ds_read_b128 v[132:135], v140 offset:1024
	ds_read_b128 v[136:139], v140 offset:2048
	ds_read_b128 v[140:143], v140 offset:3072
	ds_read_b128 v[172:175], v144
	ds_read_b128 v[176:179], v144 offset:1024
	ds_read_b128 v[180:183], v144 offset:2048
	ds_read_b128 v[184:187], v144 offset:3072
	s_add_i32 m0, s18, 0xc000
	ds_read_b128 v[188:191], v228
	ds_read_b128 v[192:195], v228 offset:1024
	ds_read_b128 v[196:199], v228 offset:2048
	ds_read_b128 v[200:203], v228 offset:3072
	ds_read_b128 v[204:207], v228 offset:4096
	ds_read_b128 v[208:211], v228 offset:5120
	ds_read_b128 v[234:237], v228 offset:6144
	ds_read_b128 v[238:241], v228 offset:7168
	global_load_lds_dwordx4 v166, s[48:49]
	s_add_i32 m0, s18, 0xe000
	s_nop 0
	global_load_lds_dwordx4 v168, s[48:49]
	s_waitcnt vmcnt(8)
	s_waitcnt lgkmcnt(0)
	s_barrier
	v_mfma_i32_16x16x64_i8 v[124:127], v[128:131], v[188:191], v[124:127]
	v_mfma_i32_16x16x64_i8 v[120:123], v[136:139], v[188:191], v[120:123]
	v_mfma_i32_16x16x64_i8 v[116:119], v[128:131], v[196:199], v[116:119]
	v_mfma_i32_16x16x64_i8 v[112:115], v[136:139], v[196:199], v[112:115]
	v_mfma_i32_16x16x64_i8 v[108:111], v[128:131], v[204:207], v[108:111]
	v_mfma_i32_16x16x64_i8 v[104:107], v[136:139], v[204:207], v[104:107]
	v_mfma_i32_16x16x64_i8 v[100:103], v[128:131], v[234:237], v[100:103]
	v_mfma_i32_16x16x64_i8 v[96:99], v[136:139], v[234:237], v[96:99]
	v_mfma_i32_16x16x64_i8 v[124:127], v[132:135], v[192:195], v[124:127]
	v_mfma_i32_16x16x64_i8 v[120:123], v[140:143], v[192:195], v[120:123]
	v_mfma_i32_16x16x64_i8 v[116:119], v[132:135], v[200:203], v[116:119]
	v_mfma_i32_16x16x64_i8 v[112:115], v[140:143], v[200:203], v[112:115]
	v_mfma_i32_16x16x64_i8 v[108:111], v[132:135], v[208:211], v[108:111]
	v_mfma_i32_16x16x64_i8 v[104:107], v[140:143], v[208:211], v[104:107]
	v_mfma_i32_16x16x64_i8 v[100:103], v[132:135], v[238:241], v[100:103]
	v_mfma_i32_16x16x64_i8 v[96:99], v[140:143], v[238:241], v[96:99]
	v_mfma_i32_16x16x64_i8 v[92:95], v[172:175], v[188:191], v[92:95]
	v_mfma_i32_16x16x64_i8 v[88:91], v[180:183], v[188:191], v[88:91]
	v_mfma_i32_16x16x64_i8 v[84:87], v[172:175], v[196:199], v[84:87]
	v_mfma_i32_16x16x64_i8 v[80:83], v[180:183], v[196:199], v[80:83]
	v_mfma_i32_16x16x64_i8 v[76:79], v[172:175], v[204:207], v[76:79]
	v_mfma_i32_16x16x64_i8 v[72:75], v[180:183], v[204:207], v[72:75]
	v_mfma_i32_16x16x64_i8 v[68:71], v[172:175], v[234:237], v[68:71]
	v_mfma_i32_16x16x64_i8 v[64:67], v[180:183], v[234:237], v[64:67]
	v_mfma_i32_16x16x64_i8 v[92:95], v[176:179], v[192:195], v[92:95]
	v_mfma_i32_16x16x64_i8 v[88:91], v[184:187], v[192:195], v[88:91]
	v_mfma_i32_16x16x64_i8 v[84:87], v[176:179], v[200:203], v[84:87]
	v_mfma_i32_16x16x64_i8 v[80:83], v[184:187], v[200:203], v[80:83]
	v_mfma_i32_16x16x64_i8 v[76:79], v[176:179], v[208:211], v[76:79]
	v_mfma_i32_16x16x64_i8 v[72:75], v[184:187], v[208:211], v[72:75]
	v_mfma_i32_16x16x64_i8 v[68:71], v[176:179], v[238:241], v[68:71]
	v_mfma_i32_16x16x64_i8 v[64:67], v[184:187], v[238:241], v[64:67]
	s_barrier
	s_add_i32 s78, s78, s11
	s_mov_b64 s[98:99], s[68:69]
	s_mov_b32 m0, s78
	ds_read_b128 v[188:191], v228 offset:16384
	ds_read_b128 v[192:195], v228 offset:17408
	ds_read_b128 v[196:199], v228 offset:18432
	ds_read_b128 v[200:203], v228 offset:19456
	ds_read_b128 v[204:207], v228 offset:20480
	ds_read_b128 v[208:211], v228 offset:21504
	ds_read_b128 v[234:237], v228 offset:22528
	ds_read_b128 v[238:241], v228 offset:23552
	global_load_lds_dwordx4 v152, s[68:69]
	s_add_i32 m0, s78, 0x2000
	s_add_u32 s78, s68, 0x20000
	s_addc_u32 s79, s69, 0
	s_add_i32 vcc_hi, vcc_hi, s11
	global_load_lds_dwordx4 v156, s[68:69]
	s_mov_b32 m0, vcc_hi
	s_mov_b64 s[100:101], s[72:73]
	global_load_lds_dwordx4 v152, s[78:79]
	s_add_i32 m0, vcc_hi, 0x2000
	s_nop 0
	global_load_lds_dwordx4 v156, s[78:79]
	s_mov_b32 m0, s18
	s_nop 0
	global_load_lds_dwordx4 v150, s[72:73]
	s_mov_b32 m0, s19
	s_nop 0
	global_load_lds_dwordx4 v154, s[72:73]
	s_waitcnt vmcnt(8)
	s_waitcnt lgkmcnt(0)
	s_barrier
	v_mfma_i32_16x16x64_i8 v[60:63], v[128:131], v[188:191], v[60:63]
	v_mfma_i32_16x16x64_i8 v[56:59], v[136:139], v[188:191], v[56:59]
	v_mfma_i32_16x16x64_i8 v[52:55], v[128:131], v[196:199], v[52:55]
	v_mfma_i32_16x16x64_i8 v[48:51], v[136:139], v[196:199], v[48:51]
	v_mfma_i32_16x16x64_i8 v[44:47], v[128:131], v[204:207], v[44:47]
	v_mfma_i32_16x16x64_i8 v[40:43], v[136:139], v[204:207], v[40:43]
	v_mfma_i32_16x16x64_i8 v[36:39], v[128:131], v[234:237], v[36:39]
	v_mfma_i32_16x16x64_i8 v[32:35], v[136:139], v[234:237], v[32:35]
	v_mfma_i32_16x16x64_i8 v[60:63], v[132:135], v[192:195], v[60:63]
	v_mfma_i32_16x16x64_i8 v[56:59], v[140:143], v[192:195], v[56:59]
	v_mfma_i32_16x16x64_i8 v[52:55], v[132:135], v[200:203], v[52:55]
	v_mfma_i32_16x16x64_i8 v[48:51], v[140:143], v[200:203], v[48:51]
	v_mfma_i32_16x16x64_i8 v[44:47], v[132:135], v[208:211], v[44:47]
	v_mfma_i32_16x16x64_i8 v[40:43], v[140:143], v[208:211], v[40:43]
	v_mfma_i32_16x16x64_i8 v[36:39], v[132:135], v[238:241], v[36:39]
	v_mfma_i32_16x16x64_i8 v[32:35], v[140:143], v[238:241], v[32:35]
	v_mfma_i32_16x16x64_i8 v[28:31], v[172:175], v[188:191], v[28:31]
	v_mfma_i32_16x16x64_i8 v[24:27], v[180:183], v[188:191], v[24:27]
	v_mfma_i32_16x16x64_i8 v[20:23], v[172:175], v[196:199], v[20:23]
	v_mfma_i32_16x16x64_i8 v[16:19], v[180:183], v[196:199], v[16:19]
	v_mfma_i32_16x16x64_i8 v[12:15], v[172:175], v[204:207], v[12:15]
	v_mfma_i32_16x16x64_i8 v[8:11], v[180:183], v[204:207], v[8:11]
	v_mfma_i32_16x16x64_i8 v[4:7], v[172:175], v[234:237], v[4:7]
	v_mfma_i32_16x16x64_i8 v[0:3], v[180:183], v[234:237], v[0:3]
	v_mfma_i32_16x16x64_i8 v[28:31], v[176:179], v[192:195], v[28:31]
	v_mfma_i32_16x16x64_i8 v[24:27], v[184:187], v[192:195], v[24:27]
	v_mfma_i32_16x16x64_i8 v[20:23], v[176:179], v[200:203], v[20:23]
	v_mfma_i32_16x16x64_i8 v[16:19], v[184:187], v[200:203], v[16:19]
	v_mfma_i32_16x16x64_i8 v[12:15], v[176:179], v[208:211], v[12:15]
	v_mfma_i32_16x16x64_i8 v[8:11], v[184:187], v[208:211], v[8:11]
	v_mfma_i32_16x16x64_i8 v[4:7], v[176:179], v[238:241], v[4:7]
	v_mfma_i32_16x16x64_i8 v[0:3], v[184:187], v[238:241], v[0:3]
	s_barrier
	s_add_i32 s78, 0, 0x1c000
	v_add_u32_e32 v140, s0, v225
	v_add_u32_e32 v144, s78, v225
	ds_read_b128 v[128:131], v140
	ds_read_b128 v[132:135], v140 offset:1024
	ds_read_b128 v[136:139], v140 offset:2048
	ds_read_b128 v[140:143], v140 offset:3072
	ds_read_b128 v[172:175], v144
	ds_read_b128 v[176:179], v144 offset:1024
	ds_read_b128 v[180:183], v144 offset:2048
	ds_read_b128 v[184:187], v144 offset:3072
	s_add_u32 s72, s72, 0x20000
	s_addc_u32 s73, s73, 0
	s_mov_b32 m0, s20
	ds_read_b128 v[188:191], v228 offset:32768
	ds_read_b128 v[192:195], v228 offset:33792
	ds_read_b128 v[196:199], v228 offset:34816
	ds_read_b128 v[200:203], v228 offset:35840
	ds_read_b128 v[204:207], v228 offset:36864
	ds_read_b128 v[208:211], v228 offset:37888
	ds_read_b128 v[234:237], v228 offset:38912
	ds_read_b128 v[238:241], v228 offset:39936
	global_load_lds_dwordx4 v150, s[72:73]
	s_mov_b32 m0, s21
	s_nop 0
	global_load_lds_dwordx4 v154, s[72:73]
	s_waitcnt vmcnt(8)
	s_waitcnt lgkmcnt(0)
	s_barrier
	v_mfma_i32_16x16x64_i8 v[124:127], v[128:131], v[188:191], v[124:127]
	v_mfma_i32_16x16x64_i8 v[120:123], v[136:139], v[188:191], v[120:123]
	v_mfma_i32_16x16x64_i8 v[116:119], v[128:131], v[196:199], v[116:119]
	v_mfma_i32_16x16x64_i8 v[112:115], v[136:139], v[196:199], v[112:115]
	v_mfma_i32_16x16x64_i8 v[108:111], v[128:131], v[204:207], v[108:111]
	v_mfma_i32_16x16x64_i8 v[104:107], v[136:139], v[204:207], v[104:107]
	v_mfma_i32_16x16x64_i8 v[100:103], v[128:131], v[234:237], v[100:103]
	v_mfma_i32_16x16x64_i8 v[96:99], v[136:139], v[234:237], v[96:99]
	v_mfma_i32_16x16x64_i8 v[124:127], v[132:135], v[192:195], v[124:127]
	v_mfma_i32_16x16x64_i8 v[120:123], v[140:143], v[192:195], v[120:123]
	v_mfma_i32_16x16x64_i8 v[116:119], v[132:135], v[200:203], v[116:119]
	v_mfma_i32_16x16x64_i8 v[112:115], v[140:143], v[200:203], v[112:115]
	v_mfma_i32_16x16x64_i8 v[108:111], v[132:135], v[208:211], v[108:111]
	v_mfma_i32_16x16x64_i8 v[104:107], v[140:143], v[208:211], v[104:107]
	v_mfma_i32_16x16x64_i8 v[100:103], v[132:135], v[238:241], v[100:103]
	v_mfma_i32_16x16x64_i8 v[96:99], v[140:143], v[238:241], v[96:99]
	v_mfma_i32_16x16x64_i8 v[92:95], v[172:175], v[188:191], v[92:95]
	v_mfma_i32_16x16x64_i8 v[88:91], v[180:183], v[188:191], v[88:91]
	v_mfma_i32_16x16x64_i8 v[84:87], v[172:175], v[196:199], v[84:87]
	v_mfma_i32_16x16x64_i8 v[80:83], v[180:183], v[196:199], v[80:83]
	v_mfma_i32_16x16x64_i8 v[76:79], v[172:175], v[204:207], v[76:79]
	v_mfma_i32_16x16x64_i8 v[72:75], v[180:183], v[204:207], v[72:75]
	v_mfma_i32_16x16x64_i8 v[68:71], v[172:175], v[234:237], v[68:71]
	v_mfma_i32_16x16x64_i8 v[64:67], v[180:183], v[234:237], v[64:67]
	v_mfma_i32_16x16x64_i8 v[92:95], v[176:179], v[192:195], v[92:95]
	v_mfma_i32_16x16x64_i8 v[88:91], v[184:187], v[192:195], v[88:91]
	v_mfma_i32_16x16x64_i8 v[84:87], v[176:179], v[200:203], v[84:87]
	v_mfma_i32_16x16x64_i8 v[80:83], v[184:187], v[200:203], v[80:83]
	v_mfma_i32_16x16x64_i8 v[76:79], v[176:179], v[208:211], v[76:79]
	v_mfma_i32_16x16x64_i8 v[72:75], v[184:187], v[208:211], v[72:75]
	v_mfma_i32_16x16x64_i8 v[68:71], v[176:179], v[238:241], v[68:71]
	v_mfma_i32_16x16x64_i8 v[64:67], v[184:187], v[238:241], v[64:67]
	s_barrier
	s_add_i32 s72, s0, s11
	s_add_u32 s98, s98, s24
	s_addc_u32 s99, s99, s25
	s_mov_b32 m0, s72
	ds_read_b128 v[188:191], v228 offset:49152
	ds_read_b128 v[192:195], v228 offset:50176
	ds_read_b128 v[196:199], v228 offset:51200
	ds_read_b128 v[200:203], v228 offset:52224
	ds_read_b128 v[204:207], v228 offset:53248
	ds_read_b128 v[208:211], v228 offset:54272
	ds_read_b128 v[234:237], v228 offset:55296
	ds_read_b128 v[238:241], v228 offset:56320
	global_load_lds_dwordx4 v152, s[98:99]
	s_add_i32 m0, s72, 0x2000
	s_add_u32 s68, s68, 0x20080
	s_addc_u32 s69, s69, 0
	s_add_i32 s72, s78, s11
	global_load_lds_dwordx4 v156, s[98:99]
	s_mov_b32 m0, s72
	s_nop 0
	global_load_lds_dwordx4 v152, s[68:69]
	s_add_i32 m0, s72, 0x2000
	s_nop 0
	global_load_lds_dwordx4 v156, s[68:69]
	s_add_u32 s100, s100, s24
	s_addc_u32 s101, s101, s25
	s_mov_b32 m0, s77
	s_nop 0
	global_load_lds_dwordx4 v150, s[100:101]
	s_mov_b32 m0, s84
	s_nop 0
	global_load_lds_dwordx4 v154, s[100:101]
	s_waitcnt vmcnt(8)
	s_waitcnt lgkmcnt(0)
	s_barrier
	v_mfma_i32_16x16x64_i8 v[60:63], v[128:131], v[188:191], v[60:63]
	v_mfma_i32_16x16x64_i8 v[56:59], v[136:139], v[188:191], v[56:59]
	v_mfma_i32_16x16x64_i8 v[52:55], v[128:131], v[196:199], v[52:55]
	v_mfma_i32_16x16x64_i8 v[48:51], v[136:139], v[196:199], v[48:51]
	v_mfma_i32_16x16x64_i8 v[44:47], v[128:131], v[204:207], v[44:47]
	v_mfma_i32_16x16x64_i8 v[40:43], v[136:139], v[204:207], v[40:43]
	v_mfma_i32_16x16x64_i8 v[36:39], v[128:131], v[234:237], v[36:39]
	v_mfma_i32_16x16x64_i8 v[32:35], v[136:139], v[234:237], v[32:35]
	v_mfma_i32_16x16x64_i8 v[60:63], v[132:135], v[192:195], v[60:63]
	v_mfma_i32_16x16x64_i8 v[56:59], v[140:143], v[192:195], v[56:59]
	v_mfma_i32_16x16x64_i8 v[52:55], v[132:135], v[200:203], v[52:55]
	v_mfma_i32_16x16x64_i8 v[48:51], v[140:143], v[200:203], v[48:51]
	v_mfma_i32_16x16x64_i8 v[44:47], v[132:135], v[208:211], v[44:47]
	v_mfma_i32_16x16x64_i8 v[40:43], v[140:143], v[208:211], v[40:43]
	v_mfma_i32_16x16x64_i8 v[36:39], v[132:135], v[238:241], v[36:39]
	v_mfma_i32_16x16x64_i8 v[32:35], v[140:143], v[238:241], v[32:35]
	v_mfma_i32_16x16x64_i8 v[28:31], v[172:175], v[188:191], v[28:31]
	v_mfma_i32_16x16x64_i8 v[24:27], v[180:183], v[188:191], v[24:27]
	v_mfma_i32_16x16x64_i8 v[20:23], v[172:175], v[196:199], v[20:23]
	v_mfma_i32_16x16x64_i8 v[16:19], v[180:183], v[196:199], v[16:19]
	v_mfma_i32_16x16x64_i8 v[12:15], v[172:175], v[204:207], v[12:15]
	v_mfma_i32_16x16x64_i8 v[8:11], v[180:183], v[204:207], v[8:11]
	v_mfma_i32_16x16x64_i8 v[4:7], v[172:175], v[234:237], v[4:7]
	v_mfma_i32_16x16x64_i8 v[0:3], v[180:183], v[234:237], v[0:3]
	v_mfma_i32_16x16x64_i8 v[28:31], v[176:179], v[192:195], v[28:31]
	v_mfma_i32_16x16x64_i8 v[24:27], v[184:187], v[192:195], v[24:27]
	v_mfma_i32_16x16x64_i8 v[20:23], v[176:179], v[200:203], v[20:23]
	v_mfma_i32_16x16x64_i8 v[16:19], v[184:187], v[200:203], v[16:19]
	v_mfma_i32_16x16x64_i8 v[12:15], v[176:179], v[208:211], v[12:15]
	v_mfma_i32_16x16x64_i8 v[8:11], v[184:187], v[208:211], v[8:11]
	v_mfma_i32_16x16x64_i8 v[4:7], v[176:179], v[238:241], v[4:7]
	v_mfma_i32_16x16x64_i8 v[0:3], v[184:187], v[238:241], v[0:3]
	s_barrier
	s_add_i32 vcc_lo, vcc_lo, 2
	s_add_u32 s48, s48, 0x100
	s_addc_u32 s49, s49, 0
	s_add_u32 s74, s74, 0x100
	s_addc_u32 s75, s75, 0
	s_cmp_gt_u32 vcc_lo, 5
	s_cbranch_scc0 .LBB0_2189
	s_and_b64 vcc, exec, s[58:59]
	s_cbranch_vccz .LBB0_2192
	s_barrier

.LBB0_2520:
	s_add_u32 s48, s8, 0xfffc0080
	s_addc_u32 s49, s9, -1
	s_add_i32 s84, 0, 0x10000
	s_cmp_eq_u32 s67, 12
	s_cselect_b32 s61, s7, s49
	s_cselect_b32 s60, s55, s48
	v_add_u32_e32 v128, s84, v173
	s_cselect_b32 s49, s53, s66
	s_cselect_b32 s48, s64, s65
	s_add_i32 s88, 0, 0x14000
	ds_read_b128 v[174:177], v128
	ds_read_b128 v[180:183], v128 offset:1024
	ds_read_b128 v[184:187], v128 offset:2048
	ds_read_b128 v[188:191], v128 offset:3072
	v_add_u32_e32 v128, s88, v173
	ds_read_b128 v[192:195], v128
	ds_read_b128 v[196:199], v128 offset:1024
	ds_read_b128 v[204:207], v128 offset:2048
	ds_read_b128 v[208:211], v128 offset:3072
	s_add_i32 m0, s63, 0xc000
	ds_read_b128 v[212:215], v203
	ds_read_b128 v[216:219], v203 offset:1024
	ds_read_b128 v[220:223], v203 offset:2048
	ds_read_b128 v[224:227], v203 offset:3072
	ds_read_b128 v[228:231], v203 offset:4096
	ds_read_b128 v[234:237], v203 offset:5120
	ds_read_b128 v[238:241], v203 offset:6144
	ds_read_b128 v[242:245], v203 offset:7168
	global_load_lds_dwordx4 v148, s[8:9]
	s_add_i32 m0, s63, 0xe000
	s_nop 0
	global_load_lds_dwordx4 v150, s[8:9]
	s_waitcnt vmcnt(8)
	s_waitcnt lgkmcnt(0)
	s_barrier
	v_mfma_f32_16x16x32_bf16 v[124:127], v[174:177], v[212:215], v[124:127]
	v_mfma_f32_16x16x32_bf16 v[120:123], v[184:187], v[212:215], v[120:123]
	v_mfma_f32_16x16x32_bf16 v[108:111], v[174:177], v[220:223], v[108:111]
	v_mfma_f32_16x16x32_bf16 v[104:107], v[184:187], v[220:223], v[104:107]
	v_mfma_f32_16x16x32_bf16 v[92:95], v[174:177], v[228:231], v[92:95]
	v_mfma_f32_16x16x32_bf16 v[88:91], v[184:187], v[228:231], v[88:91]
	v_mfma_f32_16x16x32_bf16 v[76:79], v[174:177], v[238:241], v[76:79]
	v_mfma_f32_16x16x32_bf16 v[72:75], v[184:187], v[238:241], v[72:75]
	v_mfma_f32_16x16x32_bf16 v[124:127], v[180:183], v[216:219], v[124:127]
	v_mfma_f32_16x16x32_bf16 v[120:123], v[188:191], v[216:219], v[120:123]
	v_mfma_f32_16x16x32_bf16 v[108:111], v[180:183], v[224:227], v[108:111]
	v_mfma_f32_16x16x32_bf16 v[104:107], v[188:191], v[224:227], v[104:107]
	v_mfma_f32_16x16x32_bf16 v[92:95], v[180:183], v[234:237], v[92:95]
	v_mfma_f32_16x16x32_bf16 v[88:91], v[188:191], v[234:237], v[88:91]
	v_mfma_f32_16x16x32_bf16 v[76:79], v[180:183], v[242:245], v[76:79]
	v_mfma_f32_16x16x32_bf16 v[72:75], v[188:191], v[242:245], v[72:75]
	v_mfma_f32_16x16x32_bf16 v[116:119], v[192:195], v[212:215], v[116:119]
	v_mfma_f32_16x16x32_bf16 v[112:115], v[204:207], v[212:215], v[112:115]
	v_mfma_f32_16x16x32_bf16 v[100:103], v[192:195], v[220:223], v[100:103]
	v_mfma_f32_16x16x32_bf16 v[96:99], v[204:207], v[220:223], v[96:99]
	v_mfma_f32_16x16x32_bf16 v[84:87], v[192:195], v[228:231], v[84:87]
	v_mfma_f32_16x16x32_bf16 v[80:83], v[204:207], v[228:231], v[80:83]
	v_mfma_f32_16x16x32_bf16 v[68:71], v[192:195], v[238:241], v[68:71]
	v_mfma_f32_16x16x32_bf16 v[64:67], v[204:207], v[238:241], v[64:67]
	v_mfma_f32_16x16x32_bf16 v[116:119], v[196:199], v[216:219], v[116:119]
	v_mfma_f32_16x16x32_bf16 v[112:115], v[208:211], v[216:219], v[112:115]
	v_mfma_f32_16x16x32_bf16 v[100:103], v[196:199], v[224:227], v[100:103]
	v_mfma_f32_16x16x32_bf16 v[96:99], v[208:211], v[224:227], v[96:99]
	v_mfma_f32_16x16x32_bf16 v[84:87], v[196:199], v[234:237], v[84:87]
	v_mfma_f32_16x16x32_bf16 v[80:83], v[208:211], v[234:237], v[80:83]
	v_mfma_f32_16x16x32_bf16 v[68:71], v[196:199], v[242:245], v[68:71]
	v_mfma_f32_16x16x32_bf16 v[64:67], v[208:211], v[242:245], v[64:67]
	s_barrier
	s_add_i32 s84, s84, s75
	s_mov_b64 s[98:99], s[48:49]
	s_mov_b32 m0, s84
	ds_read_b128 v[212:215], v203 offset:16384
	ds_read_b128 v[216:219], v203 offset:17408
	ds_read_b128 v[220:223], v203 offset:18432
	ds_read_b128 v[224:227], v203 offset:19456
	ds_read_b128 v[228:231], v203 offset:20480
	ds_read_b128 v[234:237], v203 offset:21504
	ds_read_b128 v[238:241], v203 offset:22528
	ds_read_b128 v[242:245], v203 offset:23552
	global_load_lds_dwordx4 v136, s[48:49]
	s_add_i32 m0, s84, 0x2000
	s_add_u32 s86, s48, 0x40000
	s_addc_u32 s87, s49, 0
	s_add_i32 s84, s88, s75
	global_load_lds_dwordx4 v140, s[48:49]
	s_mov_b32 m0, s84
	s_mov_b64 s[100:101], s[60:61]
	global_load_lds_dwordx4 v136, s[86:87]
	s_add_i32 m0, s84, 0x2000
	s_nop 0
	global_load_lds_dwordx4 v140, s[86:87]
	s_mov_b32 m0, s63
	s_nop 0
	global_load_lds_dwordx4 v134, s[60:61]
	s_mov_b32 m0, s76
	s_nop 0
	global_load_lds_dwordx4 v138, s[60:61]
	s_waitcnt vmcnt(8)
	s_waitcnt lgkmcnt(0)
	s_barrier
	v_mfma_f32_16x16x32_bf16 v[60:63], v[174:177], v[212:215], v[60:63]
	v_mfma_f32_16x16x32_bf16 v[56:59], v[184:187], v[212:215], v[56:59]
	v_mfma_f32_16x16x32_bf16 v[44:47], v[174:177], v[220:223], v[44:47]
	v_mfma_f32_16x16x32_bf16 v[40:43], v[184:187], v[220:223], v[40:43]
	v_mfma_f32_16x16x32_bf16 v[28:31], v[174:177], v[228:231], v[28:31]
	v_mfma_f32_16x16x32_bf16 v[24:27], v[184:187], v[228:231], v[24:27]
	v_mfma_f32_16x16x32_bf16 v[12:15], v[174:177], v[238:241], v[12:15]
	v_mfma_f32_16x16x32_bf16 v[8:11], v[184:187], v[238:241], v[8:11]
	v_mfma_f32_16x16x32_bf16 v[60:63], v[180:183], v[216:219], v[60:63]
	v_mfma_f32_16x16x32_bf16 v[56:59], v[188:191], v[216:219], v[56:59]
	v_mfma_f32_16x16x32_bf16 v[44:47], v[180:183], v[224:227], v[44:47]
	v_mfma_f32_16x16x32_bf16 v[40:43], v[188:191], v[224:227], v[40:43]
	v_mfma_f32_16x16x32_bf16 v[28:31], v[180:183], v[234:237], v[28:31]
	v_mfma_f32_16x16x32_bf16 v[24:27], v[188:191], v[234:237], v[24:27]
	v_mfma_f32_16x16x32_bf16 v[12:15], v[180:183], v[242:245], v[12:15]
	v_mfma_f32_16x16x32_bf16 v[8:11], v[188:191], v[242:245], v[8:11]
	v_mfma_f32_16x16x32_bf16 v[52:55], v[192:195], v[212:215], v[52:55]
	v_mfma_f32_16x16x32_bf16 v[48:51], v[204:207], v[212:215], v[48:51]
	v_mfma_f32_16x16x32_bf16 v[36:39], v[192:195], v[220:223], v[36:39]
	v_mfma_f32_16x16x32_bf16 v[32:35], v[204:207], v[220:223], v[32:35]
	v_mfma_f32_16x16x32_bf16 v[20:23], v[192:195], v[228:231], v[20:23]
	v_mfma_f32_16x16x32_bf16 v[16:19], v[204:207], v[228:231], v[16:19]
	v_mfma_f32_16x16x32_bf16 v[4:7], v[192:195], v[238:241], v[4:7]
	v_mfma_f32_16x16x32_bf16 v[0:3], v[204:207], v[238:241], v[0:3]
	v_mfma_f32_16x16x32_bf16 v[52:55], v[196:199], v[216:219], v[52:55]
	v_mfma_f32_16x16x32_bf16 v[48:51], v[208:211], v[216:219], v[48:51]
	v_mfma_f32_16x16x32_bf16 v[36:39], v[196:199], v[224:227], v[36:39]
	v_mfma_f32_16x16x32_bf16 v[32:35], v[208:211], v[224:227], v[32:35]
	v_mfma_f32_16x16x32_bf16 v[20:23], v[196:199], v[234:237], v[20:23]
	v_mfma_f32_16x16x32_bf16 v[16:19], v[208:211], v[234:237], v[16:19]
	v_mfma_f32_16x16x32_bf16 v[4:7], v[196:199], v[242:245], v[4:7]
	v_mfma_f32_16x16x32_bf16 v[0:3], v[208:211], v[242:245], v[0:3]
	s_barrier
	v_add_u32_e32 v128, s0, v173
	s_add_i32 s84, 0, 0x1c000
	ds_read_b128 v[174:177], v128
	ds_read_b128 v[180:183], v128 offset:1024
	ds_read_b128 v[184:187], v128 offset:2048
	ds_read_b128 v[188:191], v128 offset:3072
	v_add_u32_e32 v128, s84, v173
	ds_read_b128 v[192:195], v128
	ds_read_b128 v[196:199], v128 offset:1024
	ds_read_b128 v[204:207], v128 offset:2048
	ds_read_b128 v[208:211], v128 offset:3072
	s_add_u32 s60, s60, 0x40000
	s_addc_u32 s61, s61, 0
	s_mov_b32 m0, s77
	ds_read_b128 v[212:215], v203 offset:32768
	ds_read_b128 v[216:219], v203 offset:33792
	ds_read_b128 v[220:223], v203 offset:34816
	ds_read_b128 v[224:227], v203 offset:35840
	ds_read_b128 v[228:231], v203 offset:36864
	ds_read_b128 v[234:237], v203 offset:37888
	ds_read_b128 v[238:241], v203 offset:38912
	ds_read_b128 v[242:245], v203 offset:39936
	global_load_lds_dwordx4 v134, s[60:61]
	s_mov_b32 m0, s78
	s_nop 0
	global_load_lds_dwordx4 v138, s[60:61]
	s_waitcnt vmcnt(8)
	s_waitcnt lgkmcnt(0)
	s_barrier
	v_mfma_f32_16x16x32_bf16 v[124:127], v[174:177], v[212:215], v[124:127]
	v_mfma_f32_16x16x32_bf16 v[120:123], v[184:187], v[212:215], v[120:123]
	v_mfma_f32_16x16x32_bf16 v[108:111], v[174:177], v[220:223], v[108:111]
	v_mfma_f32_16x16x32_bf16 v[104:107], v[184:187], v[220:223], v[104:107]
	v_mfma_f32_16x16x32_bf16 v[92:95], v[174:177], v[228:231], v[92:95]
	v_mfma_f32_16x16x32_bf16 v[88:91], v[184:187], v[228:231], v[88:91]
	v_mfma_f32_16x16x32_bf16 v[76:79], v[174:177], v[238:241], v[76:79]
	v_mfma_f32_16x16x32_bf16 v[72:75], v[184:187], v[238:241], v[72:75]
	v_mfma_f32_16x16x32_bf16 v[124:127], v[180:183], v[216:219], v[124:127]
	v_mfma_f32_16x16x32_bf16 v[120:123], v[188:191], v[216:219], v[120:123]
	v_mfma_f32_16x16x32_bf16 v[108:111], v[180:183], v[224:227], v[108:111]
	v_mfma_f32_16x16x32_bf16 v[104:107], v[188:191], v[224:227], v[104:107]
	v_mfma_f32_16x16x32_bf16 v[92:95], v[180:183], v[234:237], v[92:95]
	v_mfma_f32_16x16x32_bf16 v[88:91], v[188:191], v[234:237], v[88:91]
	v_mfma_f32_16x16x32_bf16 v[76:79], v[180:183], v[242:245], v[76:79]
	v_mfma_f32_16x16x32_bf16 v[72:75], v[188:191], v[242:245], v[72:75]
	v_mfma_f32_16x16x32_bf16 v[116:119], v[192:195], v[212:215], v[116:119]
	v_mfma_f32_16x16x32_bf16 v[112:115], v[204:207], v[212:215], v[112:115]
	v_mfma_f32_16x16x32_bf16 v[100:103], v[192:195], v[220:223], v[100:103]
	v_mfma_f32_16x16x32_bf16 v[96:99], v[204:207], v[220:223], v[96:99]
	v_mfma_f32_16x16x32_bf16 v[84:87], v[192:195], v[228:231], v[84:87]
	v_mfma_f32_16x16x32_bf16 v[80:83], v[204:207], v[228:231], v[80:83]
	v_mfma_f32_16x16x32_bf16 v[68:71], v[192:195], v[238:241], v[68:71]
	v_mfma_f32_16x16x32_bf16 v[64:67], v[204:207], v[238:241], v[64:67]
	v_mfma_f32_16x16x32_bf16 v[116:119], v[196:199], v[216:219], v[116:119]
	v_mfma_f32_16x16x32_bf16 v[112:115], v[208:211], v[216:219], v[112:115]
	v_mfma_f32_16x16x32_bf16 v[100:103], v[196:199], v[224:227], v[100:103]
	v_mfma_f32_16x16x32_bf16 v[96:99], v[208:211], v[224:227], v[96:99]
	v_mfma_f32_16x16x32_bf16 v[84:87], v[196:199], v[234:237], v[84:87]
	v_mfma_f32_16x16x32_bf16 v[80:83], v[208:211], v[234:237], v[80:83]
	v_mfma_f32_16x16x32_bf16 v[68:71], v[196:199], v[242:245], v[68:71]
	v_mfma_f32_16x16x32_bf16 v[64:67], v[208:211], v[242:245], v[64:67]
	s_barrier
	s_add_i32 s60, s0, s75
	s_add_u32 s98, s98, s12
	s_addc_u32 s99, s99, s13
	s_mov_b32 m0, s60
	ds_read_b128 v[212:215], v203 offset:49152
	ds_read_b128 v[216:219], v203 offset:50176
	ds_read_b128 v[220:223], v203 offset:51200
	ds_read_b128 v[224:227], v203 offset:52224
	ds_read_b128 v[228:231], v203 offset:53248
	ds_read_b128 v[234:237], v203 offset:54272
	ds_read_b128 v[238:241], v203 offset:55296
	ds_read_b128 v[242:245], v203 offset:56320
	global_load_lds_dwordx4 v136, s[98:99]
	s_add_i32 m0, s60, 0x2000
	s_add_u32 s48, s48, 0x40080
	s_addc_u32 s49, s49, 0
	s_add_i32 s60, s84, s75
	global_load_lds_dwordx4 v140, s[98:99]
	s_mov_b32 m0, s60
	s_nop 0
	global_load_lds_dwordx4 v136, s[48:49]
	s_add_i32 m0, s60, 0x2000
	s_nop 0
	global_load_lds_dwordx4 v140, s[48:49]
	s_add_u32 s100, s100, s12
	s_addc_u32 s101, s101, s13
	s_mov_b32 m0, s79
	s_nop 0
	global_load_lds_dwordx4 v134, s[100:101]
	s_mov_b32 m0, s80
	s_nop 0
	global_load_lds_dwordx4 v138, s[100:101]
	s_waitcnt vmcnt(8)
	s_waitcnt lgkmcnt(0)
	s_barrier
	v_mfma_f32_16x16x32_bf16 v[60:63], v[174:177], v[212:215], v[60:63]
	v_mfma_f32_16x16x32_bf16 v[56:59], v[184:187], v[212:215], v[56:59]
	v_mfma_f32_16x16x32_bf16 v[44:47], v[174:177], v[220:223], v[44:47]
	v_mfma_f32_16x16x32_bf16 v[40:43], v[184:187], v[220:223], v[40:43]
	v_mfma_f32_16x16x32_bf16 v[28:31], v[174:177], v[228:231], v[28:31]
	v_mfma_f32_16x16x32_bf16 v[24:27], v[184:187], v[228:231], v[24:27]
	v_mfma_f32_16x16x32_bf16 v[12:15], v[174:177], v[238:241], v[12:15]
	v_mfma_f32_16x16x32_bf16 v[8:11], v[184:187], v[238:241], v[8:11]
	v_mfma_f32_16x16x32_bf16 v[60:63], v[180:183], v[216:219], v[60:63]
	v_mfma_f32_16x16x32_bf16 v[56:59], v[188:191], v[216:219], v[56:59]
	v_mfma_f32_16x16x32_bf16 v[44:47], v[180:183], v[224:227], v[44:47]
	v_mfma_f32_16x16x32_bf16 v[40:43], v[188:191], v[224:227], v[40:43]
	v_mfma_f32_16x16x32_bf16 v[28:31], v[180:183], v[234:237], v[28:31]
	v_mfma_f32_16x16x32_bf16 v[24:27], v[188:191], v[234:237], v[24:27]
	v_mfma_f32_16x16x32_bf16 v[12:15], v[180:183], v[242:245], v[12:15]
	v_mfma_f32_16x16x32_bf16 v[8:11], v[188:191], v[242:245], v[8:11]
	v_mfma_f32_16x16x32_bf16 v[52:55], v[192:195], v[212:215], v[52:55]
	v_mfma_f32_16x16x32_bf16 v[48:51], v[204:207], v[212:215], v[48:51]
	v_mfma_f32_16x16x32_bf16 v[36:39], v[192:195], v[220:223], v[36:39]
	v_mfma_f32_16x16x32_bf16 v[32:35], v[204:207], v[220:223], v[32:35]
	v_mfma_f32_16x16x32_bf16 v[20:23], v[192:195], v[228:231], v[20:23]
	v_mfma_f32_16x16x32_bf16 v[16:19], v[204:207], v[228:231], v[16:19]
	v_mfma_f32_16x16x32_bf16 v[4:7], v[192:195], v[238:241], v[4:7]
	v_mfma_f32_16x16x32_bf16 v[0:3], v[204:207], v[238:241], v[0:3]
	v_mfma_f32_16x16x32_bf16 v[52:55], v[196:199], v[216:219], v[52:55]
	v_mfma_f32_16x16x32_bf16 v[48:51], v[208:211], v[216:219], v[48:51]
	v_mfma_f32_16x16x32_bf16 v[36:39], v[196:199], v[224:227], v[36:39]
	v_mfma_f32_16x16x32_bf16 v[32:35], v[208:211], v[224:227], v[32:35]
	v_mfma_f32_16x16x32_bf16 v[20:23], v[196:199], v[234:237], v[20:23]
	v_mfma_f32_16x16x32_bf16 v[16:19], v[208:211], v[234:237], v[16:19]
	v_mfma_f32_16x16x32_bf16 v[4:7], v[196:199], v[242:245], v[4:7]
	v_mfma_f32_16x16x32_bf16 v[0:3], v[208:211], v[242:245], v[0:3]
	s_barrier
	s_add_i32 s67, s67, 2
	s_add_u32 s8, s8, 0x100
	s_addc_u32 s9, s9, 0
	s_add_u32 s65, s65, 0x100
	s_addc_u32 s66, s66, 0
	s_cmp_gt_u32 s67, 13
	s_cbranch_scc0 .LBB0_2520
	s_and_b64 vcc, exec, s[50:51]
	s_cbranch_vccz .LBB0_2523
	s_barrier

.LBB0_2602:
	s_add_u32 s56, s48, 0xfffe0080
	s_addc_u32 s57, s49, -1
	s_add_i32 s87, 0, 0x10000
	s_cmp_eq_u32 s86, 4
	s_cselect_b32 s61, s7, s57
	s_cselect_b32 s60, s51, s56
	s_cselect_b32 s57, s45, s85
	s_cselect_b32 s56, s62, s63
	s_add_i32 s90, 0, 0x14000
	v_add_u32_e32 v140, s87, v203
	v_add_u32_e32 v144, s90, v203
	ds_read_b128 v[128:131], v140
	ds_read_b128 v[132:135], v140 offset:1024
	ds_read_b128 v[136:139], v140 offset:2048
	ds_read_b128 v[140:143], v140 offset:3072
	ds_read_b128 v[172:175], v144
	ds_read_b128 v[176:179], v144 offset:1024
	ds_read_b128 v[180:183], v144 offset:2048
	ds_read_b128 v[184:187], v144 offset:3072
	s_add_i32 m0, s76, 0xc000
	ds_read_b128 v[188:191], v206
	ds_read_b128 v[208:211], v206 offset:1024
	ds_read_b128 v[212:215], v206 offset:2048
	ds_read_b128 v[216:219], v206 offset:3072
	ds_read_b128 v[220:223], v206 offset:4096
	ds_read_b128 v[224:227], v206 offset:5120
	ds_read_b128 v[228:231], v206 offset:6144
	ds_read_b128 v[234:237], v206 offset:7168
	global_load_lds_dwordx4 v166, s[48:49]
	s_add_i32 m0, s76, 0xe000
	s_nop 0
	global_load_lds_dwordx4 v168, s[48:49]
	s_waitcnt vmcnt(8)
	s_waitcnt lgkmcnt(0)
	s_barrier
	v_mfma_i32_16x16x64_i8 v[124:127], v[128:131], v[188:191], v[124:127]
	v_mfma_i32_16x16x64_i8 v[120:123], v[136:139], v[188:191], v[120:123]
	v_mfma_i32_16x16x64_i8 v[116:119], v[128:131], v[212:215], v[116:119]
	v_mfma_i32_16x16x64_i8 v[112:115], v[136:139], v[212:215], v[112:115]
	v_mfma_i32_16x16x64_i8 v[108:111], v[128:131], v[220:223], v[108:111]
	v_mfma_i32_16x16x64_i8 v[104:107], v[136:139], v[220:223], v[104:107]
	v_mfma_i32_16x16x64_i8 v[100:103], v[128:131], v[228:231], v[100:103]
	v_mfma_i32_16x16x64_i8 v[96:99], v[136:139], v[228:231], v[96:99]
	v_mfma_i32_16x16x64_i8 v[124:127], v[132:135], v[208:211], v[124:127]
	v_mfma_i32_16x16x64_i8 v[120:123], v[140:143], v[208:211], v[120:123]
	v_mfma_i32_16x16x64_i8 v[116:119], v[132:135], v[216:219], v[116:119]
	v_mfma_i32_16x16x64_i8 v[112:115], v[140:143], v[216:219], v[112:115]
	v_mfma_i32_16x16x64_i8 v[108:111], v[132:135], v[224:227], v[108:111]
	v_mfma_i32_16x16x64_i8 v[104:107], v[140:143], v[224:227], v[104:107]
	v_mfma_i32_16x16x64_i8 v[100:103], v[132:135], v[234:237], v[100:103]
	v_mfma_i32_16x16x64_i8 v[96:99], v[140:143], v[234:237], v[96:99]
	v_mfma_i32_16x16x64_i8 v[92:95], v[172:175], v[188:191], v[92:95]
	v_mfma_i32_16x16x64_i8 v[88:91], v[180:183], v[188:191], v[88:91]
	v_mfma_i32_16x16x64_i8 v[84:87], v[172:175], v[212:215], v[84:87]
	v_mfma_i32_16x16x64_i8 v[80:83], v[180:183], v[212:215], v[80:83]
	v_mfma_i32_16x16x64_i8 v[76:79], v[172:175], v[220:223], v[76:79]
	v_mfma_i32_16x16x64_i8 v[72:75], v[180:183], v[220:223], v[72:75]
	v_mfma_i32_16x16x64_i8 v[68:71], v[172:175], v[228:231], v[68:71]
	v_mfma_i32_16x16x64_i8 v[64:67], v[180:183], v[228:231], v[64:67]
	v_mfma_i32_16x16x64_i8 v[92:95], v[176:179], v[208:211], v[92:95]
	v_mfma_i32_16x16x64_i8 v[88:91], v[184:187], v[208:211], v[88:91]
	v_mfma_i32_16x16x64_i8 v[84:87], v[176:179], v[216:219], v[84:87]
	v_mfma_i32_16x16x64_i8 v[80:83], v[184:187], v[216:219], v[80:83]
	v_mfma_i32_16x16x64_i8 v[76:79], v[176:179], v[224:227], v[76:79]
	v_mfma_i32_16x16x64_i8 v[72:75], v[184:187], v[224:227], v[72:75]
	v_mfma_i32_16x16x64_i8 v[68:71], v[176:179], v[234:237], v[68:71]
	v_mfma_i32_16x16x64_i8 v[64:67], v[184:187], v[234:237], v[64:67]
	s_barrier
	s_add_i32 s87, s87, s75
	s_mov_b64 s[98:99], s[56:57]
	s_mov_b32 m0, s87
	ds_read_b128 v[188:191], v206 offset:16384
	ds_read_b128 v[208:211], v206 offset:17408
	ds_read_b128 v[212:215], v206 offset:18432
	ds_read_b128 v[216:219], v206 offset:19456
	ds_read_b128 v[220:223], v206 offset:20480
	ds_read_b128 v[224:227], v206 offset:21504
	ds_read_b128 v[228:231], v206 offset:22528
	ds_read_b128 v[234:237], v206 offset:23552
	global_load_lds_dwordx4 v152, s[56:57]
	s_add_i32 m0, s87, 0x2000
	s_add_u32 s88, s56, 0x20000
	s_addc_u32 s89, s57, 0
	s_add_i32 s87, s90, s75
	global_load_lds_dwordx4 v156, s[56:57]
	s_mov_b32 m0, s87
	s_mov_b64 s[100:101], s[60:61]
	global_load_lds_dwordx4 v152, s[88:89]
	s_add_i32 m0, s87, 0x2000
	s_nop 0
	global_load_lds_dwordx4 v156, s[88:89]
	s_mov_b32 m0, s76
	s_nop 0
	global_load_lds_dwordx4 v150, s[60:61]
	s_mov_b32 m0, s77
	s_nop 0
	global_load_lds_dwordx4 v154, s[60:61]
	s_waitcnt vmcnt(8)
	s_waitcnt lgkmcnt(0)
	s_barrier
	v_mfma_i32_16x16x64_i8 v[60:63], v[128:131], v[188:191], v[60:63]
	v_mfma_i32_16x16x64_i8 v[56:59], v[136:139], v[188:191], v[56:59]
	v_mfma_i32_16x16x64_i8 v[52:55], v[128:131], v[212:215], v[52:55]
	v_mfma_i32_16x16x64_i8 v[48:51], v[136:139], v[212:215], v[48:51]
	v_mfma_i32_16x16x64_i8 v[44:47], v[128:131], v[220:223], v[44:47]
	v_mfma_i32_16x16x64_i8 v[40:43], v[136:139], v[220:223], v[40:43]
	v_mfma_i32_16x16x64_i8 v[36:39], v[128:131], v[228:231], v[36:39]
	v_mfma_i32_16x16x64_i8 v[32:35], v[136:139], v[228:231], v[32:35]
	v_mfma_i32_16x16x64_i8 v[60:63], v[132:135], v[208:211], v[60:63]
	v_mfma_i32_16x16x64_i8 v[56:59], v[140:143], v[208:211], v[56:59]
	v_mfma_i32_16x16x64_i8 v[52:55], v[132:135], v[216:219], v[52:55]
	v_mfma_i32_16x16x64_i8 v[48:51], v[140:143], v[216:219], v[48:51]
	v_mfma_i32_16x16x64_i8 v[44:47], v[132:135], v[224:227], v[44:47]
	v_mfma_i32_16x16x64_i8 v[40:43], v[140:143], v[224:227], v[40:43]
	v_mfma_i32_16x16x64_i8 v[36:39], v[132:135], v[234:237], v[36:39]
	v_mfma_i32_16x16x64_i8 v[32:35], v[140:143], v[234:237], v[32:35]
	v_mfma_i32_16x16x64_i8 v[28:31], v[172:175], v[188:191], v[28:31]
	v_mfma_i32_16x16x64_i8 v[24:27], v[180:183], v[188:191], v[24:27]
	v_mfma_i32_16x16x64_i8 v[20:23], v[172:175], v[212:215], v[20:23]
	v_mfma_i32_16x16x64_i8 v[16:19], v[180:183], v[212:215], v[16:19]
	v_mfma_i32_16x16x64_i8 v[12:15], v[172:175], v[220:223], v[12:15]
	v_mfma_i32_16x16x64_i8 v[8:11], v[180:183], v[220:223], v[8:11]
	v_mfma_i32_16x16x64_i8 v[4:7], v[172:175], v[228:231], v[4:7]
	v_mfma_i32_16x16x64_i8 v[0:3], v[180:183], v[228:231], v[0:3]
	v_mfma_i32_16x16x64_i8 v[28:31], v[176:179], v[208:211], v[28:31]
	v_mfma_i32_16x16x64_i8 v[24:27], v[184:187], v[208:211], v[24:27]
	v_mfma_i32_16x16x64_i8 v[20:23], v[176:179], v[216:219], v[20:23]
	v_mfma_i32_16x16x64_i8 v[16:19], v[184:187], v[216:219], v[16:19]
	v_mfma_i32_16x16x64_i8 v[12:15], v[176:179], v[224:227], v[12:15]
	v_mfma_i32_16x16x64_i8 v[8:11], v[184:187], v[224:227], v[8:11]
	v_mfma_i32_16x16x64_i8 v[4:7], v[176:179], v[234:237], v[4:7]
	v_mfma_i32_16x16x64_i8 v[0:3], v[184:187], v[234:237], v[0:3]
	s_barrier
	s_add_i32 s87, 0, 0x1c000
	v_add_u32_e32 v140, s0, v203
	v_add_u32_e32 v144, s87, v203
	ds_read_b128 v[128:131], v140
	ds_read_b128 v[132:135], v140 offset:1024
	ds_read_b128 v[136:139], v140 offset:2048
	ds_read_b128 v[140:143], v140 offset:3072
	ds_read_b128 v[172:175], v144
	ds_read_b128 v[176:179], v144 offset:1024
	ds_read_b128 v[180:183], v144 offset:2048
	ds_read_b128 v[184:187], v144 offset:3072
	s_add_u32 s60, s60, 0x20000
	s_addc_u32 s61, s61, 0
	s_mov_b32 m0, s78
	ds_read_b128 v[188:191], v206 offset:32768
	ds_read_b128 v[208:211], v206 offset:33792
	ds_read_b128 v[212:215], v206 offset:34816
	ds_read_b128 v[216:219], v206 offset:35840
	ds_read_b128 v[220:223], v206 offset:36864
	ds_read_b128 v[224:227], v206 offset:37888
	ds_read_b128 v[228:231], v206 offset:38912
	ds_read_b128 v[234:237], v206 offset:39936
	global_load_lds_dwordx4 v150, s[60:61]
	s_mov_b32 m0, s79
	s_nop 0
	global_load_lds_dwordx4 v154, s[60:61]
	s_waitcnt vmcnt(8)
	s_waitcnt lgkmcnt(0)
	s_barrier
	v_mfma_i32_16x16x64_i8 v[124:127], v[128:131], v[188:191], v[124:127]
	v_mfma_i32_16x16x64_i8 v[120:123], v[136:139], v[188:191], v[120:123]
	v_mfma_i32_16x16x64_i8 v[116:119], v[128:131], v[212:215], v[116:119]
	v_mfma_i32_16x16x64_i8 v[112:115], v[136:139], v[212:215], v[112:115]
	v_mfma_i32_16x16x64_i8 v[108:111], v[128:131], v[220:223], v[108:111]
	v_mfma_i32_16x16x64_i8 v[104:107], v[136:139], v[220:223], v[104:107]
	v_mfma_i32_16x16x64_i8 v[100:103], v[128:131], v[228:231], v[100:103]
	v_mfma_i32_16x16x64_i8 v[96:99], v[136:139], v[228:231], v[96:99]
	v_mfma_i32_16x16x64_i8 v[124:127], v[132:135], v[208:211], v[124:127]
	v_mfma_i32_16x16x64_i8 v[120:123], v[140:143], v[208:211], v[120:123]
	v_mfma_i32_16x16x64_i8 v[116:119], v[132:135], v[216:219], v[116:119]
	v_mfma_i32_16x16x64_i8 v[112:115], v[140:143], v[216:219], v[112:115]
	v_mfma_i32_16x16x64_i8 v[108:111], v[132:135], v[224:227], v[108:111]
	v_mfma_i32_16x16x64_i8 v[104:107], v[140:143], v[224:227], v[104:107]
	v_mfma_i32_16x16x64_i8 v[100:103], v[132:135], v[234:237], v[100:103]
	v_mfma_i32_16x16x64_i8 v[96:99], v[140:143], v[234:237], v[96:99]
	v_mfma_i32_16x16x64_i8 v[92:95], v[172:175], v[188:191], v[92:95]
	v_mfma_i32_16x16x64_i8 v[88:91], v[180:183], v[188:191], v[88:91]
	v_mfma_i32_16x16x64_i8 v[84:87], v[172:175], v[212:215], v[84:87]
	v_mfma_i32_16x16x64_i8 v[80:83], v[180:183], v[212:215], v[80:83]
	v_mfma_i32_16x16x64_i8 v[76:79], v[172:175], v[220:223], v[76:79]
	v_mfma_i32_16x16x64_i8 v[72:75], v[180:183], v[220:223], v[72:75]
	v_mfma_i32_16x16x64_i8 v[68:71], v[172:175], v[228:231], v[68:71]
	v_mfma_i32_16x16x64_i8 v[64:67], v[180:183], v[228:231], v[64:67]
	v_mfma_i32_16x16x64_i8 v[92:95], v[176:179], v[208:211], v[92:95]
	v_mfma_i32_16x16x64_i8 v[88:91], v[184:187], v[208:211], v[88:91]
	v_mfma_i32_16x16x64_i8 v[84:87], v[176:179], v[216:219], v[84:87]
	v_mfma_i32_16x16x64_i8 v[80:83], v[184:187], v[216:219], v[80:83]
	v_mfma_i32_16x16x64_i8 v[76:79], v[176:179], v[224:227], v[76:79]
	v_mfma_i32_16x16x64_i8 v[72:75], v[184:187], v[224:227], v[72:75]
	v_mfma_i32_16x16x64_i8 v[68:71], v[176:179], v[234:237], v[68:71]
	v_mfma_i32_16x16x64_i8 v[64:67], v[184:187], v[234:237], v[64:67]
	s_barrier
	s_add_i32 s60, s0, s75
	s_add_u32 s98, s98, s10
	s_addc_u32 s99, s99, s11
	s_mov_b32 m0, s60
	ds_read_b128 v[188:191], v206 offset:49152
	ds_read_b128 v[208:211], v206 offset:50176
	ds_read_b128 v[212:215], v206 offset:51200
	ds_read_b128 v[216:219], v206 offset:52224
	ds_read_b128 v[220:223], v206 offset:53248
	ds_read_b128 v[224:227], v206 offset:54272
	ds_read_b128 v[228:231], v206 offset:55296
	ds_read_b128 v[234:237], v206 offset:56320
	global_load_lds_dwordx4 v152, s[98:99]
	s_add_i32 m0, s60, 0x2000
	s_add_u32 s56, s56, 0x20080
	s_addc_u32 s57, s57, 0
	s_add_i32 s60, s87, s75
	global_load_lds_dwordx4 v156, s[98:99]
	s_mov_b32 m0, s60
	s_nop 0
	global_load_lds_dwordx4 v152, s[56:57]
	s_add_i32 m0, s60, 0x2000
	s_nop 0
	global_load_lds_dwordx4 v156, s[56:57]
	s_add_u32 s100, s100, s10
	s_addc_u32 s101, s101, s11
	s_mov_b32 m0, s80
	s_nop 0
	global_load_lds_dwordx4 v150, s[100:101]
	s_mov_b32 m0, s81
	s_nop 0
	global_load_lds_dwordx4 v154, s[100:101]
	s_waitcnt vmcnt(8)
	s_waitcnt lgkmcnt(0)
	s_barrier
	v_mfma_i32_16x16x64_i8 v[60:63], v[128:131], v[188:191], v[60:63]
	v_mfma_i32_16x16x64_i8 v[56:59], v[136:139], v[188:191], v[56:59]
	v_mfma_i32_16x16x64_i8 v[52:55], v[128:131], v[212:215], v[52:55]
	v_mfma_i32_16x16x64_i8 v[48:51], v[136:139], v[212:215], v[48:51]
	v_mfma_i32_16x16x64_i8 v[44:47], v[128:131], v[220:223], v[44:47]
	v_mfma_i32_16x16x64_i8 v[40:43], v[136:139], v[220:223], v[40:43]
	v_mfma_i32_16x16x64_i8 v[36:39], v[128:131], v[228:231], v[36:39]
	v_mfma_i32_16x16x64_i8 v[32:35], v[136:139], v[228:231], v[32:35]
	v_mfma_i32_16x16x64_i8 v[60:63], v[132:135], v[208:211], v[60:63]
	v_mfma_i32_16x16x64_i8 v[56:59], v[140:143], v[208:211], v[56:59]
	v_mfma_i32_16x16x64_i8 v[52:55], v[132:135], v[216:219], v[52:55]
	v_mfma_i32_16x16x64_i8 v[48:51], v[140:143], v[216:219], v[48:51]
	v_mfma_i32_16x16x64_i8 v[44:47], v[132:135], v[224:227], v[44:47]
	v_mfma_i32_16x16x64_i8 v[40:43], v[140:143], v[224:227], v[40:43]
	v_mfma_i32_16x16x64_i8 v[36:39], v[132:135], v[234:237], v[36:39]
	v_mfma_i32_16x16x64_i8 v[32:35], v[140:143], v[234:237], v[32:35]
	v_mfma_i32_16x16x64_i8 v[28:31], v[172:175], v[188:191], v[28:31]
	v_mfma_i32_16x16x64_i8 v[24:27], v[180:183], v[188:191], v[24:27]
	v_mfma_i32_16x16x64_i8 v[20:23], v[172:175], v[212:215], v[20:23]
	v_mfma_i32_16x16x64_i8 v[16:19], v[180:183], v[212:215], v[16:19]
	v_mfma_i32_16x16x64_i8 v[12:15], v[172:175], v[220:223], v[12:15]
	v_mfma_i32_16x16x64_i8 v[8:11], v[180:183], v[220:223], v[8:11]
	v_mfma_i32_16x16x64_i8 v[4:7], v[172:175], v[228:231], v[4:7]
	v_mfma_i32_16x16x64_i8 v[0:3], v[180:183], v[228:231], v[0:3]
	v_mfma_i32_16x16x64_i8 v[28:31], v[176:179], v[208:211], v[28:31]
	v_mfma_i32_16x16x64_i8 v[24:27], v[184:187], v[208:211], v[24:27]
	v_mfma_i32_16x16x64_i8 v[20:23], v[176:179], v[216:219], v[20:23]
	v_mfma_i32_16x16x64_i8 v[16:19], v[184:187], v[216:219], v[16:19]
	v_mfma_i32_16x16x64_i8 v[12:15], v[176:179], v[224:227], v[12:15]
	v_mfma_i32_16x16x64_i8 v[8:11], v[184:187], v[224:227], v[8:11]
	v_mfma_i32_16x16x64_i8 v[4:7], v[176:179], v[234:237], v[4:7]
	v_mfma_i32_16x16x64_i8 v[0:3], v[184:187], v[234:237], v[0:3]
	s_barrier
	s_add_i32 s86, s86, 2
	s_add_u32 s48, s48, 0x100
	s_addc_u32 s49, s49, 0
	s_add_u32 s63, s63, 0x100
	s_addc_u32 s85, s85, 0
	s_cmp_gt_u32 s86, 5
	s_cbranch_scc0 .LBB0_2602
	s_and_b64 vcc, exec, s[42:43]
	s_cbranch_vccz .LBB0_2605
	s_barrier

.LBB0_2985:
	s_add_u32 s58, s56, 0xfffe0080
	s_addc_u32 s59, s57, -1
	s_add_i32 s85, 0, 0x10000
	s_cmp_eq_u32 s84, 4
	s_cselect_b32 s61, s51, s59
	s_cselect_b32 s60, s81, s58
	s_cselect_b32 s59, s43, s83
	s_cselect_b32 s58, s45, s82
	s_add_i32 s88, 0, 0x14000
	v_add_u32_e32 v150, s85, v182
	v_add_u32_e32 v154, s88, v182
	ds_read_b128 v[138:141], v150
	ds_read_b128 v[142:145], v150 offset:1024
	ds_read_b128 v[146:149], v150 offset:2048
	ds_read_b128 v[150:153], v150 offset:3072
	ds_read_b128 v[166:169], v154
	ds_read_b128 v[190:193], v154 offset:1024
	ds_read_b128 v[194:197], v154 offset:2048
	ds_read_b128 v[198:201], v154 offset:3072
	s_add_i32 m0, s12, 0xc000
	ds_read_b128 v[202:205], v185
	ds_read_b128 v[206:209], v185 offset:1024
	ds_read_b128 v[210:213], v185 offset:2048
	ds_read_b128 v[214:217], v185 offset:3072
	ds_read_b128 v[218:221], v185 offset:4096
	ds_read_b128 v[222:225], v185 offset:5120
	ds_read_b128 v[226:229], v185 offset:6144
	ds_read_b128 v[234:237], v185 offset:7168
	global_load_lds_dwordx4 v134, s[56:57]
	s_add_i32 m0, s12, 0xe000
	s_nop 0
	global_load_lds_dwordx4 v136, s[56:57]
	s_waitcnt vmcnt(8)
	s_waitcnt lgkmcnt(0)
	s_barrier
	v_mfma_i32_16x16x64_i8 v[126:129], v[138:141], v[202:205], v[126:129]
	v_mfma_i32_16x16x64_i8 v[122:125], v[146:149], v[202:205], v[122:125]
	v_mfma_i32_16x16x64_i8 v[110:113], v[138:141], v[210:213], v[110:113]
	v_mfma_i32_16x16x64_i8 v[106:109], v[146:149], v[210:213], v[106:109]
	v_mfma_i32_16x16x64_i8 v[94:97], v[138:141], v[218:221], v[94:97]
	v_mfma_i32_16x16x64_i8 v[90:93], v[146:149], v[218:221], v[90:93]
	v_mfma_i32_16x16x64_i8 v[78:81], v[138:141], v[226:229], v[78:81]
	v_mfma_i32_16x16x64_i8 v[74:77], v[146:149], v[226:229], v[74:77]
	v_mfma_i32_16x16x64_i8 v[126:129], v[142:145], v[206:209], v[126:129]
	v_mfma_i32_16x16x64_i8 v[122:125], v[150:153], v[206:209], v[122:125]
	v_mfma_i32_16x16x64_i8 v[110:113], v[142:145], v[214:217], v[110:113]
	v_mfma_i32_16x16x64_i8 v[106:109], v[150:153], v[214:217], v[106:109]
	v_mfma_i32_16x16x64_i8 v[94:97], v[142:145], v[222:225], v[94:97]
	v_mfma_i32_16x16x64_i8 v[90:93], v[150:153], v[222:225], v[90:93]
	v_mfma_i32_16x16x64_i8 v[78:81], v[142:145], v[234:237], v[78:81]
	v_mfma_i32_16x16x64_i8 v[74:77], v[150:153], v[234:237], v[74:77]
	v_mfma_i32_16x16x64_i8 v[118:121], v[166:169], v[202:205], v[118:121]
	v_mfma_i32_16x16x64_i8 v[114:117], v[194:197], v[202:205], v[114:117]
	v_mfma_i32_16x16x64_i8 v[102:105], v[166:169], v[210:213], v[102:105]
	v_mfma_i32_16x16x64_i8 v[98:101], v[194:197], v[210:213], v[98:101]
	v_mfma_i32_16x16x64_i8 v[86:89], v[166:169], v[218:221], v[86:89]
	v_mfma_i32_16x16x64_i8 v[82:85], v[194:197], v[218:221], v[82:85]
	v_mfma_i32_16x16x64_i8 v[70:73], v[166:169], v[226:229], v[70:73]
	v_mfma_i32_16x16x64_i8 v[66:69], v[194:197], v[226:229], v[66:69]
	v_mfma_i32_16x16x64_i8 v[118:121], v[190:193], v[206:209], v[118:121]
	v_mfma_i32_16x16x64_i8 v[114:117], v[198:201], v[206:209], v[114:117]
	v_mfma_i32_16x16x64_i8 v[102:105], v[190:193], v[214:217], v[102:105]
	v_mfma_i32_16x16x64_i8 v[98:101], v[198:201], v[214:217], v[98:101]
	v_mfma_i32_16x16x64_i8 v[86:89], v[190:193], v[222:225], v[86:89]
	v_mfma_i32_16x16x64_i8 v[82:85], v[198:201], v[222:225], v[82:85]
	v_mfma_i32_16x16x64_i8 v[70:73], v[190:193], v[234:237], v[70:73]
	v_mfma_i32_16x16x64_i8 v[66:69], v[198:201], v[234:237], v[66:69]
	s_barrier
	s_add_i32 s85, s85, s71
	s_mov_b64 s[98:99], s[58:59]
	s_mov_b32 m0, s85
	ds_read_b128 v[202:205], v185 offset:16384
	ds_read_b128 v[206:209], v185 offset:17408
	ds_read_b128 v[210:213], v185 offset:18432
	ds_read_b128 v[214:217], v185 offset:19456
	ds_read_b128 v[218:221], v185 offset:20480
	ds_read_b128 v[222:225], v185 offset:21504
	ds_read_b128 v[226:229], v185 offset:22528
	ds_read_b128 v[234:237], v185 offset:23552
	global_load_lds_dwordx4 v0, s[58:59]
	s_add_i32 m0, s85, 0x2000
	s_add_u32 s86, s58, 0x20000
	s_addc_u32 s87, s59, 0
	s_add_i32 s85, s88, s71
	global_load_lds_dwordx4 v164, s[58:59]
	s_mov_b32 m0, s85
	s_mov_b64 s[100:101], s[60:61]
	global_load_lds_dwordx4 v0, s[86:87]
	s_add_i32 m0, s85, 0x2000
	s_nop 0
	global_load_lds_dwordx4 v164, s[86:87]
	s_mov_b32 m0, s12
	s_nop 0
	global_load_lds_dwordx4 v160, s[60:61]
	s_mov_b32 m0, s49
	s_nop 0
	global_load_lds_dwordx4 v162, s[60:61]
	s_waitcnt vmcnt(8)
	s_waitcnt lgkmcnt(0)
	s_barrier
	v_mfma_i32_16x16x64_i8 v[62:65], v[138:141], v[202:205], v[62:65]
	v_mfma_i32_16x16x64_i8 v[58:61], v[146:149], v[202:205], v[58:61]
	v_mfma_i32_16x16x64_i8 v[46:49], v[138:141], v[210:213], v[46:49]
	v_mfma_i32_16x16x64_i8 v[42:45], v[146:149], v[210:213], v[42:45]
	v_mfma_i32_16x16x64_i8 v[30:33], v[138:141], v[218:221], v[30:33]
	v_mfma_i32_16x16x64_i8 v[26:29], v[146:149], v[218:221], v[26:29]
	v_mfma_i32_16x16x64_i8 v[10:13], v[138:141], v[226:229], v[10:13]
	v_mfma_i32_16x16x64_i8 v[2:5], v[146:149], v[226:229], v[2:5]
	v_mfma_i32_16x16x64_i8 v[62:65], v[142:145], v[206:209], v[62:65]
	v_mfma_i32_16x16x64_i8 v[58:61], v[150:153], v[206:209], v[58:61]
	v_mfma_i32_16x16x64_i8 v[46:49], v[142:145], v[214:217], v[46:49]
	v_mfma_i32_16x16x64_i8 v[42:45], v[150:153], v[214:217], v[42:45]
	v_mfma_i32_16x16x64_i8 v[30:33], v[142:145], v[222:225], v[30:33]
	v_mfma_i32_16x16x64_i8 v[26:29], v[150:153], v[222:225], v[26:29]
	v_mfma_i32_16x16x64_i8 v[10:13], v[142:145], v[234:237], v[10:13]
	v_mfma_i32_16x16x64_i8 v[2:5], v[150:153], v[234:237], v[2:5]
	v_mfma_i32_16x16x64_i8 v[54:57], v[166:169], v[202:205], v[54:57]
	v_mfma_i32_16x16x64_i8 v[50:53], v[194:197], v[202:205], v[50:53]
	v_mfma_i32_16x16x64_i8 v[38:41], v[166:169], v[210:213], v[38:41]
	v_mfma_i32_16x16x64_i8 v[34:37], v[194:197], v[210:213], v[34:37]
	v_mfma_i32_16x16x64_i8 v[22:25], v[166:169], v[218:221], v[22:25]
	v_mfma_i32_16x16x64_i8 v[18:21], v[194:197], v[218:221], v[18:21]
	v_mfma_i32_16x16x64_i8 v[14:17], v[166:169], v[226:229], v[14:17]
	v_mfma_i32_16x16x64_i8 v[6:9], v[194:197], v[226:229], v[6:9]
	v_mfma_i32_16x16x64_i8 v[54:57], v[190:193], v[206:209], v[54:57]
	v_mfma_i32_16x16x64_i8 v[50:53], v[198:201], v[206:209], v[50:53]
	v_mfma_i32_16x16x64_i8 v[38:41], v[190:193], v[214:217], v[38:41]
	v_mfma_i32_16x16x64_i8 v[34:37], v[198:201], v[214:217], v[34:37]
	v_mfma_i32_16x16x64_i8 v[22:25], v[190:193], v[222:225], v[22:25]
	v_mfma_i32_16x16x64_i8 v[18:21], v[198:201], v[222:225], v[18:21]
	v_mfma_i32_16x16x64_i8 v[14:17], v[190:193], v[234:237], v[14:17]
	v_mfma_i32_16x16x64_i8 v[6:9], v[198:201], v[234:237], v[6:9]
	s_barrier
	s_add_i32 s85, 0, 0x18000
	s_add_i32 s86, 0, 0x1c000
	v_add_u32_e32 v150, s85, v182
	v_add_u32_e32 v189, s86, v182
	ds_read_b128 v[138:141], v150
	ds_read_b128 v[142:145], v150 offset:1024
	ds_read_b128 v[146:149], v150 offset:2048
	ds_read_b128 v[150:153], v150 offset:3072
	ds_read_b128 v[166:169], v189
	ds_read_b128 v[190:193], v189 offset:1024
	ds_read_b128 v[194:197], v189 offset:2048
	ds_read_b128 v[198:201], v189 offset:3072
	s_add_u32 s60, s60, 0x20000
	s_addc_u32 s61, s61, 0
	s_mov_b32 m0, s72
	ds_read_b128 v[202:205], v185 offset:32768
	ds_read_b128 v[206:209], v185 offset:33792
	ds_read_b128 v[210:213], v185 offset:34816
	ds_read_b128 v[214:217], v185 offset:35840
	ds_read_b128 v[218:221], v185 offset:36864
	ds_read_b128 v[222:225], v185 offset:37888
	ds_read_b128 v[226:229], v185 offset:38912
	ds_read_b128 v[234:237], v185 offset:39936
	global_load_lds_dwordx4 v160, s[60:61]
	s_mov_b32 m0, s73
	s_nop 0
	global_load_lds_dwordx4 v162, s[60:61]
	s_waitcnt vmcnt(8)
	s_waitcnt lgkmcnt(0)
	s_barrier
	v_mfma_i32_16x16x64_i8 v[126:129], v[138:141], v[202:205], v[126:129]
	v_mfma_i32_16x16x64_i8 v[122:125], v[146:149], v[202:205], v[122:125]
	v_mfma_i32_16x16x64_i8 v[110:113], v[138:141], v[210:213], v[110:113]
	v_mfma_i32_16x16x64_i8 v[106:109], v[146:149], v[210:213], v[106:109]
	v_mfma_i32_16x16x64_i8 v[94:97], v[138:141], v[218:221], v[94:97]
	v_mfma_i32_16x16x64_i8 v[90:93], v[146:149], v[218:221], v[90:93]
	v_mfma_i32_16x16x64_i8 v[78:81], v[138:141], v[226:229], v[78:81]
	v_mfma_i32_16x16x64_i8 v[74:77], v[146:149], v[226:229], v[74:77]
	v_mfma_i32_16x16x64_i8 v[126:129], v[142:145], v[206:209], v[126:129]
	v_mfma_i32_16x16x64_i8 v[122:125], v[150:153], v[206:209], v[122:125]
	v_mfma_i32_16x16x64_i8 v[110:113], v[142:145], v[214:217], v[110:113]
	v_mfma_i32_16x16x64_i8 v[106:109], v[150:153], v[214:217], v[106:109]
	v_mfma_i32_16x16x64_i8 v[94:97], v[142:145], v[222:225], v[94:97]
	v_mfma_i32_16x16x64_i8 v[90:93], v[150:153], v[222:225], v[90:93]
	v_mfma_i32_16x16x64_i8 v[78:81], v[142:145], v[234:237], v[78:81]
	v_mfma_i32_16x16x64_i8 v[74:77], v[150:153], v[234:237], v[74:77]
	v_mfma_i32_16x16x64_i8 v[118:121], v[166:169], v[202:205], v[118:121]
	v_mfma_i32_16x16x64_i8 v[114:117], v[194:197], v[202:205], v[114:117]
	v_mfma_i32_16x16x64_i8 v[102:105], v[166:169], v[210:213], v[102:105]
	v_mfma_i32_16x16x64_i8 v[98:101], v[194:197], v[210:213], v[98:101]
	v_mfma_i32_16x16x64_i8 v[86:89], v[166:169], v[218:221], v[86:89]
	v_mfma_i32_16x16x64_i8 v[82:85], v[194:197], v[218:221], v[82:85]
	v_mfma_i32_16x16x64_i8 v[70:73], v[166:169], v[226:229], v[70:73]
	v_mfma_i32_16x16x64_i8 v[66:69], v[194:197], v[226:229], v[66:69]
	v_mfma_i32_16x16x64_i8 v[118:121], v[190:193], v[206:209], v[118:121]
	v_mfma_i32_16x16x64_i8 v[114:117], v[198:201], v[206:209], v[114:117]
	v_mfma_i32_16x16x64_i8 v[102:105], v[190:193], v[214:217], v[102:105]
	v_mfma_i32_16x16x64_i8 v[98:101], v[198:201], v[214:217], v[98:101]
	v_mfma_i32_16x16x64_i8 v[86:89], v[190:193], v[222:225], v[86:89]
	v_mfma_i32_16x16x64_i8 v[82:85], v[198:201], v[222:225], v[82:85]
	v_mfma_i32_16x16x64_i8 v[70:73], v[190:193], v[234:237], v[70:73]
	v_mfma_i32_16x16x64_i8 v[66:69], v[198:201], v[234:237], v[66:69]
	s_barrier
	s_add_i32 s60, s85, s71
	s_add_u32 s98, s98, s14
	s_addc_u32 s99, s99, s15
	s_mov_b32 m0, s60
	ds_read_b128 v[202:205], v185 offset:49152
	ds_read_b128 v[206:209], v185 offset:50176
	ds_read_b128 v[210:213], v185 offset:51200
	ds_read_b128 v[214:217], v185 offset:52224
	ds_read_b128 v[218:221], v185 offset:53248
	ds_read_b128 v[222:225], v185 offset:54272
	ds_read_b128 v[226:229], v185 offset:55296
	ds_read_b128 v[234:237], v185 offset:56320
	global_load_lds_dwordx4 v0, s[98:99]
	s_add_i32 m0, s60, 0x2000
	s_add_u32 s58, s58, 0x20080
	s_addc_u32 s59, s59, 0
	s_add_i32 s60, s86, s71
	global_load_lds_dwordx4 v164, s[98:99]
	s_mov_b32 m0, s60
	s_nop 0
	global_load_lds_dwordx4 v0, s[58:59]
	s_add_i32 m0, s60, 0x2000
	s_nop 0
	global_load_lds_dwordx4 v164, s[58:59]
	s_add_u32 s100, s100, s14
	s_addc_u32 s101, s101, s15
	s_mov_b32 m0, s74
	s_nop 0
	global_load_lds_dwordx4 v160, s[100:101]
	s_mov_b32 m0, s75
	s_nop 0
	global_load_lds_dwordx4 v162, s[100:101]
	s_waitcnt vmcnt(8)
	s_waitcnt lgkmcnt(0)
	s_barrier
	v_mfma_i32_16x16x64_i8 v[62:65], v[138:141], v[202:205], v[62:65]
	v_mfma_i32_16x16x64_i8 v[58:61], v[146:149], v[202:205], v[58:61]
	v_mfma_i32_16x16x64_i8 v[46:49], v[138:141], v[210:213], v[46:49]
	v_mfma_i32_16x16x64_i8 v[42:45], v[146:149], v[210:213], v[42:45]
	v_mfma_i32_16x16x64_i8 v[30:33], v[138:141], v[218:221], v[30:33]
	v_mfma_i32_16x16x64_i8 v[26:29], v[146:149], v[218:221], v[26:29]
	v_mfma_i32_16x16x64_i8 v[10:13], v[138:141], v[226:229], v[10:13]
	v_mfma_i32_16x16x64_i8 v[2:5], v[146:149], v[226:229], v[2:5]
	v_mfma_i32_16x16x64_i8 v[62:65], v[142:145], v[206:209], v[62:65]
	v_mfma_i32_16x16x64_i8 v[58:61], v[150:153], v[206:209], v[58:61]
	v_mfma_i32_16x16x64_i8 v[46:49], v[142:145], v[214:217], v[46:49]
	v_mfma_i32_16x16x64_i8 v[42:45], v[150:153], v[214:217], v[42:45]
	v_mfma_i32_16x16x64_i8 v[30:33], v[142:145], v[222:225], v[30:33]
	v_mfma_i32_16x16x64_i8 v[26:29], v[150:153], v[222:225], v[26:29]
	v_mfma_i32_16x16x64_i8 v[10:13], v[142:145], v[234:237], v[10:13]
	v_mfma_i32_16x16x64_i8 v[2:5], v[150:153], v[234:237], v[2:5]
	v_mfma_i32_16x16x64_i8 v[54:57], v[166:169], v[202:205], v[54:57]
	v_mfma_i32_16x16x64_i8 v[50:53], v[194:197], v[202:205], v[50:53]
	v_mfma_i32_16x16x64_i8 v[38:41], v[166:169], v[210:213], v[38:41]
	v_mfma_i32_16x16x64_i8 v[34:37], v[194:197], v[210:213], v[34:37]
	v_mfma_i32_16x16x64_i8 v[22:25], v[166:169], v[218:221], v[22:25]
	v_mfma_i32_16x16x64_i8 v[18:21], v[194:197], v[218:221], v[18:21]
	v_mfma_i32_16x16x64_i8 v[14:17], v[166:169], v[226:229], v[14:17]
	v_mfma_i32_16x16x64_i8 v[6:9], v[194:197], v[226:229], v[6:9]
	v_mfma_i32_16x16x64_i8 v[54:57], v[190:193], v[206:209], v[54:57]
	v_mfma_i32_16x16x64_i8 v[50:53], v[198:201], v[206:209], v[50:53]
	v_mfma_i32_16x16x64_i8 v[38:41], v[190:193], v[214:217], v[38:41]
	v_mfma_i32_16x16x64_i8 v[34:37], v[198:201], v[214:217], v[34:37]
	v_mfma_i32_16x16x64_i8 v[22:25], v[190:193], v[222:225], v[22:25]
	v_mfma_i32_16x16x64_i8 v[18:21], v[198:201], v[222:225], v[18:21]
	v_mfma_i32_16x16x64_i8 v[14:17], v[190:193], v[234:237], v[14:17]
	v_mfma_i32_16x16x64_i8 v[6:9], v[198:201], v[234:237], v[6:9]
	s_barrier
	s_add_i32 s84, s84, 2
	s_add_u32 s56, s56, 0x100
	s_addc_u32 s57, s57, 0
	s_add_u32 s82, s82, 0x100
	s_addc_u32 s83, s83, 0
	s_cmp_gt_u32 s84, 5
	s_cbranch_scc0 .LBB0_2985
	s_and_b64 vcc, exec, s[40:41]
	s_cbranch_vccz .LBB0_2988
	s_barrier

.LBB0_3015:
	s_add_u32 s8, s6, 0xfffe0080
	s_addc_u32 s9, s7, -1
	s_add_i32 s72, 0, 0x10000
	s_cmp_eq_u32 s71, 4
	s_cselect_b32 s55, s43, s9
	s_cselect_b32 s54, s49, s8
	v_add_u32_e32 v0, s72, v188
	s_cselect_b32 s9, s39, s70
	s_cselect_b32 s8, s41, s69
	s_add_i32 s74, 0, 0x14000
	ds_read_b128 v[132:135], v0
	ds_read_b128 v[136:139], v0 offset:1024
	ds_read_b128 v[140:143], v0 offset:2048
	ds_read_b128 v[144:147], v0 offset:3072
	v_add_u32_e32 v0, s74, v188
	ds_read_b128 v[148:151], v0
	ds_read_b128 v[152:155], v0 offset:1024
	ds_read_b128 v[176:179], v0 offset:2048
	ds_read_b128 v[180:183], v0 offset:3072
	s_add_i32 m0, s45, 0xc000
	ds_read_b128 v[198:201], v196
	ds_read_b128 v[202:205], v196 offset:1024
	ds_read_b128 v[206:209], v196 offset:2048
	ds_read_b128 v[210:213], v196 offset:3072
	ds_read_b128 v[214:217], v196 offset:4096
	ds_read_b128 v[218:221], v196 offset:5120
	ds_read_b128 v[222:225], v196 offset:6144
	ds_read_b128 v[226:229], v196 offset:7168
	global_load_lds_dwordx4 v172, s[6:7]
	s_add_i32 m0, s45, 0xe000
	s_nop 0
	global_load_lds_dwordx4 v174, s[6:7]
	s_waitcnt vmcnt(8)
	s_waitcnt lgkmcnt(0)
	s_barrier
	v_mfma_f32_16x16x32_bf16 v[128:131], v[132:135], v[198:201], v[128:131]
	v_mfma_f32_16x16x32_bf16 v[124:127], v[140:143], v[198:201], v[124:127]
	v_mfma_f32_16x16x32_bf16 v[120:123], v[132:135], v[206:209], v[120:123]
	v_mfma_f32_16x16x32_bf16 v[116:119], v[140:143], v[206:209], v[116:119]
	v_mfma_f32_16x16x32_bf16 v[112:115], v[132:135], v[214:217], v[112:115]
	v_mfma_f32_16x16x32_bf16 v[108:111], v[140:143], v[214:217], v[108:111]
	v_mfma_f32_16x16x32_bf16 v[104:107], v[132:135], v[222:225], v[104:107]
	v_mfma_f32_16x16x32_bf16 v[100:103], v[140:143], v[222:225], v[100:103]
	v_mfma_f32_16x16x32_bf16 v[128:131], v[136:139], v[202:205], v[128:131]
	v_mfma_f32_16x16x32_bf16 v[124:127], v[144:147], v[202:205], v[124:127]
	v_mfma_f32_16x16x32_bf16 v[120:123], v[136:139], v[210:213], v[120:123]
	v_mfma_f32_16x16x32_bf16 v[116:119], v[144:147], v[210:213], v[116:119]
	v_mfma_f32_16x16x32_bf16 v[112:115], v[136:139], v[218:221], v[112:115]
	v_mfma_f32_16x16x32_bf16 v[108:111], v[144:147], v[218:221], v[108:111]
	v_mfma_f32_16x16x32_bf16 v[104:107], v[136:139], v[226:229], v[104:107]
	v_mfma_f32_16x16x32_bf16 v[100:103], v[144:147], v[226:229], v[100:103]
	v_mfma_f32_16x16x32_bf16 v[96:99], v[148:151], v[198:201], v[96:99]
	v_mfma_f32_16x16x32_bf16 v[92:95], v[176:179], v[198:201], v[92:95]
	v_mfma_f32_16x16x32_bf16 v[88:91], v[148:151], v[206:209], v[88:91]
	v_mfma_f32_16x16x32_bf16 v[84:87], v[176:179], v[206:209], v[84:87]
	v_mfma_f32_16x16x32_bf16 v[80:83], v[148:151], v[214:217], v[80:83]
	v_mfma_f32_16x16x32_bf16 v[76:79], v[176:179], v[214:217], v[76:79]
	v_mfma_f32_16x16x32_bf16 v[72:75], v[148:151], v[222:225], v[72:75]
	v_mfma_f32_16x16x32_bf16 v[68:71], v[176:179], v[222:225], v[68:71]
	v_mfma_f32_16x16x32_bf16 v[96:99], v[152:155], v[202:205], v[96:99]
	v_mfma_f32_16x16x32_bf16 v[92:95], v[180:183], v[202:205], v[92:95]
	v_mfma_f32_16x16x32_bf16 v[88:91], v[152:155], v[210:213], v[88:91]
	v_mfma_f32_16x16x32_bf16 v[84:87], v[180:183], v[210:213], v[84:87]
	v_mfma_f32_16x16x32_bf16 v[80:83], v[152:155], v[218:221], v[80:83]
	v_mfma_f32_16x16x32_bf16 v[76:79], v[180:183], v[218:221], v[76:79]
	v_mfma_f32_16x16x32_bf16 v[72:75], v[152:155], v[226:229], v[72:75]
	v_mfma_f32_16x16x32_bf16 v[68:71], v[180:183], v[226:229], v[68:71]
	s_barrier
	s_add_i32 s72, s72, s60
	s_mov_b64 s[98:99], s[8:9]
	s_mov_b32 m0, s72
	ds_read_b128 v[198:201], v196 offset:16384
	ds_read_b128 v[202:205], v196 offset:17408
	ds_read_b128 v[206:209], v196 offset:18432
	ds_read_b128 v[210:213], v196 offset:19456
	ds_read_b128 v[214:217], v196 offset:20480
	ds_read_b128 v[218:221], v196 offset:21504
	ds_read_b128 v[222:225], v196 offset:22528
	ds_read_b128 v[226:229], v196 offset:23552
	global_load_lds_dwordx4 v166, s[8:9]
	s_add_i32 m0, s72, 0x2000
	s_add_u32 s72, s8, 0x20000
	s_addc_u32 s73, s9, 0
	s_add_i32 s74, s74, s60
	global_load_lds_dwordx4 v164, s[8:9]
	s_mov_b32 m0, s74
	s_mov_b64 s[100:101], s[54:55]
	global_load_lds_dwordx4 v166, s[72:73]
	s_add_i32 m0, s74, 0x2000
	s_nop 0
	global_load_lds_dwordx4 v164, s[72:73]
	s_mov_b32 m0, s45
	s_nop 0
	global_load_lds_dwordx4 v160, s[54:55]
	s_mov_b32 m0, s61
	s_nop 0
	global_load_lds_dwordx4 v162, s[54:55]
	s_waitcnt vmcnt(8)
	s_waitcnt lgkmcnt(0)
	s_barrier
	v_mfma_f32_16x16x32_bf16 v[64:67], v[132:135], v[198:201], v[64:67]
	v_mfma_f32_16x16x32_bf16 v[60:63], v[140:143], v[198:201], v[60:63]
	v_mfma_f32_16x16x32_bf16 v[56:59], v[132:135], v[206:209], v[56:59]
	v_mfma_f32_16x16x32_bf16 v[52:55], v[140:143], v[206:209], v[52:55]
	v_mfma_f32_16x16x32_bf16 v[48:51], v[132:135], v[214:217], v[48:51]
	v_mfma_f32_16x16x32_bf16 v[44:47], v[140:143], v[214:217], v[44:47]
	v_mfma_f32_16x16x32_bf16 v[40:43], v[132:135], v[222:225], v[40:43]
	v_mfma_f32_16x16x32_bf16 v[36:39], v[140:143], v[222:225], v[36:39]
	v_mfma_f32_16x16x32_bf16 v[64:67], v[136:139], v[202:205], v[64:67]
	v_mfma_f32_16x16x32_bf16 v[60:63], v[144:147], v[202:205], v[60:63]
	v_mfma_f32_16x16x32_bf16 v[56:59], v[136:139], v[210:213], v[56:59]
	v_mfma_f32_16x16x32_bf16 v[52:55], v[144:147], v[210:213], v[52:55]
	v_mfma_f32_16x16x32_bf16 v[48:51], v[136:139], v[218:221], v[48:51]
	v_mfma_f32_16x16x32_bf16 v[44:47], v[144:147], v[218:221], v[44:47]
	v_mfma_f32_16x16x32_bf16 v[40:43], v[136:139], v[226:229], v[40:43]
	v_mfma_f32_16x16x32_bf16 v[36:39], v[144:147], v[226:229], v[36:39]
	v_mfma_f32_16x16x32_bf16 v[32:35], v[148:151], v[198:201], v[32:35]
	v_mfma_f32_16x16x32_bf16 v[28:31], v[176:179], v[198:201], v[28:31]
	v_mfma_f32_16x16x32_bf16 v[24:27], v[148:151], v[206:209], v[24:27]
	v_mfma_f32_16x16x32_bf16 v[20:23], v[176:179], v[206:209], v[20:23]
	v_mfma_f32_16x16x32_bf16 v[16:19], v[148:151], v[214:217], v[16:19]
	v_mfma_f32_16x16x32_bf16 v[12:15], v[176:179], v[214:217], v[12:15]
	v_mfma_f32_16x16x32_bf16 v[8:11], v[148:151], v[222:225], v[8:11]
	v_mfma_f32_16x16x32_bf16 v[2:5], v[176:179], v[222:225], v[4:7]
	v_mfma_f32_16x16x32_bf16 v[32:35], v[152:155], v[202:205], v[32:35]
	v_mfma_f32_16x16x32_bf16 v[28:31], v[180:183], v[202:205], v[28:31]
	v_mfma_f32_16x16x32_bf16 v[24:27], v[152:155], v[210:213], v[24:27]
	v_mfma_f32_16x16x32_bf16 v[20:23], v[180:183], v[210:213], v[20:23]
	v_mfma_f32_16x16x32_bf16 v[16:19], v[152:155], v[218:221], v[16:19]
	v_mfma_f32_16x16x32_bf16 v[12:15], v[180:183], v[218:221], v[12:15]
	v_mfma_f32_16x16x32_bf16 v[8:11], v[152:155], v[226:229], v[8:11]
	v_mfma_f32_16x16x32_bf16 v[2:5], v[180:183], v[226:229], v[2:5]
	s_barrier
	s_add_i32 s72, 0, 0x18000
	v_add_u32_e32 v0, s72, v188
	s_add_i32 s73, 0, 0x1c000
	ds_read_b128 v[132:135], v0
	ds_read_b128 v[136:139], v0 offset:1024
	ds_read_b128 v[140:143], v0 offset:2048
	ds_read_b128 v[144:147], v0 offset:3072
	v_add_u32_e32 v0, s73, v188
	ds_read_b128 v[148:151], v0
	ds_read_b128 v[152:155], v0 offset:1024
	ds_read_b128 v[176:179], v0 offset:2048
	ds_read_b128 v[180:183], v0 offset:3072
	s_add_u32 s54, s54, 0x20000
	s_addc_u32 s55, s55, 0
	s_mov_b32 m0, s62
	ds_read_b128 v[198:201], v196 offset:32768
	ds_read_b128 v[202:205], v196 offset:33792
	ds_read_b128 v[206:209], v196 offset:34816
	ds_read_b128 v[210:213], v196 offset:35840
	ds_read_b128 v[214:217], v196 offset:36864
	ds_read_b128 v[218:221], v196 offset:37888
	ds_read_b128 v[222:225], v196 offset:38912
	ds_read_b128 v[226:229], v196 offset:39936
	global_load_lds_dwordx4 v160, s[54:55]
	s_mov_b32 m0, s63
	s_nop 0
	global_load_lds_dwordx4 v162, s[54:55]
	s_waitcnt vmcnt(8)
	s_waitcnt lgkmcnt(0)
	s_barrier
	v_mfma_f32_16x16x32_bf16 v[128:131], v[132:135], v[198:201], v[128:131]
	v_mfma_f32_16x16x32_bf16 v[124:127], v[140:143], v[198:201], v[124:127]
	v_mfma_f32_16x16x32_bf16 v[120:123], v[132:135], v[206:209], v[120:123]
	v_mfma_f32_16x16x32_bf16 v[116:119], v[140:143], v[206:209], v[116:119]
	v_mfma_f32_16x16x32_bf16 v[112:115], v[132:135], v[214:217], v[112:115]
	v_mfma_f32_16x16x32_bf16 v[108:111], v[140:143], v[214:217], v[108:111]
	v_mfma_f32_16x16x32_bf16 v[104:107], v[132:135], v[222:225], v[104:107]
	v_mfma_f32_16x16x32_bf16 v[100:103], v[140:143], v[222:225], v[100:103]
	v_mfma_f32_16x16x32_bf16 v[128:131], v[136:139], v[202:205], v[128:131]
	v_mfma_f32_16x16x32_bf16 v[124:127], v[144:147], v[202:205], v[124:127]
	v_mfma_f32_16x16x32_bf16 v[120:123], v[136:139], v[210:213], v[120:123]
	v_mfma_f32_16x16x32_bf16 v[116:119], v[144:147], v[210:213], v[116:119]
	v_mfma_f32_16x16x32_bf16 v[112:115], v[136:139], v[218:221], v[112:115]
	v_mfma_f32_16x16x32_bf16 v[108:111], v[144:147], v[218:221], v[108:111]
	v_mfma_f32_16x16x32_bf16 v[104:107], v[136:139], v[226:229], v[104:107]
	v_mfma_f32_16x16x32_bf16 v[100:103], v[144:147], v[226:229], v[100:103]
	v_mfma_f32_16x16x32_bf16 v[96:99], v[148:151], v[198:201], v[96:99]
	v_mfma_f32_16x16x32_bf16 v[92:95], v[176:179], v[198:201], v[92:95]
	v_mfma_f32_16x16x32_bf16 v[88:91], v[148:151], v[206:209], v[88:91]
	v_mfma_f32_16x16x32_bf16 v[84:87], v[176:179], v[206:209], v[84:87]
	v_mfma_f32_16x16x32_bf16 v[80:83], v[148:151], v[214:217], v[80:83]
	v_mfma_f32_16x16x32_bf16 v[76:79], v[176:179], v[214:217], v[76:79]
	v_mfma_f32_16x16x32_bf16 v[72:75], v[148:151], v[222:225], v[72:75]
	v_mfma_f32_16x16x32_bf16 v[68:71], v[176:179], v[222:225], v[68:71]
	v_mfma_f32_16x16x32_bf16 v[96:99], v[152:155], v[202:205], v[96:99]
	v_mfma_f32_16x16x32_bf16 v[92:95], v[180:183], v[202:205], v[92:95]
	v_mfma_f32_16x16x32_bf16 v[88:91], v[152:155], v[210:213], v[88:91]
	v_mfma_f32_16x16x32_bf16 v[84:87], v[180:183], v[210:213], v[84:87]
	v_mfma_f32_16x16x32_bf16 v[80:83], v[152:155], v[218:221], v[80:83]
	v_mfma_f32_16x16x32_bf16 v[76:79], v[180:183], v[218:221], v[76:79]
	v_mfma_f32_16x16x32_bf16 v[72:75], v[152:155], v[226:229], v[72:75]
	v_mfma_f32_16x16x32_bf16 v[68:71], v[180:183], v[226:229], v[68:71]
	s_barrier
	s_add_i32 s54, s72, s60
	s_add_u32 s98, s98, s14
	s_addc_u32 s99, s99, s15
	s_mov_b32 m0, s54
	ds_read_b128 v[198:201], v196 offset:49152
	ds_read_b128 v[202:205], v196 offset:50176
	ds_read_b128 v[206:209], v196 offset:51200
	ds_read_b128 v[210:213], v196 offset:52224
	ds_read_b128 v[214:217], v196 offset:53248
	ds_read_b128 v[218:221], v196 offset:54272
	ds_read_b128 v[222:225], v196 offset:55296
	ds_read_b128 v[226:229], v196 offset:56320
	global_load_lds_dwordx4 v166, s[98:99]
	s_add_i32 m0, s54, 0x2000
	s_add_u32 s8, s8, 0x20080
	s_addc_u32 s9, s9, 0
	s_add_i32 s54, s73, s60
	global_load_lds_dwordx4 v164, s[98:99]
	s_mov_b32 m0, s54
	s_nop 0
	global_load_lds_dwordx4 v166, s[8:9]
	s_add_i32 m0, s54, 0x2000
	s_nop 0
	global_load_lds_dwordx4 v164, s[8:9]
	s_add_u32 s100, s100, s14
	s_addc_u32 s101, s101, s15
	s_mov_b32 m0, s65
	s_nop 0
	global_load_lds_dwordx4 v160, s[100:101]
	s_mov_b32 m0, s66
	s_nop 0
	global_load_lds_dwordx4 v162, s[100:101]
	s_waitcnt vmcnt(8)
	s_waitcnt lgkmcnt(0)
	s_barrier
	v_mfma_f32_16x16x32_bf16 v[64:67], v[132:135], v[198:201], v[64:67]
	v_mfma_f32_16x16x32_bf16 v[60:63], v[140:143], v[198:201], v[60:63]
	v_mfma_f32_16x16x32_bf16 v[56:59], v[132:135], v[206:209], v[56:59]
	v_mfma_f32_16x16x32_bf16 v[52:55], v[140:143], v[206:209], v[52:55]
	v_mfma_f32_16x16x32_bf16 v[48:51], v[132:135], v[214:217], v[48:51]
	v_mfma_f32_16x16x32_bf16 v[44:47], v[140:143], v[214:217], v[44:47]
	v_mfma_f32_16x16x32_bf16 v[40:43], v[132:135], v[222:225], v[40:43]
	v_mfma_f32_16x16x32_bf16 v[36:39], v[140:143], v[222:225], v[36:39]
	v_mfma_f32_16x16x32_bf16 v[64:67], v[136:139], v[202:205], v[64:67]
	v_mfma_f32_16x16x32_bf16 v[60:63], v[144:147], v[202:205], v[60:63]
	v_mfma_f32_16x16x32_bf16 v[56:59], v[136:139], v[210:213], v[56:59]
	v_mfma_f32_16x16x32_bf16 v[52:55], v[144:147], v[210:213], v[52:55]
	v_mfma_f32_16x16x32_bf16 v[48:51], v[136:139], v[218:221], v[48:51]
	v_mfma_f32_16x16x32_bf16 v[44:47], v[144:147], v[218:221], v[44:47]
	v_mfma_f32_16x16x32_bf16 v[40:43], v[136:139], v[226:229], v[40:43]
	v_mfma_f32_16x16x32_bf16 v[36:39], v[144:147], v[226:229], v[36:39]
	v_mfma_f32_16x16x32_bf16 v[32:35], v[148:151], v[198:201], v[32:35]
	v_mfma_f32_16x16x32_bf16 v[28:31], v[176:179], v[198:201], v[28:31]
	v_mfma_f32_16x16x32_bf16 v[24:27], v[148:151], v[206:209], v[24:27]
	v_mfma_f32_16x16x32_bf16 v[20:23], v[176:179], v[206:209], v[20:23]
	v_mfma_f32_16x16x32_bf16 v[16:19], v[148:151], v[214:217], v[16:19]
	v_mfma_f32_16x16x32_bf16 v[12:15], v[176:179], v[214:217], v[12:15]
	v_mfma_f32_16x16x32_bf16 v[6:9], v[148:151], v[222:225], v[8:11]
	v_mfma_f32_16x16x32_bf16 v[2:5], v[176:179], v[222:225], v[2:5]
	v_mfma_f32_16x16x32_bf16 v[32:35], v[152:155], v[202:205], v[32:35]
	v_mfma_f32_16x16x32_bf16 v[28:31], v[180:183], v[202:205], v[28:31]
	v_mfma_f32_16x16x32_bf16 v[24:27], v[152:155], v[210:213], v[24:27]
	v_mfma_f32_16x16x32_bf16 v[20:23], v[180:183], v[210:213], v[20:23]
	v_mfma_f32_16x16x32_bf16 v[16:19], v[152:155], v[218:221], v[16:19]
	v_mfma_f32_16x16x32_bf16 v[12:15], v[180:183], v[218:221], v[12:15]
	v_mfma_f32_16x16x32_bf16 v[8:11], v[152:155], v[226:229], v[6:9]
	v_mfma_f32_16x16x32_bf16 v[4:7], v[180:183], v[226:229], v[2:5]
	s_barrier
	s_add_i32 s71, s71, 2
	s_add_u32 s6, s6, 0x100
	s_addc_u32 s7, s7, 0
	s_add_u32 s69, s69, 0x100
	s_addc_u32 s70, s70, 0
	s_cmp_gt_u32 s71, 5
	s_cbranch_scc0 .LBB0_3015
	s_and_b64 vcc, exec, s[36:37]
	s_cbranch_vccz .LBB0_3018
	s_barrier

.LBB0_3227:
	s_add_u32 s58, s48, 0xfffc0080
	s_addc_u32 s59, s49, -1
	s_add_i32 s64, 0, 0x10000
	s_cmp_eq_u32 s63, 12
	s_cselect_b32 s61, s14, s59
	s_cselect_b32 s60, s45, s58
	v_add_u32_e32 v0, s64, v169
	s_cselect_b32 s59, s43, s62
	s_cselect_b32 s58, s55, s57
	s_add_i32 s66, 0, 0x14000
	ds_read_b128 v[148:151], v0
	ds_read_b128 v[152:155], v0 offset:1024
	ds_read_b128 v[156:159], v0 offset:2048
	ds_read_b128 v[190:193], v0 offset:3072
	v_add_u32_e32 v0, s66, v169
	ds_read_b128 v[194:197], v0
	ds_read_b128 v[198:201], v0 offset:1024
	ds_read_b128 v[202:205], v0 offset:2048
	ds_read_b128 v[206:209], v0 offset:3072
	s_add_i32 m0, s80, 0xc000
	ds_read_b128 v[210:213], v188
	ds_read_b128 v[214:217], v188 offset:1024
	ds_read_b128 v[218:221], v188 offset:2048
	ds_read_b128 v[222:225], v188 offset:3072
	ds_read_b128 v[226:229], v188 offset:4096
	ds_read_b128 v[234:237], v188 offset:5120
	ds_read_b128 v[238:241], v188 offset:6144
	ds_read_b128 v[242:245], v188 offset:7168
	global_load_lds_dwordx4 v144, s[48:49]
	s_add_i32 m0, s80, 0xe000
	s_nop 0
	global_load_lds_dwordx4 v146, s[48:49]
	s_waitcnt vmcnt(8)
	s_waitcnt lgkmcnt(0)
	s_barrier
	v_mfma_f32_16x16x32_bf16 v[126:129], v[148:151], v[210:213], v[126:129]
	v_mfma_f32_16x16x32_bf16 v[122:125], v[156:159], v[210:213], v[122:125]
	v_mfma_f32_16x16x32_bf16 v[110:113], v[148:151], v[218:221], v[110:113]
	v_mfma_f32_16x16x32_bf16 v[106:109], v[156:159], v[218:221], v[106:109]
	v_mfma_f32_16x16x32_bf16 v[94:97], v[148:151], v[226:229], v[94:97]
	v_mfma_f32_16x16x32_bf16 v[90:93], v[156:159], v[226:229], v[90:93]
	v_mfma_f32_16x16x32_bf16 v[78:81], v[148:151], v[238:241], v[78:81]
	v_mfma_f32_16x16x32_bf16 v[74:77], v[156:159], v[238:241], v[74:77]
	v_mfma_f32_16x16x32_bf16 v[126:129], v[152:155], v[214:217], v[126:129]
	v_mfma_f32_16x16x32_bf16 v[122:125], v[190:193], v[214:217], v[122:125]
	v_mfma_f32_16x16x32_bf16 v[110:113], v[152:155], v[222:225], v[110:113]
	v_mfma_f32_16x16x32_bf16 v[106:109], v[190:193], v[222:225], v[106:109]
	v_mfma_f32_16x16x32_bf16 v[94:97], v[152:155], v[234:237], v[94:97]
	v_mfma_f32_16x16x32_bf16 v[90:93], v[190:193], v[234:237], v[90:93]
	v_mfma_f32_16x16x32_bf16 v[78:81], v[152:155], v[242:245], v[78:81]
	v_mfma_f32_16x16x32_bf16 v[74:77], v[190:193], v[242:245], v[74:77]
	v_mfma_f32_16x16x32_bf16 v[118:121], v[194:197], v[210:213], v[118:121]
	v_mfma_f32_16x16x32_bf16 v[114:117], v[202:205], v[210:213], v[114:117]
	v_mfma_f32_16x16x32_bf16 v[102:105], v[194:197], v[218:221], v[102:105]
	v_mfma_f32_16x16x32_bf16 v[98:101], v[202:205], v[218:221], v[98:101]
	v_mfma_f32_16x16x32_bf16 v[86:89], v[194:197], v[226:229], v[86:89]
	v_mfma_f32_16x16x32_bf16 v[82:85], v[202:205], v[226:229], v[82:85]
	v_mfma_f32_16x16x32_bf16 v[70:73], v[194:197], v[238:241], v[70:73]
	v_mfma_f32_16x16x32_bf16 v[66:69], v[202:205], v[238:241], v[66:69]
	v_mfma_f32_16x16x32_bf16 v[118:121], v[198:201], v[214:217], v[118:121]
	v_mfma_f32_16x16x32_bf16 v[114:117], v[206:209], v[214:217], v[114:117]
	v_mfma_f32_16x16x32_bf16 v[102:105], v[198:201], v[222:225], v[102:105]
	v_mfma_f32_16x16x32_bf16 v[98:101], v[206:209], v[222:225], v[98:101]
	v_mfma_f32_16x16x32_bf16 v[86:89], v[198:201], v[234:237], v[86:89]
	v_mfma_f32_16x16x32_bf16 v[82:85], v[206:209], v[234:237], v[82:85]
	v_mfma_f32_16x16x32_bf16 v[70:73], v[198:201], v[242:245], v[70:73]
	v_mfma_f32_16x16x32_bf16 v[66:69], v[206:209], v[242:245], v[66:69]
	s_barrier
	s_add_i32 s64, s64, s79
	s_mov_b64 s[98:99], s[58:59]
	s_mov_b32 m0, s64
	ds_read_b128 v[210:213], v188 offset:16384
	ds_read_b128 v[214:217], v188 offset:17408
	ds_read_b128 v[218:221], v188 offset:18432
	ds_read_b128 v[222:225], v188 offset:19456
	ds_read_b128 v[226:229], v188 offset:20480
	ds_read_b128 v[234:237], v188 offset:21504
	ds_read_b128 v[238:241], v188 offset:22528
	ds_read_b128 v[242:245], v188 offset:23552
	global_load_lds_dwordx4 v136, s[58:59]
	s_add_i32 m0, s64, 0x2000
	s_add_u32 s64, s58, 0x40000
	s_addc_u32 s65, s59, 0
	s_add_i32 s66, s66, s79
	global_load_lds_dwordx4 v140, s[58:59]
	s_mov_b32 m0, s66
	s_mov_b64 s[100:101], s[60:61]
	global_load_lds_dwordx4 v136, s[64:65]
	s_add_i32 m0, s66, 0x2000
	s_nop 0
	global_load_lds_dwordx4 v140, s[64:65]
	s_mov_b32 m0, s80
	s_nop 0
	global_load_lds_dwordx4 v134, s[60:61]
	s_mov_b32 m0, s81
	s_nop 0
	global_load_lds_dwordx4 v138, s[60:61]
	s_waitcnt vmcnt(8)
	s_waitcnt lgkmcnt(0)
	s_barrier
	v_mfma_f32_16x16x32_bf16 v[62:65], v[148:151], v[210:213], v[62:65]
	v_mfma_f32_16x16x32_bf16 v[58:61], v[156:159], v[210:213], v[58:61]
	v_mfma_f32_16x16x32_bf16 v[46:49], v[148:151], v[218:221], v[46:49]
	v_mfma_f32_16x16x32_bf16 v[42:45], v[156:159], v[218:221], v[42:45]
	v_mfma_f32_16x16x32_bf16 v[30:33], v[148:151], v[226:229], v[30:33]
	v_mfma_f32_16x16x32_bf16 v[26:29], v[156:159], v[226:229], v[26:29]
	v_mfma_f32_16x16x32_bf16 v[14:17], v[148:151], v[238:241], v[14:17]
	v_mfma_f32_16x16x32_bf16 v[10:13], v[156:159], v[238:241], v[10:13]
	v_mfma_f32_16x16x32_bf16 v[62:65], v[152:155], v[214:217], v[62:65]
	v_mfma_f32_16x16x32_bf16 v[58:61], v[190:193], v[214:217], v[58:61]
	v_mfma_f32_16x16x32_bf16 v[46:49], v[152:155], v[222:225], v[46:49]
	v_mfma_f32_16x16x32_bf16 v[42:45], v[190:193], v[222:225], v[42:45]
	v_mfma_f32_16x16x32_bf16 v[30:33], v[152:155], v[234:237], v[30:33]
	v_mfma_f32_16x16x32_bf16 v[26:29], v[190:193], v[234:237], v[26:29]
	v_mfma_f32_16x16x32_bf16 v[14:17], v[152:155], v[242:245], v[14:17]
	v_mfma_f32_16x16x32_bf16 v[10:13], v[190:193], v[242:245], v[10:13]
	v_mfma_f32_16x16x32_bf16 v[54:57], v[194:197], v[210:213], v[54:57]
	v_mfma_f32_16x16x32_bf16 v[50:53], v[202:205], v[210:213], v[50:53]
	v_mfma_f32_16x16x32_bf16 v[38:41], v[194:197], v[218:221], v[38:41]
	v_mfma_f32_16x16x32_bf16 v[34:37], v[202:205], v[218:221], v[34:37]
	v_mfma_f32_16x16x32_bf16 v[22:25], v[194:197], v[226:229], v[22:25]
	v_mfma_f32_16x16x32_bf16 v[18:21], v[202:205], v[226:229], v[18:21]
	v_mfma_f32_16x16x32_bf16 v[6:9], v[194:197], v[238:241], v[6:9]
	v_mfma_f32_16x16x32_bf16 v[2:5], v[202:205], v[238:241], v[2:5]
	v_mfma_f32_16x16x32_bf16 v[54:57], v[198:201], v[214:217], v[54:57]
	v_mfma_f32_16x16x32_bf16 v[50:53], v[206:209], v[214:217], v[50:53]
	v_mfma_f32_16x16x32_bf16 v[38:41], v[198:201], v[222:225], v[38:41]
	v_mfma_f32_16x16x32_bf16 v[34:37], v[206:209], v[222:225], v[34:37]
	v_mfma_f32_16x16x32_bf16 v[22:25], v[198:201], v[234:237], v[22:25]
	v_mfma_f32_16x16x32_bf16 v[18:21], v[206:209], v[234:237], v[18:21]
	v_mfma_f32_16x16x32_bf16 v[6:9], v[198:201], v[242:245], v[6:9]
	v_mfma_f32_16x16x32_bf16 v[2:5], v[206:209], v[242:245], v[2:5]
	s_barrier
	s_add_i32 s64, 0, 0x18000
	v_add_u32_e32 v0, s64, v169
	s_add_i32 s65, 0, 0x1c000
	ds_read_b128 v[148:151], v0
	ds_read_b128 v[152:155], v0 offset:1024
	ds_read_b128 v[156:159], v0 offset:2048
	ds_read_b128 v[190:193], v0 offset:3072
	v_add_u32_e32 v0, s65, v169
	ds_read_b128 v[194:197], v0
	ds_read_b128 v[198:201], v0 offset:1024
	ds_read_b128 v[202:205], v0 offset:2048
	ds_read_b128 v[206:209], v0 offset:3072
	s_add_u32 s60, s60, 0x40000
	s_addc_u32 s61, s61, 0
	s_mov_b32 m0, s82
	ds_read_b128 v[210:213], v188 offset:32768
	ds_read_b128 v[214:217], v188 offset:33792
	ds_read_b128 v[218:221], v188 offset:34816
	ds_read_b128 v[222:225], v188 offset:35840
	ds_read_b128 v[226:229], v188 offset:36864
	ds_read_b128 v[234:237], v188 offset:37888
	ds_read_b128 v[238:241], v188 offset:38912
	ds_read_b128 v[242:245], v188 offset:39936
	global_load_lds_dwordx4 v134, s[60:61]
	s_mov_b32 m0, s83
	s_nop 0
	global_load_lds_dwordx4 v138, s[60:61]
	s_waitcnt vmcnt(8)
	s_waitcnt lgkmcnt(0)
	s_barrier
	v_mfma_f32_16x16x32_bf16 v[126:129], v[148:151], v[210:213], v[126:129]
	v_mfma_f32_16x16x32_bf16 v[122:125], v[156:159], v[210:213], v[122:125]
	v_mfma_f32_16x16x32_bf16 v[110:113], v[148:151], v[218:221], v[110:113]
	v_mfma_f32_16x16x32_bf16 v[106:109], v[156:159], v[218:221], v[106:109]
	v_mfma_f32_16x16x32_bf16 v[94:97], v[148:151], v[226:229], v[94:97]
	v_mfma_f32_16x16x32_bf16 v[90:93], v[156:159], v[226:229], v[90:93]
	v_mfma_f32_16x16x32_bf16 v[78:81], v[148:151], v[238:241], v[78:81]
	v_mfma_f32_16x16x32_bf16 v[74:77], v[156:159], v[238:241], v[74:77]
	v_mfma_f32_16x16x32_bf16 v[126:129], v[152:155], v[214:217], v[126:129]
	v_mfma_f32_16x16x32_bf16 v[122:125], v[190:193], v[214:217], v[122:125]
	v_mfma_f32_16x16x32_bf16 v[110:113], v[152:155], v[222:225], v[110:113]
	v_mfma_f32_16x16x32_bf16 v[106:109], v[190:193], v[222:225], v[106:109]
	v_mfma_f32_16x16x32_bf16 v[94:97], v[152:155], v[234:237], v[94:97]
	v_mfma_f32_16x16x32_bf16 v[90:93], v[190:193], v[234:237], v[90:93]
	v_mfma_f32_16x16x32_bf16 v[78:81], v[152:155], v[242:245], v[78:81]
	v_mfma_f32_16x16x32_bf16 v[74:77], v[190:193], v[242:245], v[74:77]
	v_mfma_f32_16x16x32_bf16 v[118:121], v[194:197], v[210:213], v[118:121]
	v_mfma_f32_16x16x32_bf16 v[114:117], v[202:205], v[210:213], v[114:117]
	v_mfma_f32_16x16x32_bf16 v[102:105], v[194:197], v[218:221], v[102:105]
	v_mfma_f32_16x16x32_bf16 v[98:101], v[202:205], v[218:221], v[98:101]
	v_mfma_f32_16x16x32_bf16 v[86:89], v[194:197], v[226:229], v[86:89]
	v_mfma_f32_16x16x32_bf16 v[82:85], v[202:205], v[226:229], v[82:85]
	v_mfma_f32_16x16x32_bf16 v[70:73], v[194:197], v[238:241], v[70:73]
	v_mfma_f32_16x16x32_bf16 v[66:69], v[202:205], v[238:241], v[66:69]
	v_mfma_f32_16x16x32_bf16 v[118:121], v[198:201], v[214:217], v[118:121]
	v_mfma_f32_16x16x32_bf16 v[114:117], v[206:209], v[214:217], v[114:117]
	v_mfma_f32_16x16x32_bf16 v[102:105], v[198:201], v[222:225], v[102:105]
	v_mfma_f32_16x16x32_bf16 v[98:101], v[206:209], v[222:225], v[98:101]
	v_mfma_f32_16x16x32_bf16 v[86:89], v[198:201], v[234:237], v[86:89]
	v_mfma_f32_16x16x32_bf16 v[82:85], v[206:209], v[234:237], v[82:85]
	v_mfma_f32_16x16x32_bf16 v[70:73], v[198:201], v[242:245], v[70:73]
	v_mfma_f32_16x16x32_bf16 v[66:69], v[206:209], v[242:245], v[66:69]
	s_barrier
	s_add_i32 s60, s64, s79
	s_add_u32 s98, s98, s16
	s_addc_u32 s99, s99, s17
	s_mov_b32 m0, s60
	ds_read_b128 v[210:213], v188 offset:49152
	ds_read_b128 v[214:217], v188 offset:50176
	ds_read_b128 v[218:221], v188 offset:51200
	ds_read_b128 v[222:225], v188 offset:52224
	ds_read_b128 v[226:229], v188 offset:53248
	ds_read_b128 v[234:237], v188 offset:54272
	ds_read_b128 v[238:241], v188 offset:55296
	ds_read_b128 v[242:245], v188 offset:56320
	global_load_lds_dwordx4 v136, s[98:99]
	s_add_i32 m0, s60, 0x2000
	s_add_u32 s58, s58, 0x40080
	s_addc_u32 s59, s59, 0
	s_add_i32 s60, s65, s79
	global_load_lds_dwordx4 v140, s[98:99]
	s_mov_b32 m0, s60
	s_nop 0
	global_load_lds_dwordx4 v136, s[58:59]
	s_add_i32 m0, s60, 0x2000
	s_nop 0
	global_load_lds_dwordx4 v140, s[58:59]
	s_add_u32 s100, s100, s16
	s_addc_u32 s101, s101, s17
	s_mov_b32 m0, s86
	s_nop 0
	global_load_lds_dwordx4 v134, s[100:101]
	s_mov_b32 m0, s87
	s_nop 0
	global_load_lds_dwordx4 v138, s[100:101]
	s_waitcnt vmcnt(8)
	s_waitcnt lgkmcnt(0)
	s_barrier
	v_mfma_f32_16x16x32_bf16 v[62:65], v[148:151], v[210:213], v[62:65]
	v_mfma_f32_16x16x32_bf16 v[58:61], v[156:159], v[210:213], v[58:61]
	v_mfma_f32_16x16x32_bf16 v[46:49], v[148:151], v[218:221], v[46:49]
	v_mfma_f32_16x16x32_bf16 v[42:45], v[156:159], v[218:221], v[42:45]
	v_mfma_f32_16x16x32_bf16 v[30:33], v[148:151], v[226:229], v[30:33]
	v_mfma_f32_16x16x32_bf16 v[26:29], v[156:159], v[226:229], v[26:29]
	v_mfma_f32_16x16x32_bf16 v[14:17], v[148:151], v[238:241], v[14:17]
	v_mfma_f32_16x16x32_bf16 v[10:13], v[156:159], v[238:241], v[10:13]
	v_mfma_f32_16x16x32_bf16 v[62:65], v[152:155], v[214:217], v[62:65]
	v_mfma_f32_16x16x32_bf16 v[58:61], v[190:193], v[214:217], v[58:61]
	v_mfma_f32_16x16x32_bf16 v[46:49], v[152:155], v[222:225], v[46:49]
	v_mfma_f32_16x16x32_bf16 v[42:45], v[190:193], v[222:225], v[42:45]
	v_mfma_f32_16x16x32_bf16 v[30:33], v[152:155], v[234:237], v[30:33]
	v_mfma_f32_16x16x32_bf16 v[26:29], v[190:193], v[234:237], v[26:29]
	v_mfma_f32_16x16x32_bf16 v[14:17], v[152:155], v[242:245], v[14:17]
	v_mfma_f32_16x16x32_bf16 v[10:13], v[190:193], v[242:245], v[10:13]
	v_mfma_f32_16x16x32_bf16 v[54:57], v[194:197], v[210:213], v[54:57]
	v_mfma_f32_16x16x32_bf16 v[50:53], v[202:205], v[210:213], v[50:53]
	v_mfma_f32_16x16x32_bf16 v[38:41], v[194:197], v[218:221], v[38:41]
	v_mfma_f32_16x16x32_bf16 v[34:37], v[202:205], v[218:221], v[34:37]
	v_mfma_f32_16x16x32_bf16 v[22:25], v[194:197], v[226:229], v[22:25]
	v_mfma_f32_16x16x32_bf16 v[18:21], v[202:205], v[226:229], v[18:21]
	v_mfma_f32_16x16x32_bf16 v[6:9], v[194:197], v[238:241], v[6:9]
	v_mfma_f32_16x16x32_bf16 v[2:5], v[202:205], v[238:241], v[2:5]
	v_mfma_f32_16x16x32_bf16 v[54:57], v[198:201], v[214:217], v[54:57]
	v_mfma_f32_16x16x32_bf16 v[50:53], v[206:209], v[214:217], v[50:53]
	v_mfma_f32_16x16x32_bf16 v[38:41], v[198:201], v[222:225], v[38:41]
	v_mfma_f32_16x16x32_bf16 v[34:37], v[206:209], v[222:225], v[34:37]
	v_mfma_f32_16x16x32_bf16 v[22:25], v[198:201], v[234:237], v[22:25]
	v_mfma_f32_16x16x32_bf16 v[18:21], v[206:209], v[234:237], v[18:21]
	v_mfma_f32_16x16x32_bf16 v[6:9], v[198:201], v[242:245], v[6:9]
	v_mfma_f32_16x16x32_bf16 v[2:5], v[206:209], v[242:245], v[2:5]
	s_barrier
	s_add_i32 s63, s63, 2
	s_add_u32 s48, s48, 0x100
	s_addc_u32 s49, s49, 0
	s_add_u32 s57, s57, 0x100
	s_addc_u32 s62, s62, 0
	s_cmp_gt_u32 s63, 13
	s_cbranch_scc0 .LBB0_3227
	s_and_b64 vcc, exec, s[36:37]
	s_cbranch_vccz .LBB0_3231
	s_barrier
	s_andn2_b64 vcc, exec, s[20:21]
	s_cbranch_vccz .LBB0_3232

.LBB0_3694:
	s_add_u32 s22, s20, 0xfff50080
	s_addc_u32 s23, s21, -1
	s_add_i32 s57, 0, 0x10000
	s_cmp_eq_u32 s56, 40
	s_cselect_b32 s25, s5, s23
	s_cselect_b32 s24, s4, s22
	v_add_u32_e32 v153, s57, v151
	s_cselect_b32 s23, s19, s55
	s_cselect_b32 s22, s18, s54
	s_add_i32 s60, 0, 0x14000
	ds_read_b128 v[146:149], v153
	ds_read_b128 v[154:157], v153 offset:1024
	ds_read_b128 v[158:161], v153 offset:2048
	ds_read_b128 v[162:165], v153 offset:3072
	v_add_u32_e32 v153, s60, v151
	ds_read_b128 v[166:169], v153
	ds_read_b128 v[170:173], v153 offset:1024
	ds_read_b128 v[174:177], v153 offset:2048
	ds_read_b128 v[178:181], v153 offset:3072
	s_add_i32 m0, s41, 0xc000
	ds_read_b128 v[182:185], v152
	ds_read_b128 v[186:189], v152 offset:1024
	ds_read_b128 v[190:193], v152 offset:2048
	ds_read_b128 v[194:197], v152 offset:3072
	ds_read_b128 v[198:201], v152 offset:4096
	ds_read_b128 v[202:205], v152 offset:5120
	ds_read_b128 v[206:209], v152 offset:6144
	ds_read_b128 v[210:213], v152 offset:7168
	global_load_lds_dwordx4 v142, s[20:21]
	s_add_i32 m0, s41, 0xe000
	s_nop 0
	global_load_lds_dwordx4 v144, s[20:21]
	s_waitcnt vmcnt(8)
	s_waitcnt lgkmcnt(0)
	s_barrier
	v_mfma_f32_16x16x32_bf16 v[124:127], v[146:149], v[182:185], v[124:127]
	v_mfma_f32_16x16x32_bf16 v[120:123], v[158:161], v[182:185], v[120:123]
	v_mfma_f32_16x16x32_bf16 v[108:111], v[146:149], v[190:193], v[108:111]
	v_mfma_f32_16x16x32_bf16 v[104:107], v[158:161], v[190:193], v[104:107]
	v_mfma_f32_16x16x32_bf16 v[92:95], v[146:149], v[198:201], v[92:95]
	v_mfma_f32_16x16x32_bf16 v[88:91], v[158:161], v[198:201], v[88:91]
	v_mfma_f32_16x16x32_bf16 v[76:79], v[146:149], v[206:209], v[76:79]
	v_mfma_f32_16x16x32_bf16 v[72:75], v[158:161], v[206:209], v[72:75]
	v_mfma_f32_16x16x32_bf16 v[124:127], v[154:157], v[186:189], v[124:127]
	v_mfma_f32_16x16x32_bf16 v[120:123], v[162:165], v[186:189], v[120:123]
	v_mfma_f32_16x16x32_bf16 v[108:111], v[154:157], v[194:197], v[108:111]
	v_mfma_f32_16x16x32_bf16 v[104:107], v[162:165], v[194:197], v[104:107]
	v_mfma_f32_16x16x32_bf16 v[92:95], v[154:157], v[202:205], v[92:95]
	v_mfma_f32_16x16x32_bf16 v[88:91], v[162:165], v[202:205], v[88:91]
	v_mfma_f32_16x16x32_bf16 v[76:79], v[154:157], v[210:213], v[76:79]
	v_mfma_f32_16x16x32_bf16 v[72:75], v[162:165], v[210:213], v[72:75]
	v_mfma_f32_16x16x32_bf16 v[116:119], v[166:169], v[182:185], v[116:119]
	v_mfma_f32_16x16x32_bf16 v[112:115], v[174:177], v[182:185], v[112:115]
	v_mfma_f32_16x16x32_bf16 v[100:103], v[166:169], v[190:193], v[100:103]
	v_mfma_f32_16x16x32_bf16 v[96:99], v[174:177], v[190:193], v[96:99]
	v_mfma_f32_16x16x32_bf16 v[84:87], v[166:169], v[198:201], v[84:87]
	v_mfma_f32_16x16x32_bf16 v[80:83], v[174:177], v[198:201], v[80:83]
	v_mfma_f32_16x16x32_bf16 v[68:71], v[166:169], v[206:209], v[68:71]
	v_mfma_f32_16x16x32_bf16 v[64:67], v[174:177], v[206:209], v[64:67]
	v_mfma_f32_16x16x32_bf16 v[116:119], v[170:173], v[186:189], v[116:119]
	v_mfma_f32_16x16x32_bf16 v[112:115], v[178:181], v[186:189], v[112:115]
	v_mfma_f32_16x16x32_bf16 v[100:103], v[170:173], v[194:197], v[100:103]
	v_mfma_f32_16x16x32_bf16 v[96:99], v[178:181], v[194:197], v[96:99]
	v_mfma_f32_16x16x32_bf16 v[84:87], v[170:173], v[202:205], v[84:87]
	v_mfma_f32_16x16x32_bf16 v[80:83], v[178:181], v[202:205], v[80:83]
	v_mfma_f32_16x16x32_bf16 v[68:71], v[170:173], v[210:213], v[68:71]
	v_mfma_f32_16x16x32_bf16 v[64:67], v[178:181], v[210:213], v[64:67]
	s_barrier
	s_add_i32 s57, s57, s40
	s_mov_b64 s[98:99], s[22:23]
	s_mov_b32 m0, s57
	ds_read_b128 v[182:185], v152 offset:16384
	ds_read_b128 v[186:189], v152 offset:17408
	ds_read_b128 v[190:193], v152 offset:18432
	ds_read_b128 v[194:197], v152 offset:19456
	ds_read_b128 v[198:201], v152 offset:20480
	ds_read_b128 v[202:205], v152 offset:21504
	ds_read_b128 v[206:209], v152 offset:22528
	ds_read_b128 v[210:213], v152 offset:23552
	global_load_lds_dwordx4 v128, s[22:23]
	s_add_i32 m0, s57, 0x2000
	s_add_u32 s58, s22, 0xb0000
	s_addc_u32 s59, s23, 0
	s_add_i32 s57, s60, s40
	global_load_lds_dwordx4 v138, s[22:23]
	s_mov_b32 m0, s57
	s_mov_b64 s[100:101], s[24:25]
	global_load_lds_dwordx4 v128, s[58:59]
	s_add_i32 m0, s57, 0x2000
	s_nop 0
	global_load_lds_dwordx4 v138, s[58:59]
	s_mov_b32 m0, s41
	s_nop 0
	global_load_lds_dwordx4 v134, s[24:25]
	s_mov_b32 m0, s42
	s_nop 0
	global_load_lds_dwordx4 v136, s[24:25]
	s_waitcnt vmcnt(8)
	s_waitcnt lgkmcnt(0)
	s_barrier
	v_mfma_f32_16x16x32_bf16 v[60:63], v[146:149], v[182:185], v[60:63]
	v_mfma_f32_16x16x32_bf16 v[56:59], v[158:161], v[182:185], v[56:59]
	v_mfma_f32_16x16x32_bf16 v[44:47], v[146:149], v[190:193], v[44:47]
	v_mfma_f32_16x16x32_bf16 v[40:43], v[158:161], v[190:193], v[40:43]
	v_mfma_f32_16x16x32_bf16 v[28:31], v[146:149], v[198:201], v[28:31]
	v_mfma_f32_16x16x32_bf16 v[24:27], v[158:161], v[198:201], v[24:27]
	v_mfma_f32_16x16x32_bf16 v[12:15], v[146:149], v[206:209], v[12:15]
	v_mfma_f32_16x16x32_bf16 v[8:11], v[158:161], v[206:209], v[8:11]
	v_mfma_f32_16x16x32_bf16 v[60:63], v[154:157], v[186:189], v[60:63]
	v_mfma_f32_16x16x32_bf16 v[56:59], v[162:165], v[186:189], v[56:59]
	v_mfma_f32_16x16x32_bf16 v[44:47], v[154:157], v[194:197], v[44:47]
	v_mfma_f32_16x16x32_bf16 v[40:43], v[162:165], v[194:197], v[40:43]
	v_mfma_f32_16x16x32_bf16 v[28:31], v[154:157], v[202:205], v[28:31]
	v_mfma_f32_16x16x32_bf16 v[24:27], v[162:165], v[202:205], v[24:27]
	v_mfma_f32_16x16x32_bf16 v[12:15], v[154:157], v[210:213], v[12:15]
	v_mfma_f32_16x16x32_bf16 v[8:11], v[162:165], v[210:213], v[8:11]
	v_mfma_f32_16x16x32_bf16 v[52:55], v[166:169], v[182:185], v[52:55]
	v_mfma_f32_16x16x32_bf16 v[48:51], v[174:177], v[182:185], v[48:51]
	v_mfma_f32_16x16x32_bf16 v[36:39], v[166:169], v[190:193], v[36:39]
	v_mfma_f32_16x16x32_bf16 v[32:35], v[174:177], v[190:193], v[32:35]
	v_mfma_f32_16x16x32_bf16 v[20:23], v[166:169], v[198:201], v[20:23]
	v_mfma_f32_16x16x32_bf16 v[16:19], v[174:177], v[198:201], v[16:19]
	v_mfma_f32_16x16x32_bf16 v[4:7], v[166:169], v[206:209], v[4:7]
	v_mfma_f32_16x16x32_bf16 v[0:3], v[174:177], v[206:209], v[0:3]
	v_mfma_f32_16x16x32_bf16 v[52:55], v[170:173], v[186:189], v[52:55]
	v_mfma_f32_16x16x32_bf16 v[48:51], v[178:181], v[186:189], v[48:51]
	v_mfma_f32_16x16x32_bf16 v[36:39], v[170:173], v[194:197], v[36:39]
	v_mfma_f32_16x16x32_bf16 v[32:35], v[178:181], v[194:197], v[32:35]
	v_mfma_f32_16x16x32_bf16 v[20:23], v[170:173], v[202:205], v[20:23]
	v_mfma_f32_16x16x32_bf16 v[16:19], v[178:181], v[202:205], v[16:19]
	v_mfma_f32_16x16x32_bf16 v[4:7], v[170:173], v[210:213], v[4:7]
	v_mfma_f32_16x16x32_bf16 v[0:3], v[178:181], v[210:213], v[0:3]
	s_barrier
	s_add_i32 s57, 0, 0x18000
	v_add_u32_e32 v153, s57, v151
	s_add_i32 s58, 0, 0x1c000
	ds_read_b128 v[146:149], v153
	ds_read_b128 v[154:157], v153 offset:1024
	ds_read_b128 v[158:161], v153 offset:2048
	ds_read_b128 v[162:165], v153 offset:3072
	v_add_u32_e32 v153, s58, v151
	ds_read_b128 v[166:169], v153
	ds_read_b128 v[170:173], v153 offset:1024
	ds_read_b128 v[174:177], v153 offset:2048
	ds_read_b128 v[178:181], v153 offset:3072
	s_add_u32 s24, s24, 0xb0000
	s_addc_u32 s25, s25, 0
	s_mov_b32 m0, s43
	ds_read_b128 v[182:185], v152 offset:32768
	ds_read_b128 v[186:189], v152 offset:33792
	ds_read_b128 v[190:193], v152 offset:34816
	ds_read_b128 v[194:197], v152 offset:35840
	ds_read_b128 v[198:201], v152 offset:36864
	ds_read_b128 v[202:205], v152 offset:37888
	ds_read_b128 v[206:209], v152 offset:38912
	ds_read_b128 v[210:213], v152 offset:39936
	global_load_lds_dwordx4 v134, s[24:25]
	s_mov_b32 m0, s44
	s_nop 0
	global_load_lds_dwordx4 v136, s[24:25]
	s_waitcnt vmcnt(8)
	s_waitcnt lgkmcnt(0)
	s_barrier
	v_mfma_f32_16x16x32_bf16 v[124:127], v[146:149], v[182:185], v[124:127]
	v_mfma_f32_16x16x32_bf16 v[120:123], v[158:161], v[182:185], v[120:123]
	v_mfma_f32_16x16x32_bf16 v[108:111], v[146:149], v[190:193], v[108:111]
	v_mfma_f32_16x16x32_bf16 v[104:107], v[158:161], v[190:193], v[104:107]
	v_mfma_f32_16x16x32_bf16 v[92:95], v[146:149], v[198:201], v[92:95]
	v_mfma_f32_16x16x32_bf16 v[88:91], v[158:161], v[198:201], v[88:91]
	v_mfma_f32_16x16x32_bf16 v[76:79], v[146:149], v[206:209], v[76:79]
	v_mfma_f32_16x16x32_bf16 v[72:75], v[158:161], v[206:209], v[72:75]
	v_mfma_f32_16x16x32_bf16 v[124:127], v[154:157], v[186:189], v[124:127]
	v_mfma_f32_16x16x32_bf16 v[120:123], v[162:165], v[186:189], v[120:123]
	v_mfma_f32_16x16x32_bf16 v[108:111], v[154:157], v[194:197], v[108:111]
	v_mfma_f32_16x16x32_bf16 v[104:107], v[162:165], v[194:197], v[104:107]
	v_mfma_f32_16x16x32_bf16 v[92:95], v[154:157], v[202:205], v[92:95]
	v_mfma_f32_16x16x32_bf16 v[88:91], v[162:165], v[202:205], v[88:91]
	v_mfma_f32_16x16x32_bf16 v[76:79], v[154:157], v[210:213], v[76:79]
	v_mfma_f32_16x16x32_bf16 v[72:75], v[162:165], v[210:213], v[72:75]
	v_mfma_f32_16x16x32_bf16 v[116:119], v[166:169], v[182:185], v[116:119]
	v_mfma_f32_16x16x32_bf16 v[112:115], v[174:177], v[182:185], v[112:115]
	v_mfma_f32_16x16x32_bf16 v[100:103], v[166:169], v[190:193], v[100:103]
	v_mfma_f32_16x16x32_bf16 v[96:99], v[174:177], v[190:193], v[96:99]
	v_mfma_f32_16x16x32_bf16 v[84:87], v[166:169], v[198:201], v[84:87]
	v_mfma_f32_16x16x32_bf16 v[80:83], v[174:177], v[198:201], v[80:83]
	v_mfma_f32_16x16x32_bf16 v[68:71], v[166:169], v[206:209], v[68:71]
	v_mfma_f32_16x16x32_bf16 v[64:67], v[174:177], v[206:209], v[64:67]
	v_mfma_f32_16x16x32_bf16 v[116:119], v[170:173], v[186:189], v[116:119]
	v_mfma_f32_16x16x32_bf16 v[112:115], v[178:181], v[186:189], v[112:115]
	v_mfma_f32_16x16x32_bf16 v[100:103], v[170:173], v[194:197], v[100:103]
	v_mfma_f32_16x16x32_bf16 v[96:99], v[178:181], v[194:197], v[96:99]
	v_mfma_f32_16x16x32_bf16 v[84:87], v[170:173], v[202:205], v[84:87]
	v_mfma_f32_16x16x32_bf16 v[80:83], v[178:181], v[202:205], v[80:83]
	v_mfma_f32_16x16x32_bf16 v[68:71], v[170:173], v[210:213], v[68:71]
	v_mfma_f32_16x16x32_bf16 v[64:67], v[178:181], v[210:213], v[64:67]
	s_barrier
	s_add_i32 s24, s57, s40
	s_add_u32 s98, s98, s6
	s_addc_u32 s99, s99, s7
	s_mov_b32 m0, s24
	ds_read_b128 v[182:185], v152 offset:49152
	ds_read_b128 v[186:189], v152 offset:50176
	ds_read_b128 v[190:193], v152 offset:51200
	ds_read_b128 v[194:197], v152 offset:52224
	ds_read_b128 v[198:201], v152 offset:53248
	ds_read_b128 v[202:205], v152 offset:54272
	ds_read_b128 v[206:209], v152 offset:55296
	ds_read_b128 v[210:213], v152 offset:56320
	global_load_lds_dwordx4 v128, s[98:99]
	s_add_i32 m0, s24, 0x2000
	s_add_u32 s22, s22, 0xb0080
	s_addc_u32 s23, s23, 0
	s_add_i32 s24, s58, s40
	global_load_lds_dwordx4 v138, s[98:99]
	s_mov_b32 m0, s24
	s_nop 0
	global_load_lds_dwordx4 v128, s[22:23]
	s_add_i32 m0, s24, 0x2000
	s_nop 0
	global_load_lds_dwordx4 v138, s[22:23]
	s_add_u32 s100, s100, s6
	s_addc_u32 s101, s101, s7
	s_mov_b32 m0, s45
	s_nop 0
	global_load_lds_dwordx4 v134, s[100:101]
	s_mov_b32 m0, s48
	s_nop 0
	global_load_lds_dwordx4 v136, s[100:101]
	s_waitcnt vmcnt(8)
	s_waitcnt lgkmcnt(0)
	s_barrier
	v_mfma_f32_16x16x32_bf16 v[60:63], v[146:149], v[182:185], v[60:63]
	v_mfma_f32_16x16x32_bf16 v[56:59], v[158:161], v[182:185], v[56:59]
	v_mfma_f32_16x16x32_bf16 v[44:47], v[146:149], v[190:193], v[44:47]
	v_mfma_f32_16x16x32_bf16 v[40:43], v[158:161], v[190:193], v[40:43]
	v_mfma_f32_16x16x32_bf16 v[28:31], v[146:149], v[198:201], v[28:31]
	v_mfma_f32_16x16x32_bf16 v[24:27], v[158:161], v[198:201], v[24:27]
	v_mfma_f32_16x16x32_bf16 v[12:15], v[146:149], v[206:209], v[12:15]
	v_mfma_f32_16x16x32_bf16 v[8:11], v[158:161], v[206:209], v[8:11]
	v_mfma_f32_16x16x32_bf16 v[60:63], v[154:157], v[186:189], v[60:63]
	v_mfma_f32_16x16x32_bf16 v[56:59], v[162:165], v[186:189], v[56:59]
	v_mfma_f32_16x16x32_bf16 v[44:47], v[154:157], v[194:197], v[44:47]
	v_mfma_f32_16x16x32_bf16 v[40:43], v[162:165], v[194:197], v[40:43]
	v_mfma_f32_16x16x32_bf16 v[28:31], v[154:157], v[202:205], v[28:31]
	v_mfma_f32_16x16x32_bf16 v[24:27], v[162:165], v[202:205], v[24:27]
	v_mfma_f32_16x16x32_bf16 v[12:15], v[154:157], v[210:213], v[12:15]
	v_mfma_f32_16x16x32_bf16 v[8:11], v[162:165], v[210:213], v[8:11]
	v_mfma_f32_16x16x32_bf16 v[52:55], v[166:169], v[182:185], v[52:55]
	v_mfma_f32_16x16x32_bf16 v[48:51], v[174:177], v[182:185], v[48:51]
	v_mfma_f32_16x16x32_bf16 v[36:39], v[166:169], v[190:193], v[36:39]
	v_mfma_f32_16x16x32_bf16 v[32:35], v[174:177], v[190:193], v[32:35]
	v_mfma_f32_16x16x32_bf16 v[20:23], v[166:169], v[198:201], v[20:23]
	v_mfma_f32_16x16x32_bf16 v[16:19], v[174:177], v[198:201], v[16:19]
	v_mfma_f32_16x16x32_bf16 v[4:7], v[166:169], v[206:209], v[4:7]
	v_mfma_f32_16x16x32_bf16 v[0:3], v[174:177], v[206:209], v[0:3]
	v_mfma_f32_16x16x32_bf16 v[52:55], v[170:173], v[186:189], v[52:55]
	v_mfma_f32_16x16x32_bf16 v[48:51], v[178:181], v[186:189], v[48:51]
	v_mfma_f32_16x16x32_bf16 v[36:39], v[170:173], v[194:197], v[36:39]
	v_mfma_f32_16x16x32_bf16 v[32:35], v[178:181], v[194:197], v[32:35]
	v_mfma_f32_16x16x32_bf16 v[20:23], v[170:173], v[202:205], v[20:23]
	v_mfma_f32_16x16x32_bf16 v[16:19], v[178:181], v[202:205], v[16:19]
	v_mfma_f32_16x16x32_bf16 v[4:7], v[170:173], v[210:213], v[4:7]
	v_mfma_f32_16x16x32_bf16 v[0:3], v[178:181], v[210:213], v[0:3]
	s_barrier
	s_add_i32 s56, s56, 2
	s_add_u32 s20, s20, 0x100
	s_addc_u32 s21, s21, 0
	s_add_u32 s54, s54, 0x100
	s_addc_u32 s55, s55, 0
	s_cmp_gt_u32 s56, 41
	s_cbranch_scc0 .LBB0_3694
	s_and_b64 vcc, exec, s[16:17]
	s_cbranch_vccz .LBB0_3698
	s_barrier
	s_andn2_b64 vcc, exec, s[12:13]
	s_cbranch_vccz .LBB0_3699
